# hazard-checker-guided removal of 129 wait states left over from the deleted s_setprio flips in conv/attention/pool loops; residual epilogue reordered to keep 1 wait state after packed f32 ops
# speedup vs baseline: 1.0005x; 1.0005x over previous
; #define PG8_STAGE(bufoff, gbase, voff) do { _Pragma("unroll") for (int _i = 0; _i < 2; ++_i) \
;         __builtin_amdgcn_global_load_lds((const unsigned*)((const char*)(gbase) + (voff)[_i]), (LAS unsigned*)(lds + (bufoff) + ldsw + _i * 8192), 16, 0, 0); } while (0)
; #define PG8_LDA(dst, b, h) do { _Pragma("unroll") for (int m = 0; m < 4; ++m) _Pragma("unroll") for (int k = 0; k < 2; ++k) dst[m][k] = *(const LAS bf16x8*)(lds + PG8_SA(b, h) + aoff + m * 2048 + k * 1024); } while (0)
; #define PG8_LDB(dst, b, h) do { _Pragma("unroll") for (int n = 0; n < 2; ++n) _Pragma("unroll") for (int k = 0; k < 2; ++k) dst[n][k] = *(const LAS bf16x8*)(lds + PG8_SB(b, h) + boff + n * 2048 + k * 1024); } while (0)
; #define PG8_MMA(ai, bj, At, Bt) do { __builtin_amdgcn_s_setprio(1); _Pragma("unroll") for (int m = 0; m < 4; ++m) _Pragma("unroll") for (int n = 0; n < 2; ++n) _Pragma("unroll") for (int k = 0; k < 2; ++k) \
;         acc[ai][bj][m][n] = __builtin_amdgcn_mfma_f32_16x16x32_bf16(Bt[n][k], At[m][k], acc[ai][bj][m][n], 0, 0, 0); __builtin_amdgcn_s_setprio(0); } while (0)
; #define PG8_WAIT_V(n) asm volatile("s_waitcnt vmcnt(" #n ")" ::: "memory")
; #define PG8_WAIT_L(n) asm volatile("s_waitcnt lgkmcnt(" #n ")" ::: "memory")
; #define PG8_BAR __builtin_amdgcn_s_barrier()
; #define PG8_SCHED __builtin_amdgcn_sched_barrier(0)
; template <class Epi, bool ALIGN_EPI>
; __device__ __forceinline__ void gemm_phase(LAS unsigned char* lds, const Gemm g, const StaticOrder& S, const Epi& E, const int tid) {
;     ...
;         const bool has_next = S.next(ui + 1, nxt);
;         const char* nA = has_next ? (const char*)g.A + (size_t)nxt.pm * tstepA + (size_t)nxt.pn * g.acs : cA; const char* nB = has_next ? (const char*)g.Bt + (size_t)nxt.pn * tstepB : cB;
;         for (int t = 0; t < nt; t += 2) {
;             const bool last = (t == nt - 2);
;             const char* a1 = cA + (size_t)(t + 1) * kstepA;
;             const char* a2 = last ? nA : cA + (size_t)(t + 2) * kstepA; const char* b2 = last ? nB : cB + (size_t)(t + 2) * kstepB;
;             const char* a3 = a2 + kstepA; const char* b3 = b2 + kstepB;
;             PG8_LDB(B0, 0, 0); PG8_LDB(B1, 0, 1); PG8_SCHED; PG8_LDA(At, 0, 0); PG8_STAGE(PG8_SA(1, 1), a1 + hstepA, voffA);
;             PG8_WAIT_V(8); PG8_WAIT_L(0); PG8_BAR; PG8_MMA(0, 0, At, B0); PG8_MMA(0, 1, At, B1); PG8_BAR; PG8_SCHED;
.LBB0_717:
	s_ashr_i32 s45, s44, 31
	s_lshl_b64 s[46:47], s[44:45], 19
	s_add_u32 s45, s30, s46
	s_addc_u32 s48, s60, s47
	s_ashr_i32 s43, s42, 31
	s_lshl_b64 s[46:47], s[42:43], 9
	s_add_u32 s46, s45, s46
	s_addc_u32 s47, s48, s47
	s_and_b64 s[48:49], s[38:39], exec
	s_cselect_b32 s57, s47, s51
	s_cselect_b32 s56, s46, s50
	s_lshl_b64 s[48:49], s[42:43], 17
	s_add_u32 s48, s61, s48
	s_addc_u32 s49, s71, s49
	s_and_b64 s[54:55], s[38:39], exec
	s_cselect_b32 s55, s49, s53
	s_cselect_b32 s54, s48, s52
	s_add_i32 s45, 0, 0x10000
	s_add_i32 s83, 0, 0x14000
	v_add_u32_e32 v222, s45, v170
	v_add_u32_e32 v223, s83, v170
	ds_read_b128 v[130:133], v222
	ds_read_b128 v[134:137], v222 offset:1024
	ds_read_b128 v[138:141], v222 offset:2048
	ds_read_b128 v[142:145], v222 offset:3072
	ds_read_b128 v[146:149], v223
	ds_read_b128 v[150:153], v223 offset:1024
	ds_read_b128 v[154:157], v223 offset:2048
	ds_read_b128 v[164:167], v223 offset:3072
	s_add_u32 s84, s50, 0x40080
	s_addc_u32 s85, s51, 0
	s_add_i32 s87, s73, 0xc000
	v_lshl_add_u64 v[168:169], s[84:85], 0, v[162:163]
	s_mov_b32 m0, s87
	s_add_i32 s43, s73, 0xe000
	ds_read_b128 v[172:175], v171
	ds_read_b128 v[176:179], v171 offset:1024
	ds_read_b128 v[180:183], v171 offset:2048
	ds_read_b128 v[184:187], v171 offset:3072
	ds_read_b128 v[188:191], v171 offset:4096
	ds_read_b128 v[192:195], v171 offset:5120
	ds_read_b128 v[196:199], v171 offset:6144
	ds_read_b128 v[214:217], v171 offset:7168
	global_load_lds_dwordx4 v[168:169], off
	v_lshl_add_u64 v[168:169], s[84:85], 0, v[160:161]
	s_mov_b32 m0, s43
	s_nop 0
	global_load_lds_dwordx4 v[168:169], off
	s_waitcnt vmcnt(8)
	s_waitcnt lgkmcnt(0)
	s_barrier

; #define PG8_MMA(ai, bj, At, Bt) do { __builtin_amdgcn_s_setprio(1); _Pragma("unroll") for (int m = 0; m < 4; ++m) _Pragma("unroll") for (int n = 0; n < 2; ++n) _Pragma("unroll") for (int k = 0; k < 2; ++k) \
;         acc[ai][bj][m][n] = __builtin_amdgcn_mfma_f32_16x16x32_bf16(Bt[n][k], At[m][k], acc[ai][bj][m][n], 0, 0, 0); __builtin_amdgcn_s_setprio(0); } while (0)
; #define PG8_WAIT_V(n) asm volatile("s_waitcnt vmcnt(" #n ")" ::: "memory")
; #define PG8_WAIT_L(n) asm volatile("s_waitcnt lgkmcnt(" #n ")" ::: "memory")
; #define PG8_BAR __builtin_amdgcn_s_barrier()
; #define PG8_SCHED __builtin_amdgcn_sched_barrier(0)
; template <class Epi, bool ALIGN_EPI>
; __device__ __forceinline__ void gemm_phase(LAS unsigned char* lds, const Gemm g, const StaticOrder& S, const Epi& E, const int tid) {
;     ...
;             PG8_WAIT_V(8); PG8_WAIT_L(0); PG8_BAR; PG8_MMA(0, 0, At, B0); PG8_MMA(0, 1, At, B1); PG8_BAR; PG8_SCHED;
	s_waitcnt lgkmcnt(0)
	v_mfma_f32_16x16x32_bf16 v[30:33], v[130:133], v[180:183], v[30:33]
	v_mfma_f32_16x16x32_bf16 v[26:29], v[138:141], v[180:183], v[26:29]
	v_mfma_f32_16x16x32_bf16 v[42:45], v[130:133], v[188:191], v[42:45]
	v_mfma_f32_16x16x32_bf16 v[34:37], v[138:141], v[188:191], v[34:37]
	v_mfma_f32_16x16x32_bf16 v[70:73], v[130:133], v[196:199], v[70:73]
	v_mfma_f32_16x16x32_bf16 v[78:81], v[138:141], v[196:199], v[78:81]
	v_mfma_f32_16x16x32_bf16 v[14:17], v[130:133], v[172:175], v[14:17]
	v_mfma_f32_16x16x32_bf16 v[10:13], v[138:141], v[172:175], v[10:13]
	v_mfma_f32_16x16x32_bf16 v[30:33], v[134:137], v[184:187], v[30:33]
	v_mfma_f32_16x16x32_bf16 v[26:29], v[142:145], v[184:187], v[26:29]
	v_mfma_f32_16x16x32_bf16 v[42:45], v[134:137], v[192:195], v[42:45]
	v_mfma_f32_16x16x32_bf16 v[34:37], v[142:145], v[192:195], v[34:37]
	v_mfma_f32_16x16x32_bf16 v[70:73], v[134:137], v[214:217], v[70:73]
	v_mfma_f32_16x16x32_bf16 v[78:81], v[142:145], v[214:217], v[78:81]
	v_mfma_f32_16x16x32_bf16 v[14:17], v[134:137], v[176:179], v[14:17]
	v_mfma_f32_16x16x32_bf16 v[10:13], v[142:145], v[176:179], v[10:13]
	s_nop 0

; #define PG8_MMA(ai, bj, At, Bt) do { __builtin_amdgcn_s_setprio(1); _Pragma("unroll") for (int m = 0; m < 4; ++m) _Pragma("unroll") for (int n = 0; n < 2; ++n) _Pragma("unroll") for (int k = 0; k < 2; ++k) \
;         acc[ai][bj][m][n] = __builtin_amdgcn_mfma_f32_16x16x32_bf16(Bt[n][k], At[m][k], acc[ai][bj][m][n], 0, 0, 0); __builtin_amdgcn_s_setprio(0); } while (0)
; #define PG8_WAIT_V(n) asm volatile("s_waitcnt vmcnt(" #n ")" ::: "memory")
; #define PG8_WAIT_L(n) asm volatile("s_waitcnt lgkmcnt(" #n ")" ::: "memory")
; #define PG8_BAR __builtin_amdgcn_s_barrier()
; #define PG8_SCHED __builtin_amdgcn_sched_barrier(0)
; template <class Epi, bool ALIGN_EPI>
; __device__ __forceinline__ void gemm_phase(LAS unsigned char* lds, const Gemm g, const StaticOrder& S, const Epi& E, const int tid) {
;     ...
;             PG8_WAIT_V(8); PG8_WAIT_L(0); PG8_BAR; PG8_MMA(0, 0, At, B0); PG8_MMA(0, 1, At, B1); PG8_BAR; PG8_SCHED;
	v_mfma_f32_16x16x32_bf16 v[6:9], v[146:149], v[172:175], v[6:9]
	v_mfma_f32_16x16x32_bf16 v[2:5], v[154:157], v[172:175], v[2:5]
	v_mfma_f32_16x16x32_bf16 v[22:25], v[146:149], v[180:183], v[22:25]
	v_mfma_f32_16x16x32_bf16 v[18:21], v[154:157], v[180:183], v[18:21]
	v_mfma_f32_16x16x32_bf16 v[38:41], v[146:149], v[188:191], v[38:41]
	v_mfma_f32_16x16x32_bf16 v[46:49], v[154:157], v[188:191], v[46:49]
	v_mfma_f32_16x16x32_bf16 v[62:65], v[146:149], v[196:199], v[62:65]
	v_mfma_f32_16x16x32_bf16 v[74:77], v[154:157], v[196:199], v[74:77]
	v_mfma_f32_16x16x32_bf16 v[6:9], v[150:153], v[176:179], v[6:9]
	v_mfma_f32_16x16x32_bf16 v[2:5], v[164:167], v[176:179], v[2:5]
	v_mfma_f32_16x16x32_bf16 v[22:25], v[150:153], v[184:187], v[22:25]
	v_mfma_f32_16x16x32_bf16 v[18:21], v[164:167], v[184:187], v[18:21]
	v_mfma_f32_16x16x32_bf16 v[38:41], v[150:153], v[192:195], v[38:41]
	v_mfma_f32_16x16x32_bf16 v[46:49], v[164:167], v[192:195], v[46:49]
	v_mfma_f32_16x16x32_bf16 v[62:65], v[150:153], v[214:217], v[62:65]
	v_mfma_f32_16x16x32_bf16 v[74:77], v[164:167], v[214:217], v[74:77]

; #define PG8_STAGE(bufoff, gbase, voff) do { _Pragma("unroll") for (int _i = 0; _i < 2; ++_i) \
;         __builtin_amdgcn_global_load_lds((const unsigned*)((const char*)(gbase) + (voff)[_i]), (LAS unsigned*)(lds + (bufoff) + ldsw + _i * 8192), 16, 0, 0); } while (0)
; #define PG8_LDA(dst, b, h) do { _Pragma("unroll") for (int m = 0; m < 4; ++m) _Pragma("unroll") for (int k = 0; k < 2; ++k) dst[m][k] = *(const LAS bf16x8*)(lds + PG8_SA(b, h) + aoff + m * 2048 + k * 1024); } while (0)
; #define PG8_MMA(ai, bj, At, Bt) do { __builtin_amdgcn_s_setprio(1); _Pragma("unroll") for (int m = 0; m < 4; ++m) _Pragma("unroll") for (int n = 0; n < 2; ++n) _Pragma("unroll") for (int k = 0; k < 2; ++k) \
;         acc[ai][bj][m][n] = __builtin_amdgcn_mfma_f32_16x16x32_bf16(Bt[n][k], At[m][k], acc[ai][bj][m][n], 0, 0, 0); __builtin_amdgcn_s_setprio(0); } while (0)
; #define PG8_WAIT_V(n) asm volatile("s_waitcnt vmcnt(" #n ")" ::: "memory")
; #define PG8_WAIT_L(n) asm volatile("s_waitcnt lgkmcnt(" #n ")" ::: "memory")
; #define PG8_BAR __builtin_amdgcn_s_barrier()
; #define PG8_SCHED __builtin_amdgcn_sched_barrier(0)
; template <class Epi, bool ALIGN_EPI>
; __device__ __forceinline__ void gemm_phase(LAS unsigned char* lds, const Gemm g, const StaticOrder& S, const Epi& E, const int tid) {
;     ...
;             PG8_LDA(At, 0, 1); PG8_STAGE(PG8_SB(0, 0), b2, voffB); PG8_STAGE(PG8_SB(0, 1), b2 + hstepB, voffB); PG8_STAGE(PG8_SA(0, 0), a2, voffA);
;             PG8_WAIT_V(8); PG8_WAIT_L(0); PG8_BAR; PG8_MMA(1, 0, At, B0); PG8_MMA(1, 1, At, B1); PG8_BAR; PG8_SCHED;
	s_barrier
	v_lshl_add_u64 v[168:169], s[52:53], 0, v[0:1]
	s_mov_b64 s[90:91], 0x100
	s_add_i32 s85, s45, s72
	v_lshl_add_u64 v[200:201], v[168:169], 0, s[90:91]
	s_mov_b32 m0, s85
	s_add_i32 s45, s85, 0x2000
	ds_read_b128 v[172:175], v171 offset:16384
	ds_read_b128 v[176:179], v171 offset:17408
	ds_read_b128 v[180:183], v171 offset:18432
	ds_read_b128 v[184:187], v171 offset:19456
	ds_read_b128 v[188:191], v171 offset:20480
	ds_read_b128 v[192:195], v171 offset:21504
	ds_read_b128 v[196:199], v171 offset:22528
	ds_read_b128 v[214:217], v171 offset:23552
	global_load_lds_dwordx4 v[200:201], off
	v_lshl_add_u64 v[200:201], s[52:53], 0, v[158:159]
	s_add_u32 s88, s52, 0x10100
	v_lshl_add_u64 v[210:211], v[200:201], 0, s[90:91]
	s_mov_b32 m0, s45
	s_addc_u32 s89, s53, 0
	s_add_i32 s83, s83, s72
	global_load_lds_dwordx4 v[210:211], off
	v_lshl_add_u64 v[210:211], s[88:89], 0, v[0:1]
	s_mov_b32 m0, s83
	s_add_i32 s84, s83, 0x2000
	global_load_lds_dwordx4 v[210:211], off
	v_lshl_add_u64 v[210:211], s[88:89], 0, v[158:159]
	s_mov_b32 m0, s84
	s_nop 0
	global_load_lds_dwordx4 v[210:211], off
	v_lshl_add_u64 v[210:211], s[50:51], 0, v[162:163]
	v_lshl_add_u64 v[218:219], v[210:211], 0, s[90:91]
	s_mov_b32 m0, s73
	s_nop 0
	global_load_lds_dwordx4 v[218:219], off
	v_lshl_add_u64 v[218:219], s[50:51], 0, v[160:161]
	v_lshl_add_u64 v[220:221], v[218:219], 0, s[90:91]
	s_mov_b32 m0, s74
	s_nop 0
	global_load_lds_dwordx4 v[220:221], off
	s_waitcnt vmcnt(8)
	s_waitcnt lgkmcnt(0)
	s_barrier

; #define PG8_MMA(ai, bj, At, Bt) do { __builtin_amdgcn_s_setprio(1); _Pragma("unroll") for (int m = 0; m < 4; ++m) _Pragma("unroll") for (int n = 0; n < 2; ++n) _Pragma("unroll") for (int k = 0; k < 2; ++k) \
;         acc[ai][bj][m][n] = __builtin_amdgcn_mfma_f32_16x16x32_bf16(Bt[n][k], At[m][k], acc[ai][bj][m][n], 0, 0, 0); __builtin_amdgcn_s_setprio(0); } while (0)
; #define PG8_WAIT_V(n) asm volatile("s_waitcnt vmcnt(" #n ")" ::: "memory")
; #define PG8_WAIT_L(n) asm volatile("s_waitcnt lgkmcnt(" #n ")" ::: "memory")
; #define PG8_BAR __builtin_amdgcn_s_barrier()
; #define PG8_SCHED __builtin_amdgcn_sched_barrier(0)
; template <class Epi, bool ALIGN_EPI>
; __device__ __forceinline__ void gemm_phase(LAS unsigned char* lds, const Gemm g, const StaticOrder& S, const Epi& E, const int tid) {
;     ...
;             PG8_WAIT_V(8); PG8_WAIT_L(0); PG8_BAR; PG8_MMA(1, 0, At, B0); PG8_MMA(1, 1, At, B1); PG8_BAR; PG8_SCHED;
	s_waitcnt lgkmcnt(0)
	v_mfma_f32_16x16x32_bf16 v[50:53], v[130:133], v[172:175], v[50:53]
	v_mfma_f32_16x16x32_bf16 v[58:61], v[138:141], v[172:175], v[58:61]
	v_mfma_f32_16x16x32_bf16 v[82:85], v[130:133], v[180:183], v[82:85]
	v_mfma_f32_16x16x32_bf16 v[90:93], v[138:141], v[180:183], v[90:93]
	v_mfma_f32_16x16x32_bf16 v[98:101], v[130:133], v[188:191], v[98:101]
	v_mfma_f32_16x16x32_bf16 v[106:109], v[138:141], v[188:191], v[106:109]
	v_mfma_f32_16x16x32_bf16 v[118:121], v[130:133], v[196:199], v[118:121]
	v_mfma_f32_16x16x32_bf16 v[126:129], v[138:141], v[196:199], v[126:129]
	v_mfma_f32_16x16x32_bf16 v[50:53], v[134:137], v[176:179], v[50:53]
	v_mfma_f32_16x16x32_bf16 v[58:61], v[142:145], v[176:179], v[58:61]
	v_mfma_f32_16x16x32_bf16 v[82:85], v[134:137], v[184:187], v[82:85]
	v_mfma_f32_16x16x32_bf16 v[90:93], v[142:145], v[184:187], v[90:93]
	v_mfma_f32_16x16x32_bf16 v[98:101], v[134:137], v[192:195], v[98:101]
	v_mfma_f32_16x16x32_bf16 v[106:109], v[142:145], v[192:195], v[106:109]
	v_mfma_f32_16x16x32_bf16 v[118:121], v[134:137], v[214:217], v[118:121]
	v_mfma_f32_16x16x32_bf16 v[126:129], v[142:145], v[214:217], v[126:129]
	s_nop 0

; #define PG8_MMA(ai, bj, At, Bt) do { __builtin_amdgcn_s_setprio(1); _Pragma("unroll") for (int m = 0; m < 4; ++m) _Pragma("unroll") for (int n = 0; n < 2; ++n) _Pragma("unroll") for (int k = 0; k < 2; ++k) \
;         acc[ai][bj][m][n] = __builtin_amdgcn_mfma_f32_16x16x32_bf16(Bt[n][k], At[m][k], acc[ai][bj][m][n], 0, 0, 0); __builtin_amdgcn_s_setprio(0); } while (0)
; #define PG8_WAIT_V(n) asm volatile("s_waitcnt vmcnt(" #n ")" ::: "memory")
; #define PG8_WAIT_L(n) asm volatile("s_waitcnt lgkmcnt(" #n ")" ::: "memory")
; #define PG8_BAR __builtin_amdgcn_s_barrier()
; #define PG8_SCHED __builtin_amdgcn_sched_barrier(0)
; template <class Epi, bool ALIGN_EPI>
; __device__ __forceinline__ void gemm_phase(LAS unsigned char* lds, const Gemm g, const StaticOrder& S, const Epi& E, const int tid) {
;     ...
;             PG8_WAIT_V(8); PG8_WAIT_L(0); PG8_BAR; PG8_MMA(1, 0, At, B0); PG8_MMA(1, 1, At, B1); PG8_BAR; PG8_SCHED;
	v_mfma_f32_16x16x32_bf16 v[54:57], v[146:149], v[172:175], v[54:57]
	v_mfma_f32_16x16x32_bf16 v[66:69], v[154:157], v[172:175], v[66:69]
	v_mfma_f32_16x16x32_bf16 v[86:89], v[146:149], v[180:183], v[86:89]
	v_mfma_f32_16x16x32_bf16 v[94:97], v[154:157], v[180:183], v[94:97]
	v_mfma_f32_16x16x32_bf16 v[102:105], v[146:149], v[188:191], v[102:105]
	v_mfma_f32_16x16x32_bf16 v[110:113], v[154:157], v[188:191], v[110:113]
	v_mfma_f32_16x16x32_bf16 v[122:125], v[146:149], v[196:199], v[122:125]
	v_mfma_f32_16x16x32_bf16 v[114:117], v[154:157], v[196:199], v[114:117]
	v_mfma_f32_16x16x32_bf16 v[54:57], v[150:153], v[176:179], v[54:57]
	v_mfma_f32_16x16x32_bf16 v[66:69], v[164:167], v[176:179], v[66:69]
	v_mfma_f32_16x16x32_bf16 v[86:89], v[150:153], v[184:187], v[86:89]
	v_mfma_f32_16x16x32_bf16 v[94:97], v[164:167], v[184:187], v[94:97]
	v_mfma_f32_16x16x32_bf16 v[102:105], v[150:153], v[192:195], v[102:105]
	v_mfma_f32_16x16x32_bf16 v[110:113], v[164:167], v[192:195], v[110:113]
	v_mfma_f32_16x16x32_bf16 v[122:125], v[150:153], v[214:217], v[122:125]
	v_mfma_f32_16x16x32_bf16 v[114:117], v[164:167], v[214:217], v[114:117]

; #define PG8_STAGE(bufoff, gbase, voff) do { _Pragma("unroll") for (int _i = 0; _i < 2; ++_i) \
;         __builtin_amdgcn_global_load_lds((const unsigned*)((const char*)(gbase) + (voff)[_i]), (LAS unsigned*)(lds + (bufoff) + ldsw + _i * 8192), 16, 0, 0); } while (0)
; #define PG8_LDA(dst, b, h) do { _Pragma("unroll") for (int m = 0; m < 4; ++m) _Pragma("unroll") for (int k = 0; k < 2; ++k) dst[m][k] = *(const LAS bf16x8*)(lds + PG8_SA(b, h) + aoff + m * 2048 + k * 1024); } while (0)
; #define PG8_LDB(dst, b, h) do { _Pragma("unroll") for (int n = 0; n < 2; ++n) _Pragma("unroll") for (int k = 0; k < 2; ++k) dst[n][k] = *(const LAS bf16x8*)(lds + PG8_SB(b, h) + boff + n * 2048 + k * 1024); } while (0)
; #define PG8_MMA(ai, bj, At, Bt) do { __builtin_amdgcn_s_setprio(1); _Pragma("unroll") for (int m = 0; m < 4; ++m) _Pragma("unroll") for (int n = 0; n < 2; ++n) _Pragma("unroll") for (int k = 0; k < 2; ++k) \
;         acc[ai][bj][m][n] = __builtin_amdgcn_mfma_f32_16x16x32_bf16(Bt[n][k], At[m][k], acc[ai][bj][m][n], 0, 0, 0); __builtin_amdgcn_s_setprio(0); } while (0)
; #define PG8_WAIT_V(n) asm volatile("s_waitcnt vmcnt(" #n ")" ::: "memory")
; #define PG8_WAIT_L(n) asm volatile("s_waitcnt lgkmcnt(" #n ")" ::: "memory")
; #define PG8_BAR __builtin_amdgcn_s_barrier()
; #define PG8_SCHED __builtin_amdgcn_sched_barrier(0)
; template <class Epi, bool ALIGN_EPI>
; __device__ __forceinline__ void gemm_phase(LAS unsigned char* lds, const Gemm g, const StaticOrder& S, const Epi& E, const int tid) {
;     ...
;             PG8_LDB(B0, 1, 0); PG8_LDB(B1, 1, 1); PG8_SCHED; PG8_LDA(At, 1, 0); PG8_STAGE(PG8_SA(0, 1), a2 + hstepA, voffA);
;             PG8_WAIT_V(8); PG8_WAIT_L(0); PG8_BAR; PG8_MMA(0, 0, At, B0); PG8_MMA(0, 1, At, B1); PG8_BAR; PG8_SCHED;
	s_barrier
	s_add_i32 s86, 0, 0x18000
	s_add_i32 s92, 0, 0x1c000
	v_add_u32_e32 v224, s86, v170
	v_add_u32_e32 v225, s92, v170
	ds_read_b128 v[130:133], v224
	ds_read_b128 v[134:137], v224 offset:1024
	ds_read_b128 v[138:141], v224 offset:2048
	ds_read_b128 v[142:145], v224 offset:3072
	ds_read_b128 v[146:149], v225
	ds_read_b128 v[150:153], v225 offset:1024
	ds_read_b128 v[154:157], v225 offset:2048
	ds_read_b128 v[164:167], v225 offset:3072
	s_add_u32 s88, s50, 0x40100
	s_addc_u32 s89, s51, 0
	s_mov_b32 m0, s75
	v_lshl_add_u64 v[220:221], s[88:89], 0, v[162:163]
	ds_read_b128 v[172:175], v171 offset:32768
	ds_read_b128 v[176:179], v171 offset:33792
	ds_read_b128 v[180:183], v171 offset:34816
	ds_read_b128 v[184:187], v171 offset:35840
	ds_read_b128 v[188:191], v171 offset:36864
	ds_read_b128 v[192:195], v171 offset:37888
	ds_read_b128 v[196:199], v171 offset:38912
	ds_read_b128 v[214:217], v171 offset:39936
	global_load_lds_dwordx4 v[220:221], off
	v_lshl_add_u64 v[220:221], s[88:89], 0, v[160:161]
	s_mov_b32 m0, s76
	s_nop 0
	global_load_lds_dwordx4 v[220:221], off
	s_waitcnt vmcnt(8)
	s_waitcnt lgkmcnt(0)
	s_barrier

; #define PG8_MMA(ai, bj, At, Bt) do { __builtin_amdgcn_s_setprio(1); _Pragma("unroll") for (int m = 0; m < 4; ++m) _Pragma("unroll") for (int n = 0; n < 2; ++n) _Pragma("unroll") for (int k = 0; k < 2; ++k) \
;         acc[ai][bj][m][n] = __builtin_amdgcn_mfma_f32_16x16x32_bf16(Bt[n][k], At[m][k], acc[ai][bj][m][n], 0, 0, 0); __builtin_amdgcn_s_setprio(0); } while (0)
; #define PG8_WAIT_V(n) asm volatile("s_waitcnt vmcnt(" #n ")" ::: "memory")
; #define PG8_WAIT_L(n) asm volatile("s_waitcnt lgkmcnt(" #n ")" ::: "memory")
; #define PG8_BAR __builtin_amdgcn_s_barrier()
; #define PG8_SCHED __builtin_amdgcn_sched_barrier(0)
; template <class Epi, bool ALIGN_EPI>
; __device__ __forceinline__ void gemm_phase(LAS unsigned char* lds, const Gemm g, const StaticOrder& S, const Epi& E, const int tid) {
;     ...
;             PG8_WAIT_V(8); PG8_WAIT_L(0); PG8_BAR; PG8_MMA(0, 0, At, B0); PG8_MMA(0, 1, At, B1); PG8_BAR; PG8_SCHED;
	s_waitcnt lgkmcnt(0)
	v_mfma_f32_16x16x32_bf16 v[30:33], v[130:133], v[180:183], v[30:33]
	v_mfma_f32_16x16x32_bf16 v[26:29], v[138:141], v[180:183], v[26:29]
	v_mfma_f32_16x16x32_bf16 v[42:45], v[130:133], v[188:191], v[42:45]
	v_mfma_f32_16x16x32_bf16 v[34:37], v[138:141], v[188:191], v[34:37]
	v_mfma_f32_16x16x32_bf16 v[70:73], v[130:133], v[196:199], v[70:73]
	v_mfma_f32_16x16x32_bf16 v[78:81], v[138:141], v[196:199], v[78:81]
	v_mfma_f32_16x16x32_bf16 v[14:17], v[130:133], v[172:175], v[14:17]
	v_mfma_f32_16x16x32_bf16 v[10:13], v[138:141], v[172:175], v[10:13]
	v_mfma_f32_16x16x32_bf16 v[30:33], v[134:137], v[184:187], v[30:33]
	v_mfma_f32_16x16x32_bf16 v[26:29], v[142:145], v[184:187], v[26:29]
	v_mfma_f32_16x16x32_bf16 v[42:45], v[134:137], v[192:195], v[42:45]
	v_mfma_f32_16x16x32_bf16 v[34:37], v[142:145], v[192:195], v[34:37]
	v_mfma_f32_16x16x32_bf16 v[70:73], v[134:137], v[214:217], v[70:73]
	v_mfma_f32_16x16x32_bf16 v[78:81], v[142:145], v[214:217], v[78:81]
	v_mfma_f32_16x16x32_bf16 v[14:17], v[134:137], v[176:179], v[14:17]
	v_mfma_f32_16x16x32_bf16 v[10:13], v[142:145], v[176:179], v[10:13]
	s_nop 0

; #define PG8_MMA(ai, bj, At, Bt) do { __builtin_amdgcn_s_setprio(1); _Pragma("unroll") for (int m = 0; m < 4; ++m) _Pragma("unroll") for (int n = 0; n < 2; ++n) _Pragma("unroll") for (int k = 0; k < 2; ++k) \
;         acc[ai][bj][m][n] = __builtin_amdgcn_mfma_f32_16x16x32_bf16(Bt[n][k], At[m][k], acc[ai][bj][m][n], 0, 0, 0); __builtin_amdgcn_s_setprio(0); } while (0)
; #define PG8_WAIT_V(n) asm volatile("s_waitcnt vmcnt(" #n ")" ::: "memory")
; #define PG8_WAIT_L(n) asm volatile("s_waitcnt lgkmcnt(" #n ")" ::: "memory")
; #define PG8_BAR __builtin_amdgcn_s_barrier()
; #define PG8_SCHED __builtin_amdgcn_sched_barrier(0)
; template <class Epi, bool ALIGN_EPI>
; __device__ __forceinline__ void gemm_phase(LAS unsigned char* lds, const Gemm g, const StaticOrder& S, const Epi& E, const int tid) {
;     ...
;             PG8_WAIT_V(8); PG8_WAIT_L(0); PG8_BAR; PG8_MMA(0, 0, At, B0); PG8_MMA(0, 1, At, B1); PG8_BAR; PG8_SCHED;
	v_mfma_f32_16x16x32_bf16 v[6:9], v[146:149], v[172:175], v[6:9]
	v_mfma_f32_16x16x32_bf16 v[2:5], v[154:157], v[172:175], v[2:5]
	v_mfma_f32_16x16x32_bf16 v[22:25], v[146:149], v[180:183], v[22:25]
	v_mfma_f32_16x16x32_bf16 v[18:21], v[154:157], v[180:183], v[18:21]
	v_mfma_f32_16x16x32_bf16 v[38:41], v[146:149], v[188:191], v[38:41]
	v_mfma_f32_16x16x32_bf16 v[46:49], v[154:157], v[188:191], v[46:49]
	v_mfma_f32_16x16x32_bf16 v[62:65], v[146:149], v[196:199], v[62:65]
	v_mfma_f32_16x16x32_bf16 v[74:77], v[154:157], v[196:199], v[74:77]
	v_mfma_f32_16x16x32_bf16 v[6:9], v[150:153], v[176:179], v[6:9]
	v_mfma_f32_16x16x32_bf16 v[2:5], v[164:167], v[176:179], v[2:5]
	v_mfma_f32_16x16x32_bf16 v[22:25], v[150:153], v[184:187], v[22:25]
	v_mfma_f32_16x16x32_bf16 v[18:21], v[164:167], v[184:187], v[18:21]
	v_mfma_f32_16x16x32_bf16 v[38:41], v[150:153], v[192:195], v[38:41]
	v_mfma_f32_16x16x32_bf16 v[46:49], v[164:167], v[192:195], v[46:49]
	v_mfma_f32_16x16x32_bf16 v[62:65], v[150:153], v[214:217], v[62:65]
	v_mfma_f32_16x16x32_bf16 v[74:77], v[164:167], v[214:217], v[74:77]

; #define PG8_STAGE(bufoff, gbase, voff) do { _Pragma("unroll") for (int _i = 0; _i < 2; ++_i) \
;         __builtin_amdgcn_global_load_lds((const unsigned*)((const char*)(gbase) + (voff)[_i]), (LAS unsigned*)(lds + (bufoff) + ldsw + _i * 8192), 16, 0, 0); } while (0)
; #define PG8_LDA(dst, b, h) do { _Pragma("unroll") for (int m = 0; m < 4; ++m) _Pragma("unroll") for (int k = 0; k < 2; ++k) dst[m][k] = *(const LAS bf16x8*)(lds + PG8_SA(b, h) + aoff + m * 2048 + k * 1024); } while (0)
; #define PG8_MMA(ai, bj, At, Bt) do { __builtin_amdgcn_s_setprio(1); _Pragma("unroll") for (int m = 0; m < 4; ++m) _Pragma("unroll") for (int n = 0; n < 2; ++n) _Pragma("unroll") for (int k = 0; k < 2; ++k) \
;         acc[ai][bj][m][n] = __builtin_amdgcn_mfma_f32_16x16x32_bf16(Bt[n][k], At[m][k], acc[ai][bj][m][n], 0, 0, 0); __builtin_amdgcn_s_setprio(0); } while (0)
; #define PG8_WAIT_V(n) asm volatile("s_waitcnt vmcnt(" #n ")" ::: "memory")
; #define PG8_WAIT_L(n) asm volatile("s_waitcnt lgkmcnt(" #n ")" ::: "memory")
; #define PG8_BAR __builtin_amdgcn_s_barrier()
; #define PG8_SCHED __builtin_amdgcn_sched_barrier(0)
; template <class Epi, bool ALIGN_EPI>
; __device__ __forceinline__ void gemm_phase(LAS unsigned char* lds, const Gemm g, const StaticOrder& S, const Epi& E, const int tid) {
;     ...
;             PG8_LDA(At, 1, 1); PG8_STAGE(PG8_SB(1, 0), b3, voffB); PG8_STAGE(PG8_SB(1, 1), b3 + hstepB, voffB); PG8_STAGE(PG8_SA(1, 0), a3, voffA);
;             PG8_WAIT_V(8); PG8_WAIT_L(0); PG8_BAR; PG8_MMA(1, 0, At, B0); PG8_MMA(1, 1, At, B1); PG8_BAR; PG8_SCHED;
	s_barrier
	s_add_i32 s88, s86, s72
	s_mov_b64 vcc, 0x180
	s_add_i32 s86, s88, 0x2000
	v_lshl_add_u64 v[168:169], v[168:169], 0, vcc
	s_mov_b32 m0, s88
	s_add_u32 s90, s52, 0x10180
	ds_read_b128 v[172:175], v171 offset:49152
	ds_read_b128 v[176:179], v171 offset:50176
	ds_read_b128 v[180:183], v171 offset:51200
	ds_read_b128 v[184:187], v171 offset:52224
	ds_read_b128 v[188:191], v171 offset:53248
	ds_read_b128 v[192:195], v171 offset:54272
	ds_read_b128 v[196:199], v171 offset:55296
	ds_read_b128 v[214:217], v171 offset:56320
	global_load_lds_dwordx4 v[168:169], off
	v_lshl_add_u64 v[168:169], v[200:201], 0, vcc
	s_mov_b32 m0, s86
	s_addc_u32 s91, s53, 0
	s_add_i32 s52, s92, s72
	global_load_lds_dwordx4 v[168:169], off
	v_lshl_add_u64 v[168:169], s[90:91], 0, v[0:1]
	s_mov_b32 m0, s52
	s_add_i32 s53, s52, 0x2000
	global_load_lds_dwordx4 v[168:169], off
	v_lshl_add_u64 v[168:169], s[90:91], 0, v[158:159]
	s_mov_b32 m0, s53
	s_nop 0
	global_load_lds_dwordx4 v[168:169], off
	v_lshl_add_u64 v[168:169], v[210:211], 0, vcc
	s_mov_b32 m0, s79
	s_nop 0
	global_load_lds_dwordx4 v[168:169], off
	v_lshl_add_u64 v[168:169], v[218:219], 0, vcc
	s_mov_b32 m0, s80
	s_nop 0
	global_load_lds_dwordx4 v[168:169], off
	s_waitcnt vmcnt(8)
	s_waitcnt lgkmcnt(0)
	s_barrier

; #define PG8_MMA(ai, bj, At, Bt) do { __builtin_amdgcn_s_setprio(1); _Pragma("unroll") for (int m = 0; m < 4; ++m) _Pragma("unroll") for (int n = 0; n < 2; ++n) _Pragma("unroll") for (int k = 0; k < 2; ++k) \
;         acc[ai][bj][m][n] = __builtin_amdgcn_mfma_f32_16x16x32_bf16(Bt[n][k], At[m][k], acc[ai][bj][m][n], 0, 0, 0); __builtin_amdgcn_s_setprio(0); } while (0)
; #define PG8_WAIT_V(n) asm volatile("s_waitcnt vmcnt(" #n ")" ::: "memory")
; #define PG8_WAIT_L(n) asm volatile("s_waitcnt lgkmcnt(" #n ")" ::: "memory")
; #define PG8_BAR __builtin_amdgcn_s_barrier()
; #define PG8_SCHED __builtin_amdgcn_sched_barrier(0)
; template <class Epi, bool ALIGN_EPI>
; __device__ __forceinline__ void gemm_phase(LAS unsigned char* lds, const Gemm g, const StaticOrder& S, const Epi& E, const int tid) {
;     ...
;             PG8_WAIT_V(8); PG8_WAIT_L(0); PG8_BAR; PG8_MMA(1, 0, At, B0); PG8_MMA(1, 1, At, B1); PG8_BAR; PG8_SCHED;
	s_waitcnt lgkmcnt(0)
	v_mfma_f32_16x16x32_bf16 v[50:53], v[130:133], v[172:175], v[50:53]
	v_mfma_f32_16x16x32_bf16 v[58:61], v[138:141], v[172:175], v[58:61]
	v_mfma_f32_16x16x32_bf16 v[82:85], v[130:133], v[180:183], v[82:85]
	v_mfma_f32_16x16x32_bf16 v[90:93], v[138:141], v[180:183], v[90:93]
	v_mfma_f32_16x16x32_bf16 v[98:101], v[130:133], v[188:191], v[98:101]
	v_mfma_f32_16x16x32_bf16 v[106:109], v[138:141], v[188:191], v[106:109]
	v_mfma_f32_16x16x32_bf16 v[118:121], v[130:133], v[196:199], v[118:121]
	v_mfma_f32_16x16x32_bf16 v[126:129], v[138:141], v[196:199], v[126:129]
	v_mfma_f32_16x16x32_bf16 v[50:53], v[134:137], v[176:179], v[50:53]
	v_mfma_f32_16x16x32_bf16 v[58:61], v[142:145], v[176:179], v[58:61]
	v_mfma_f32_16x16x32_bf16 v[82:85], v[134:137], v[184:187], v[82:85]
	v_mfma_f32_16x16x32_bf16 v[90:93], v[142:145], v[184:187], v[90:93]
	v_mfma_f32_16x16x32_bf16 v[98:101], v[134:137], v[192:195], v[98:101]
	v_mfma_f32_16x16x32_bf16 v[106:109], v[142:145], v[192:195], v[106:109]
	v_mfma_f32_16x16x32_bf16 v[118:121], v[134:137], v[214:217], v[118:121]
	v_mfma_f32_16x16x32_bf16 v[126:129], v[142:145], v[214:217], v[126:129]
	s_nop 0

; #define PG8_MMA(ai, bj, At, Bt) do { __builtin_amdgcn_s_setprio(1); _Pragma("unroll") for (int m = 0; m < 4; ++m) _Pragma("unroll") for (int n = 0; n < 2; ++n) _Pragma("unroll") for (int k = 0; k < 2; ++k) \
;         acc[ai][bj][m][n] = __builtin_amdgcn_mfma_f32_16x16x32_bf16(Bt[n][k], At[m][k], acc[ai][bj][m][n], 0, 0, 0); __builtin_amdgcn_s_setprio(0); } while (0)
; #define PG8_WAIT_V(n) asm volatile("s_waitcnt vmcnt(" #n ")" ::: "memory")
; #define PG8_WAIT_L(n) asm volatile("s_waitcnt lgkmcnt(" #n ")" ::: "memory")
; #define PG8_BAR __builtin_amdgcn_s_barrier()
; #define PG8_SCHED __builtin_amdgcn_sched_barrier(0)
; template <class Epi, bool ALIGN_EPI>
; __device__ __forceinline__ void gemm_phase(LAS unsigned char* lds, const Gemm g, const StaticOrder& S, const Epi& E, const int tid) {
;     ...
;             PG8_WAIT_V(8); PG8_WAIT_L(0); PG8_BAR; PG8_MMA(1, 0, At, B0); PG8_MMA(1, 1, At, B1); PG8_BAR; PG8_SCHED;
	v_mfma_f32_16x16x32_bf16 v[54:57], v[146:149], v[172:175], v[54:57]
	v_mfma_f32_16x16x32_bf16 v[66:69], v[154:157], v[172:175], v[66:69]
	v_mfma_f32_16x16x32_bf16 v[86:89], v[146:149], v[180:183], v[86:89]
	v_mfma_f32_16x16x32_bf16 v[94:97], v[154:157], v[180:183], v[94:97]
	v_mfma_f32_16x16x32_bf16 v[102:105], v[146:149], v[188:191], v[102:105]
	v_mfma_f32_16x16x32_bf16 v[110:113], v[154:157], v[188:191], v[110:113]
	v_mfma_f32_16x16x32_bf16 v[122:125], v[146:149], v[196:199], v[122:125]
	v_mfma_f32_16x16x32_bf16 v[114:117], v[154:157], v[196:199], v[114:117]
	v_mfma_f32_16x16x32_bf16 v[54:57], v[150:153], v[176:179], v[54:57]
	v_mfma_f32_16x16x32_bf16 v[66:69], v[164:167], v[176:179], v[66:69]
	v_mfma_f32_16x16x32_bf16 v[86:89], v[150:153], v[184:187], v[86:89]
	v_mfma_f32_16x16x32_bf16 v[94:97], v[164:167], v[184:187], v[94:97]
	v_mfma_f32_16x16x32_bf16 v[102:105], v[150:153], v[192:195], v[102:105]
	v_mfma_f32_16x16x32_bf16 v[110:113], v[164:167], v[192:195], v[110:113]
	v_mfma_f32_16x16x32_bf16 v[122:125], v[150:153], v[214:217], v[122:125]
	v_mfma_f32_16x16x32_bf16 v[114:117], v[164:167], v[214:217], v[114:117]

; #define PG8_STAGE(bufoff, gbase, voff) do { _Pragma("unroll") for (int _i = 0; _i < 2; ++_i) \
;         __builtin_amdgcn_global_load_lds((const unsigned*)((const char*)(gbase) + (voff)[_i]), (LAS unsigned*)(lds + (bufoff) + ldsw + _i * 8192), 16, 0, 0); } while (0)
; #define PG8_LDA(dst, b, h) do { _Pragma("unroll") for (int m = 0; m < 4; ++m) _Pragma("unroll") for (int k = 0; k < 2; ++k) dst[m][k] = *(const LAS bf16x8*)(lds + PG8_SA(b, h) + aoff + m * 2048 + k * 1024); } while (0)
; #define PG8_LDB(dst, b, h) do { _Pragma("unroll") for (int n = 0; n < 2; ++n) _Pragma("unroll") for (int k = 0; k < 2; ++k) dst[n][k] = *(const LAS bf16x8*)(lds + PG8_SB(b, h) + boff + n * 2048 + k * 1024); } while (0)
; #define PG8_MMA(ai, bj, At, Bt) do { __builtin_amdgcn_s_setprio(1); _Pragma("unroll") for (int m = 0; m < 4; ++m) _Pragma("unroll") for (int n = 0; n < 2; ++n) _Pragma("unroll") for (int k = 0; k < 2; ++k) \
;         acc[ai][bj][m][n] = __builtin_amdgcn_mfma_f32_16x16x32_bf16(Bt[n][k], At[m][k], acc[ai][bj][m][n], 0, 0, 0); __builtin_amdgcn_s_setprio(0); } while (0)
; #define PG8_WAIT_V(n) asm volatile("s_waitcnt vmcnt(" #n ")" ::: "memory")
; #define PG8_WAIT_L(n) asm volatile("s_waitcnt lgkmcnt(" #n ")" ::: "memory")
; #define PG8_BAR __builtin_amdgcn_s_barrier()
; #define PG8_SCHED __builtin_amdgcn_sched_barrier(0)
; template <class Epi, bool ALIGN_EPI>
; __device__ __forceinline__ void gemm_phase(LAS unsigned char* lds, const Gemm g, const StaticOrder& S, const Epi& E, const int tid) {
;     ...
;             const char* a2 = last ? nA : cA + (size_t)(t + 2) * kstepA; const char* b2 = last ? nB : cB + (size_t)(t + 2) * kstepB;
;             const char* a3 = a2 + kstepA; const char* b3 = b2 + kstepB;
;             PG8_LDB(B0, 0, 0); PG8_LDB(B1, 0, 1); PG8_SCHED; PG8_LDA(At, 0, 0); PG8_STAGE(PG8_SA(1, 1), a1 + hstepA, voffA);
;             PG8_WAIT_V(8); PG8_WAIT_L(0); PG8_BAR; PG8_MMA(0, 0, At, B0); PG8_MMA(0, 1, At, B1); PG8_BAR; PG8_SCHED;
	s_barrier
	ds_read_b128 v[130:133], v222
	ds_read_b128 v[134:137], v222 offset:1024
	ds_read_b128 v[138:141], v222 offset:2048
	ds_read_b128 v[142:145], v222 offset:3072
	ds_read_b128 v[146:149], v223
	ds_read_b128 v[150:153], v223 offset:1024
	ds_read_b128 v[154:157], v223 offset:2048
	ds_read_b128 v[164:167], v223 offset:3072
	s_add_u32 s50, s50, 0x40180
	s_addc_u32 s51, s51, 0
	s_mov_b32 m0, s87
	v_lshl_add_u64 v[168:169], s[50:51], 0, v[162:163]
	ds_read_b128 v[172:175], v171
	ds_read_b128 v[176:179], v171 offset:1024
	ds_read_b128 v[180:183], v171 offset:2048
	ds_read_b128 v[184:187], v171 offset:3072
	ds_read_b128 v[188:191], v171 offset:4096
	ds_read_b128 v[192:195], v171 offset:5120
	ds_read_b128 v[196:199], v171 offset:6144
	ds_read_b128 v[214:217], v171 offset:7168
	global_load_lds_dwordx4 v[168:169], off
	v_lshl_add_u64 v[168:169], s[50:51], 0, v[160:161]
	s_mov_b32 m0, s43
	s_nop 0
	global_load_lds_dwordx4 v[168:169], off
	s_waitcnt vmcnt(8)
	s_waitcnt lgkmcnt(0)
	s_barrier

; #define PG8_MMA(ai, bj, At, Bt) do { __builtin_amdgcn_s_setprio(1); _Pragma("unroll") for (int m = 0; m < 4; ++m) _Pragma("unroll") for (int n = 0; n < 2; ++n) _Pragma("unroll") for (int k = 0; k < 2; ++k) \
;         acc[ai][bj][m][n] = __builtin_amdgcn_mfma_f32_16x16x32_bf16(Bt[n][k], At[m][k], acc[ai][bj][m][n], 0, 0, 0); __builtin_amdgcn_s_setprio(0); } while (0)
; #define PG8_WAIT_V(n) asm volatile("s_waitcnt vmcnt(" #n ")" ::: "memory")
; #define PG8_WAIT_L(n) asm volatile("s_waitcnt lgkmcnt(" #n ")" ::: "memory")
; #define PG8_BAR __builtin_amdgcn_s_barrier()
; #define PG8_SCHED __builtin_amdgcn_sched_barrier(0)
; template <class Epi, bool ALIGN_EPI>
; __device__ __forceinline__ void gemm_phase(LAS unsigned char* lds, const Gemm g, const StaticOrder& S, const Epi& E, const int tid) {
;     ...
;             PG8_WAIT_V(8); PG8_WAIT_L(0); PG8_BAR; PG8_MMA(0, 0, At, B0); PG8_MMA(0, 1, At, B1); PG8_BAR; PG8_SCHED;
	s_waitcnt lgkmcnt(0)
	v_mfma_f32_16x16x32_bf16 v[30:33], v[130:133], v[180:183], v[30:33]
	v_mfma_f32_16x16x32_bf16 v[26:29], v[138:141], v[180:183], v[26:29]
	v_mfma_f32_16x16x32_bf16 v[42:45], v[130:133], v[188:191], v[42:45]
	v_mfma_f32_16x16x32_bf16 v[34:37], v[138:141], v[188:191], v[34:37]
	v_mfma_f32_16x16x32_bf16 v[70:73], v[130:133], v[196:199], v[70:73]
	v_mfma_f32_16x16x32_bf16 v[78:81], v[138:141], v[196:199], v[78:81]
	v_mfma_f32_16x16x32_bf16 v[14:17], v[130:133], v[172:175], v[14:17]
	v_mfma_f32_16x16x32_bf16 v[10:13], v[138:141], v[172:175], v[10:13]
	v_mfma_f32_16x16x32_bf16 v[30:33], v[134:137], v[184:187], v[30:33]
	v_mfma_f32_16x16x32_bf16 v[26:29], v[142:145], v[184:187], v[26:29]
	v_mfma_f32_16x16x32_bf16 v[42:45], v[134:137], v[192:195], v[42:45]
	v_mfma_f32_16x16x32_bf16 v[34:37], v[142:145], v[192:195], v[34:37]
	v_mfma_f32_16x16x32_bf16 v[70:73], v[134:137], v[214:217], v[70:73]
	v_mfma_f32_16x16x32_bf16 v[78:81], v[142:145], v[214:217], v[78:81]
	v_mfma_f32_16x16x32_bf16 v[14:17], v[134:137], v[176:179], v[14:17]
	v_mfma_f32_16x16x32_bf16 v[10:13], v[142:145], v[176:179], v[10:13]
	s_nop 0

; #define PG8_STAGE(bufoff, gbase, voff) do { _Pragma("unroll") for (int _i = 0; _i < 2; ++_i) \
;         __builtin_amdgcn_global_load_lds((const unsigned*)((const char*)(gbase) + (voff)[_i]), (LAS unsigned*)(lds + (bufoff) + ldsw + _i * 8192), 16, 0, 0); } while (0)
; #define PG8_LDA(dst, b, h) do { _Pragma("unroll") for (int m = 0; m < 4; ++m) _Pragma("unroll") for (int k = 0; k < 2; ++k) dst[m][k] = *(const LAS bf16x8*)(lds + PG8_SA(b, h) + aoff + m * 2048 + k * 1024); } while (0)
; #define PG8_MMA(ai, bj, At, Bt) do { __builtin_amdgcn_s_setprio(1); _Pragma("unroll") for (int m = 0; m < 4; ++m) _Pragma("unroll") for (int n = 0; n < 2; ++n) _Pragma("unroll") for (int k = 0; k < 2; ++k) \
;         acc[ai][bj][m][n] = __builtin_amdgcn_mfma_f32_16x16x32_bf16(Bt[n][k], At[m][k], acc[ai][bj][m][n], 0, 0, 0); __builtin_amdgcn_s_setprio(0); } while (0)
; #define PG8_WAIT_V(n) asm volatile("s_waitcnt vmcnt(" #n ")" ::: "memory")
; #define PG8_WAIT_L(n) asm volatile("s_waitcnt lgkmcnt(" #n ")" ::: "memory")
; #define PG8_BAR __builtin_amdgcn_s_barrier()
; #define PG8_SCHED __builtin_amdgcn_sched_barrier(0)
; template <class Epi, bool ALIGN_EPI>
; __device__ __forceinline__ void gemm_phase(LAS unsigned char* lds, const Gemm g, const StaticOrder& S, const Epi& E, const int tid) {
;     ...
;             PG8_WAIT_V(8); PG8_WAIT_L(0); PG8_BAR; PG8_MMA(0, 0, At, B0); PG8_MMA(0, 1, At, B1); PG8_BAR; PG8_SCHED;
;             PG8_LDA(At, 0, 1); PG8_STAGE(PG8_SB(0, 0), b2, voffB); PG8_STAGE(PG8_SB(0, 1), b2 + hstepB, voffB); PG8_STAGE(PG8_SA(0, 0), a2, voffA);
;             PG8_WAIT_V(8); PG8_WAIT_L(0); PG8_BAR; PG8_MMA(1, 0, At, B0); PG8_MMA(1, 1, At, B1); PG8_BAR; PG8_SCHED;
	v_mfma_f32_16x16x32_bf16 v[2:5], v[154:157], v[172:175], v[2:5]
	v_mfma_f32_16x16x32_bf16 v[6:9], v[146:149], v[172:175], v[6:9]
	v_mfma_f32_16x16x32_bf16 v[172:175], v[164:167], v[176:179], v[2:5]
	v_mfma_f32_16x16x32_bf16 v[2:5], v[146:149], v[180:183], v[22:25]
	v_mfma_f32_16x16x32_bf16 v[218:221], v[150:153], v[176:179], v[6:9]
	v_mfma_f32_16x16x32_bf16 v[176:179], v[150:153], v[184:187], v[2:5]
	v_mfma_f32_16x16x32_bf16 v[2:5], v[154:157], v[180:183], v[18:21]
	v_mfma_f32_16x16x32_bf16 v[180:183], v[164:167], v[184:187], v[2:5]
	v_mfma_f32_16x16x32_bf16 v[2:5], v[146:149], v[188:191], v[38:41]
	v_mfma_f32_16x16x32_bf16 v[38:41], v[150:153], v[192:195], v[2:5]
	v_mfma_f32_16x16x32_bf16 v[2:5], v[154:157], v[188:191], v[46:49]
	v_mfma_f32_16x16x32_bf16 v[46:49], v[164:167], v[192:195], v[2:5]
	v_mfma_f32_16x16x32_bf16 v[2:5], v[146:149], v[196:199], v[62:65]
	v_mfma_f32_16x16x32_bf16 v[62:65], v[150:153], v[214:217], v[2:5]
	v_mfma_f32_16x16x32_bf16 v[2:5], v[154:157], v[196:199], v[74:77]
	v_mfma_f32_16x16x32_bf16 v[74:77], v[164:167], v[214:217], v[2:5]
	s_nop 0
	s_barrier
	s_mov_b32 m0, s85
	v_lshl_add_u64 v[168:169], s[54:55], 0, v[0:1]
	s_add_u32 s50, s54, 0x10000
	s_nop 1
	ds_read_b128 v[2:5], v171 offset:16384
	ds_read_b128 v[6:9], v171 offset:17408
	ds_read_b128 v[18:21], v171 offset:18432
	ds_read_b128 v[22:25], v171 offset:19456
	ds_read_b128 v[184:187], v171 offset:20480
	ds_read_b128 v[188:191], v171 offset:21504
	ds_read_b128 v[192:195], v171 offset:22528
	ds_read_b128 v[196:199], v171 offset:23552
	global_load_lds_dwordx4 v[168:169], off
	v_lshl_add_u64 v[200:201], s[54:55], 0, v[158:159]
	s_mov_b32 m0, s45
	s_addc_u32 s51, s55, 0
	global_load_lds_dwordx4 v[200:201], off
	v_lshl_add_u64 v[210:211], s[50:51], 0, v[0:1]
	s_mov_b32 m0, s83
	v_lshl_add_u64 v[234:235], s[56:57], 0, v[160:161]
	global_load_lds_dwordx4 v[210:211], off
	v_lshl_add_u64 v[210:211], s[50:51], 0, v[158:159]
	s_mov_b32 m0, s84
	s_nop 0
	global_load_lds_dwordx4 v[210:211], off
	v_lshl_add_u64 v[210:211], s[56:57], 0, v[162:163]
	s_mov_b32 m0, s73
	s_nop 0
	global_load_lds_dwordx4 v[210:211], off
	s_mov_b32 m0, s74
	s_nop 0
	global_load_lds_dwordx4 v[234:235], off
	s_waitcnt vmcnt(8)
	s_waitcnt lgkmcnt(0)
	s_barrier

; #define PG8_MMA(ai, bj, At, Bt) do { __builtin_amdgcn_s_setprio(1); _Pragma("unroll") for (int m = 0; m < 4; ++m) _Pragma("unroll") for (int n = 0; n < 2; ++n) _Pragma("unroll") for (int k = 0; k < 2; ++k) \
;         acc[ai][bj][m][n] = __builtin_amdgcn_mfma_f32_16x16x32_bf16(Bt[n][k], At[m][k], acc[ai][bj][m][n], 0, 0, 0); __builtin_amdgcn_s_setprio(0); } while (0)
; #define PG8_WAIT_V(n) asm volatile("s_waitcnt vmcnt(" #n ")" ::: "memory")
; #define PG8_WAIT_L(n) asm volatile("s_waitcnt lgkmcnt(" #n ")" ::: "memory")
; #define PG8_BAR __builtin_amdgcn_s_barrier()
; #define PG8_SCHED __builtin_amdgcn_sched_barrier(0)
; template <class Epi, bool ALIGN_EPI>
; __device__ __forceinline__ void gemm_phase(LAS unsigned char* lds, const Gemm g, const StaticOrder& S, const Epi& E, const int tid) {
;     ...
;             PG8_WAIT_V(8); PG8_WAIT_L(0); PG8_BAR; PG8_MMA(1, 0, At, B0); PG8_MMA(1, 1, At, B1); PG8_BAR; PG8_SCHED;
	s_waitcnt lgkmcnt(0)
	v_mfma_f32_16x16x32_bf16 v[50:53], v[130:133], v[2:5], v[50:53]
	v_mfma_f32_16x16x32_bf16 v[58:61], v[138:141], v[2:5], v[58:61]
	v_mfma_f32_16x16x32_bf16 v[82:85], v[130:133], v[18:21], v[82:85]
	v_mfma_f32_16x16x32_bf16 v[90:93], v[138:141], v[18:21], v[90:93]
	v_mfma_f32_16x16x32_bf16 v[98:101], v[130:133], v[184:187], v[98:101]
	v_mfma_f32_16x16x32_bf16 v[106:109], v[138:141], v[184:187], v[106:109]
	v_mfma_f32_16x16x32_bf16 v[118:121], v[130:133], v[192:195], v[118:121]
	v_mfma_f32_16x16x32_bf16 v[126:129], v[138:141], v[192:195], v[126:129]
	v_mfma_f32_16x16x32_bf16 v[50:53], v[134:137], v[6:9], v[50:53]
	v_mfma_f32_16x16x32_bf16 v[58:61], v[142:145], v[6:9], v[58:61]
	v_mfma_f32_16x16x32_bf16 v[82:85], v[134:137], v[22:25], v[82:85]
	v_mfma_f32_16x16x32_bf16 v[90:93], v[142:145], v[22:25], v[90:93]
	v_mfma_f32_16x16x32_bf16 v[98:101], v[134:137], v[188:191], v[98:101]
	v_mfma_f32_16x16x32_bf16 v[106:109], v[142:145], v[188:191], v[106:109]
	v_mfma_f32_16x16x32_bf16 v[118:121], v[134:137], v[196:199], v[118:121]
	v_mfma_f32_16x16x32_bf16 v[126:129], v[142:145], v[196:199], v[126:129]
	s_nop 0

; #define PG8_STAGE(bufoff, gbase, voff) do { _Pragma("unroll") for (int _i = 0; _i < 2; ++_i) \
;         __builtin_amdgcn_global_load_lds((const unsigned*)((const char*)(gbase) + (voff)[_i]), (LAS unsigned*)(lds + (bufoff) + ldsw + _i * 8192), 16, 0, 0); } while (0)
; #define PG8_LDA(dst, b, h) do { _Pragma("unroll") for (int m = 0; m < 4; ++m) _Pragma("unroll") for (int k = 0; k < 2; ++k) dst[m][k] = *(const LAS bf16x8*)(lds + PG8_SA(b, h) + aoff + m * 2048 + k * 1024); } while (0)
; #define PG8_LDB(dst, b, h) do { _Pragma("unroll") for (int n = 0; n < 2; ++n) _Pragma("unroll") for (int k = 0; k < 2; ++k) dst[n][k] = *(const LAS bf16x8*)(lds + PG8_SB(b, h) + boff + n * 2048 + k * 1024); } while (0)
; #define PG8_MMA(ai, bj, At, Bt) do { __builtin_amdgcn_s_setprio(1); _Pragma("unroll") for (int m = 0; m < 4; ++m) _Pragma("unroll") for (int n = 0; n < 2; ++n) _Pragma("unroll") for (int k = 0; k < 2; ++k) \
;         acc[ai][bj][m][n] = __builtin_amdgcn_mfma_f32_16x16x32_bf16(Bt[n][k], At[m][k], acc[ai][bj][m][n], 0, 0, 0); __builtin_amdgcn_s_setprio(0); } while (0)
; #define PG8_WAIT_V(n) asm volatile("s_waitcnt vmcnt(" #n ")" ::: "memory")
; #define PG8_WAIT_L(n) asm volatile("s_waitcnt lgkmcnt(" #n ")" ::: "memory")
; #define PG8_BAR __builtin_amdgcn_s_barrier()
; #define PG8_SCHED __builtin_amdgcn_sched_barrier(0)
; template <class Epi, bool ALIGN_EPI>
; __device__ __forceinline__ void gemm_phase(LAS unsigned char* lds, const Gemm g, const StaticOrder& S, const Epi& E, const int tid) {
;     ...
;             PG8_WAIT_V(8); PG8_WAIT_L(0); PG8_BAR; PG8_MMA(1, 0, At, B0); PG8_MMA(1, 1, At, B1); PG8_BAR; PG8_SCHED;
;             PG8_LDB(B0, 1, 0); PG8_LDB(B1, 1, 1); PG8_SCHED; PG8_LDA(At, 1, 0); PG8_STAGE(PG8_SA(0, 1), a2 + hstepA, voffA);
;             PG8_WAIT_V(8); PG8_WAIT_L(0); PG8_BAR; PG8_MMA(0, 0, At, B0); PG8_MMA(0, 1, At, B1); PG8_BAR; PG8_SCHED;
	v_mfma_f32_16x16x32_bf16 v[54:57], v[146:149], v[2:5], v[54:57]
	v_mfma_f32_16x16x32_bf16 v[2:5], v[154:157], v[2:5], v[66:69]
	v_mfma_f32_16x16x32_bf16 v[66:69], v[164:167], v[6:9], v[2:5]
	v_mfma_f32_16x16x32_bf16 v[2:5], v[146:149], v[18:21], v[86:89]
	v_mfma_f32_16x16x32_bf16 v[86:89], v[150:153], v[22:25], v[2:5]
	v_mfma_f32_16x16x32_bf16 v[2:5], v[154:157], v[18:21], v[94:97]
	v_mfma_f32_16x16x32_bf16 v[94:97], v[164:167], v[22:25], v[2:5]
	v_mfma_f32_16x16x32_bf16 v[2:5], v[146:149], v[184:187], v[102:105]
	v_mfma_f32_16x16x32_bf16 v[102:105], v[150:153], v[188:191], v[2:5]
	v_mfma_f32_16x16x32_bf16 v[2:5], v[154:157], v[184:187], v[110:113]
	v_mfma_f32_16x16x32_bf16 v[110:113], v[164:167], v[188:191], v[2:5]
	v_mfma_f32_16x16x32_bf16 v[2:5], v[146:149], v[192:195], v[122:125]
	v_mfma_f32_16x16x32_bf16 v[54:57], v[150:153], v[6:9], v[54:57]
	v_mfma_f32_16x16x32_bf16 v[122:125], v[150:153], v[196:199], v[2:5]
	v_mfma_f32_16x16x32_bf16 v[2:5], v[154:157], v[192:195], v[114:117]
	v_mfma_f32_16x16x32_bf16 v[130:133], v[164:167], v[196:199], v[2:5]
	s_nop 0
	s_barrier
	ds_read_b128 v[114:117], v224
	ds_read_b128 v[134:137], v224 offset:1024
	ds_read_b128 v[138:141], v224 offset:2048
	ds_read_b128 v[142:145], v224 offset:3072
	ds_read_b128 v[146:149], v225
	ds_read_b128 v[164:167], v225 offset:1024
	ds_read_b128 v[184:187], v225 offset:2048
	ds_read_b128 v[188:191], v225 offset:3072
	s_add_u32 s50, s56, 0x40000
	s_addc_u32 s51, s57, 0
	s_mov_b32 m0, s75
	v_lshl_add_u64 v[2:3], s[50:51], 0, v[162:163]
	ds_read_b128 v[150:153], v171 offset:32768
	ds_read_b128 v[154:157], v171 offset:33792
	ds_read_b128 v[192:195], v171 offset:34816
	ds_read_b128 v[196:199], v171 offset:35840
	ds_read_b128 v[214:217], v171 offset:36864
	ds_read_b128 v[222:225], v171 offset:37888
	ds_read_b128 v[226:229], v171 offset:38912
	ds_read_b128 v[230:233], v171 offset:39936
	global_load_lds_dwordx4 v[2:3], off
	v_lshl_add_u64 v[2:3], s[50:51], 0, v[160:161]
	s_mov_b32 m0, s76
	s_nop 0
	global_load_lds_dwordx4 v[2:3], off
	s_waitcnt vmcnt(8)
	s_waitcnt lgkmcnt(0)
	s_barrier

; #define PG8_MMA(ai, bj, At, Bt) do { __builtin_amdgcn_s_setprio(1); _Pragma("unroll") for (int m = 0; m < 4; ++m) _Pragma("unroll") for (int n = 0; n < 2; ++n) _Pragma("unroll") for (int k = 0; k < 2; ++k) \
;         acc[ai][bj][m][n] = __builtin_amdgcn_mfma_f32_16x16x32_bf16(Bt[n][k], At[m][k], acc[ai][bj][m][n], 0, 0, 0); __builtin_amdgcn_s_setprio(0); } while (0)
; #define PG8_WAIT_V(n) asm volatile("s_waitcnt vmcnt(" #n ")" ::: "memory")
; #define PG8_WAIT_L(n) asm volatile("s_waitcnt lgkmcnt(" #n ")" ::: "memory")
; #define PG8_BAR __builtin_amdgcn_s_barrier()
; #define PG8_SCHED __builtin_amdgcn_sched_barrier(0)
; template <class Epi, bool ALIGN_EPI>
; __device__ __forceinline__ void gemm_phase(LAS unsigned char* lds, const Gemm g, const StaticOrder& S, const Epi& E, const int tid) {
;     ...
;             PG8_WAIT_V(8); PG8_WAIT_L(0); PG8_BAR; PG8_MMA(0, 0, At, B0); PG8_MMA(0, 1, At, B1); PG8_BAR; PG8_SCHED;
	s_waitcnt lgkmcnt(0)
	v_mfma_f32_16x16x32_bf16 v[6:9], v[138:141], v[150:153], v[10:13]
	v_mfma_f32_16x16x32_bf16 v[10:13], v[114:117], v[192:195], v[30:33]
	v_mfma_f32_16x16x32_bf16 v[18:21], v[134:137], v[196:199], v[10:13]
	v_mfma_f32_16x16x32_bf16 v[10:13], v[138:141], v[192:195], v[26:29]
	v_mfma_f32_16x16x32_bf16 v[22:25], v[142:145], v[196:199], v[10:13]
	v_mfma_f32_16x16x32_bf16 v[10:13], v[114:117], v[214:217], v[42:45]
	v_mfma_f32_16x16x32_bf16 v[42:45], v[134:137], v[222:225], v[10:13]
	v_mfma_f32_16x16x32_bf16 v[10:13], v[138:141], v[214:217], v[34:37]
	v_mfma_f32_16x16x32_bf16 v[34:37], v[142:145], v[222:225], v[10:13]
	v_mfma_f32_16x16x32_bf16 v[10:13], v[114:117], v[226:229], v[70:73]
	v_mfma_f32_16x16x32_bf16 v[2:5], v[114:117], v[150:153], v[14:17]
	v_mfma_f32_16x16x32_bf16 v[70:73], v[134:137], v[230:233], v[10:13]
	v_mfma_f32_16x16x32_bf16 v[10:13], v[138:141], v[226:229], v[78:81]
	v_mfma_f32_16x16x32_bf16 v[2:5], v[134:137], v[154:157], v[2:5]
	v_mfma_f32_16x16x32_bf16 v[6:9], v[142:145], v[154:157], v[6:9]
	v_mfma_f32_16x16x32_bf16 v[78:81], v[142:145], v[230:233], v[10:13]
	s_nop 0

; #define PG8_STAGE(bufoff, gbase, voff) do { _Pragma("unroll") for (int _i = 0; _i < 2; ++_i) \
;         __builtin_amdgcn_global_load_lds((const unsigned*)((const char*)(gbase) + (voff)[_i]), (LAS unsigned*)(lds + (bufoff) + ldsw + _i * 8192), 16, 0, 0); } while (0)
; #define PG8_LDA(dst, b, h) do { _Pragma("unroll") for (int m = 0; m < 4; ++m) _Pragma("unroll") for (int k = 0; k < 2; ++k) dst[m][k] = *(const LAS bf16x8*)(lds + PG8_SA(b, h) + aoff + m * 2048 + k * 1024); } while (0)
; #define PG8_MMA(ai, bj, At, Bt) do { __builtin_amdgcn_s_setprio(1); _Pragma("unroll") for (int m = 0; m < 4; ++m) _Pragma("unroll") for (int n = 0; n < 2; ++n) _Pragma("unroll") for (int k = 0; k < 2; ++k) \
;         acc[ai][bj][m][n] = __builtin_amdgcn_mfma_f32_16x16x32_bf16(Bt[n][k], At[m][k], acc[ai][bj][m][n], 0, 0, 0); __builtin_amdgcn_s_setprio(0); } while (0)
; #define PG8_WAIT_V(n) asm volatile("s_waitcnt vmcnt(" #n ")" ::: "memory")
; #define PG8_WAIT_L(n) asm volatile("s_waitcnt lgkmcnt(" #n ")" ::: "memory")
; #define PG8_BAR __builtin_amdgcn_s_barrier()
; #define PG8_SCHED __builtin_amdgcn_sched_barrier(0)
; template <class Epi, bool ALIGN_EPI>
; __device__ __forceinline__ void gemm_phase(LAS unsigned char* lds, const Gemm g, const StaticOrder& S, const Epi& E, const int tid) {
;     ...
;             PG8_WAIT_V(8); PG8_WAIT_L(0); PG8_BAR; PG8_MMA(0, 0, At, B0); PG8_MMA(0, 1, At, B1); PG8_BAR; PG8_SCHED;
;             PG8_LDA(At, 1, 1); PG8_STAGE(PG8_SB(1, 0), b3, voffB); PG8_STAGE(PG8_SB(1, 1), b3 + hstepB, voffB); PG8_STAGE(PG8_SA(1, 0), a3, voffA);
;             PG8_WAIT_V(8); PG8_WAIT_L(0); PG8_BAR; PG8_MMA(1, 0, At, B0); PG8_MMA(1, 1, At, B1); PG8_BAR; PG8_SCHED;
	v_mfma_f32_16x16x32_bf16 v[10:13], v[146:149], v[150:153], v[218:221]
	v_mfma_f32_16x16x32_bf16 v[26:29], v[164:167], v[154:157], v[10:13]
	v_mfma_f32_16x16x32_bf16 v[10:13], v[184:187], v[150:153], v[172:175]
	v_mfma_f32_16x16x32_bf16 v[30:33], v[188:191], v[154:157], v[10:13]
	v_mfma_f32_16x16x32_bf16 v[10:13], v[146:149], v[192:195], v[176:179]
	v_mfma_f32_16x16x32_bf16 v[150:153], v[164:167], v[196:199], v[10:13]
	v_mfma_f32_16x16x32_bf16 v[10:13], v[184:187], v[192:195], v[180:183]
	v_mfma_f32_16x16x32_bf16 v[154:157], v[188:191], v[196:199], v[10:13]
	v_mfma_f32_16x16x32_bf16 v[10:13], v[146:149], v[214:217], v[38:41]
	v_mfma_f32_16x16x32_bf16 v[38:41], v[164:167], v[222:225], v[10:13]
	v_mfma_f32_16x16x32_bf16 v[10:13], v[184:187], v[214:217], v[46:49]
	v_mfma_f32_16x16x32_bf16 v[46:49], v[188:191], v[222:225], v[10:13]
	v_mfma_f32_16x16x32_bf16 v[10:13], v[146:149], v[226:229], v[62:65]
	v_mfma_f32_16x16x32_bf16 v[62:65], v[164:167], v[230:233], v[10:13]
	v_mfma_f32_16x16x32_bf16 v[10:13], v[184:187], v[226:229], v[74:77]
	v_mfma_f32_16x16x32_bf16 v[74:77], v[188:191], v[230:233], v[10:13]
	s_nop 0
	s_barrier
	s_mov_b32 m0, s88
	v_lshl_add_u64 v[168:169], v[168:169], 0, s[6:7]
	s_add_u32 s50, s54, 0x10080
	s_nop 1
	ds_read_b128 v[10:13], v171 offset:49152
	ds_read_b128 v[14:17], v171 offset:50176
	ds_read_b128 v[172:175], v171 offset:51200
	ds_read_b128 v[176:179], v171 offset:52224
	ds_read_b128 v[180:183], v171 offset:53248
	ds_read_b128 v[192:195], v171 offset:54272
	ds_read_b128 v[196:199], v171 offset:55296
	ds_read_b128 v[214:217], v171 offset:56320
	global_load_lds_dwordx4 v[168:169], off
	v_lshl_add_u64 v[168:169], v[200:201], 0, s[6:7]
	s_mov_b32 m0, s86
	s_addc_u32 s51, s55, 0
	global_load_lds_dwordx4 v[168:169], off
	v_lshl_add_u64 v[168:169], s[50:51], 0, v[0:1]
	s_mov_b32 m0, s52
	s_nop 0
	global_load_lds_dwordx4 v[168:169], off
	v_lshl_add_u64 v[168:169], s[50:51], 0, v[158:159]
	s_mov_b32 m0, s53
	s_nop 0
	global_load_lds_dwordx4 v[168:169], off
	v_lshl_add_u64 v[168:169], v[210:211], 0, s[6:7]
	s_mov_b32 m0, s79
	s_nop 0
	global_load_lds_dwordx4 v[168:169], off
	v_lshl_add_u64 v[168:169], v[234:235], 0, s[6:7]
	s_mov_b32 m0, s80
	s_nop 0
	global_load_lds_dwordx4 v[168:169], off
	s_waitcnt vmcnt(8)
	s_waitcnt lgkmcnt(0)
	s_barrier

; #define PG8_MMA(ai, bj, At, Bt) do { __builtin_amdgcn_s_setprio(1); _Pragma("unroll") for (int m = 0; m < 4; ++m) _Pragma("unroll") for (int n = 0; n < 2; ++n) _Pragma("unroll") for (int k = 0; k < 2; ++k) \
;         acc[ai][bj][m][n] = __builtin_amdgcn_mfma_f32_16x16x32_bf16(Bt[n][k], At[m][k], acc[ai][bj][m][n], 0, 0, 0); __builtin_amdgcn_s_setprio(0); } while (0)
; #define PG8_WAIT_V(n) asm volatile("s_waitcnt vmcnt(" #n ")" ::: "memory")
; #define PG8_WAIT_L(n) asm volatile("s_waitcnt lgkmcnt(" #n ")" ::: "memory")
; #define PG8_BAR __builtin_amdgcn_s_barrier()
; #define PG8_SCHED __builtin_amdgcn_sched_barrier(0)
; template <class Epi, bool ALIGN_EPI>
; __device__ __forceinline__ void gemm_phase(LAS unsigned char* lds, const Gemm g, const StaticOrder& S, const Epi& E, const int tid) {
;     ...
;             PG8_WAIT_V(8); PG8_WAIT_L(0); PG8_BAR; PG8_MMA(1, 0, At, B0); PG8_MMA(1, 1, At, B1); PG8_BAR; PG8_SCHED;
	s_waitcnt lgkmcnt(0)
	v_mfma_f32_16x16x32_bf16 v[50:53], v[114:117], v[10:13], v[50:53]
	v_mfma_f32_16x16x32_bf16 v[82:85], v[114:117], v[172:175], v[82:85]
	v_mfma_f32_16x16x32_bf16 v[98:101], v[114:117], v[180:183], v[98:101]
	v_mfma_f32_16x16x32_bf16 v[114:117], v[114:117], v[196:199], v[118:121]
	v_mfma_f32_16x16x32_bf16 v[58:61], v[138:141], v[10:13], v[58:61]
	v_mfma_f32_16x16x32_bf16 v[90:93], v[138:141], v[172:175], v[90:93]
	v_mfma_f32_16x16x32_bf16 v[106:109], v[138:141], v[180:183], v[106:109]
	v_mfma_f32_16x16x32_bf16 v[118:121], v[134:137], v[214:217], v[114:117]
	v_mfma_f32_16x16x32_bf16 v[114:117], v[138:141], v[196:199], v[126:129]
	v_mfma_f32_16x16x32_bf16 v[50:53], v[134:137], v[14:17], v[50:53]
	v_mfma_f32_16x16x32_bf16 v[58:61], v[142:145], v[14:17], v[58:61]
	v_mfma_f32_16x16x32_bf16 v[82:85], v[134:137], v[176:179], v[82:85]
	v_mfma_f32_16x16x32_bf16 v[90:93], v[142:145], v[176:179], v[90:93]
	v_mfma_f32_16x16x32_bf16 v[98:101], v[134:137], v[192:195], v[98:101]
	v_mfma_f32_16x16x32_bf16 v[106:109], v[142:145], v[192:195], v[106:109]
	v_mfma_f32_16x16x32_bf16 v[126:129], v[142:145], v[214:217], v[114:117]
	s_nop 0

; #define PG8_MMA(ai, bj, At, Bt) do { __builtin_amdgcn_s_setprio(1); _Pragma("unroll") for (int m = 0; m < 4; ++m) _Pragma("unroll") for (int n = 0; n < 2; ++n) _Pragma("unroll") for (int k = 0; k < 2; ++k) \
;         acc[ai][bj][m][n] = __builtin_amdgcn_mfma_f32_16x16x32_bf16(Bt[n][k], At[m][k], acc[ai][bj][m][n], 0, 0, 0); __builtin_amdgcn_s_setprio(0); } while (0)
; #define PG8_WAIT_V(n) asm volatile("s_waitcnt vmcnt(" #n ")" ::: "memory")
; #define PG8_WAIT_L(n) asm volatile("s_waitcnt lgkmcnt(" #n ")" ::: "memory")
; #define PG8_BAR __builtin_amdgcn_s_barrier()
; #define PG8_SCHED __builtin_amdgcn_sched_barrier(0)
; template <class Epi, bool ALIGN_EPI>
; __device__ __forceinline__ void gemm_phase(LAS unsigned char* lds, const Gemm g, const StaticOrder& S, const Epi& E, const int tid) {
;     ...
;             PG8_WAIT_V(8); PG8_WAIT_L(0); PG8_BAR; PG8_MMA(1, 0, At, B0); PG8_MMA(1, 1, At, B1); PG8_BAR; PG8_SCHED;
;         }
;         if constexpr (ALIGN_EPI) { if (wr == 0) PG8_BAR; }
	v_mfma_f32_16x16x32_bf16 v[54:57], v[146:149], v[10:13], v[54:57]
	v_mfma_f32_16x16x32_bf16 v[10:13], v[184:187], v[10:13], v[66:69]
	v_mfma_f32_16x16x32_bf16 v[66:69], v[188:191], v[14:17], v[10:13]
	v_mfma_f32_16x16x32_bf16 v[10:13], v[146:149], v[172:175], v[86:89]
	v_mfma_f32_16x16x32_bf16 v[86:89], v[164:167], v[176:179], v[10:13]
	v_mfma_f32_16x16x32_bf16 v[10:13], v[184:187], v[172:175], v[94:97]
	v_mfma_f32_16x16x32_bf16 v[94:97], v[188:191], v[176:179], v[10:13]
	v_mfma_f32_16x16x32_bf16 v[10:13], v[146:149], v[180:183], v[102:105]
	v_mfma_f32_16x16x32_bf16 v[102:105], v[164:167], v[192:195], v[10:13]
	v_mfma_f32_16x16x32_bf16 v[10:13], v[184:187], v[180:183], v[110:113]
	v_mfma_f32_16x16x32_bf16 v[110:113], v[188:191], v[192:195], v[10:13]
	v_mfma_f32_16x16x32_bf16 v[10:13], v[146:149], v[196:199], v[122:125]
	v_mfma_f32_16x16x32_bf16 v[114:117], v[164:167], v[214:217], v[10:13]
	v_mfma_f32_16x16x32_bf16 v[10:13], v[184:187], v[196:199], v[130:133]
	v_mfma_f32_16x16x32_bf16 v[54:57], v[164:167], v[14:17], v[54:57]
	v_mfma_f32_16x16x32_bf16 v[122:125], v[188:191], v[214:217], v[10:13]
	s_nop 0
	s_barrier
	s_andn2_b64 vcc, exec, s[34:35]
	s_cbranch_vccnz .LBB0_719
	s_barrier

; #define LAS __attribute__((address_space(3)))
; template <bool PROMPT, int HALF>
; __device__ __forceinline__ void conv_item(unsigned char* ws, KArgs ka, int ib, int oct, int g, LAS unsigned char* lds, int tid, int lane, int wave) {
;     ...
;     const int xa = 8 * kq - 2 * nn;
;     LAS unsigned char* vl = lds + wave * (33 * 528);
;     { const bf16* Vg = (const bf16*)(ws + WS_VVT) + (size_t)c * T + (PROMPT ? 0 : TP + 4 * g * LS);
;       __syncthreads();
; #pragma unroll 4
;       for (int it = 0; it < 16; ++it) { const int s_ = (it * 64 + lane) * 8; *(LAS u32x4*)(vl + (s_ >> 8) * 528 + (s_ & 255) * 2) = *(const u32x4*)(Vg + s_); }
;       unsigned zz_ = 0u; asm volatile("" : "+v"(zz_));
;       if (lane < 33) *(LAS u32x4*)(vl + 32 * 528 + lane * 16) = (u32x4){zz_, zz_, zz_, zz_}; }
;     constexpr int NB = PROMPT ? 32 : 8, GS = PROMPT ? 16 : 4;
;     const int nbv = PROMPT ? nn : (nn >> 2);
;     LAS unsigned char* vcol = vl + 16 * kq + (PROMPT ? 0 : 8 * (nn & 3)) * 528;
;     const int zrow = PROMPT ? 32 : 32 - 8 * (nn & 3);
;     constexpr int W = (HALF == 2) ? 8 : 4, MO = (HALF == 1) ? 4 : 0;
;     f32x4 acc[2][W][2];
; #pragma unroll
;     for (int r = 0; r < 2; ++r)
; #pragma unroll
;         for (int q = 0; q < W; ++q)
; #pragma unroll
;             for (int gg = 0; gg < 2; ++gg) acc[r][q][gg] = (f32x4){0.f, 0.f, 0.f, 0.f};
;     constexpr int E0 = PROMPT ? -255 : -63, E1 = PROMPT ? -135 : -39, E2 = PROMPT ? 129 : 33, E3 = PROMPT ? 257 : 65;
;     static_assert((E1 - E0) % 8 == 0 && (E2 - E1) % 8 == 0 && (E3 - E2) % 8 == 0, "segments are whole 8-step blocks");
;     constexpr int DA = (HALF == 2) ? 2 : 4;
;     u32x4 rh[DA]; unsigned rl[DA];
;     u32x4 F0[W], F1[W];
.LBB0_728:
	v_add_u32_e32 v4, s23, v7
	v_ashrrev_i32_e32 v5, 31, v4
	v_lshl_add_u64 v[8:9], v[4:5], 1, s[10:11]
	global_load_dwordx4 v[8:11], v[8:9], off
	v_lshrrev_b32_e32 v3, 8, v4
	v_add_u32_e32 v12, 0x200, v4
	v_mad_i32_i24 v3, v3, s58, v2
	v_ashrrev_i32_e32 v13, 31, v12
	s_addk_i32 s23, 0x800
	s_cmpk_eq_i32 s23, 0x2000
	s_waitcnt vmcnt(0)
	ds_write_b128 v3, v[8:11]
	v_lshl_add_u64 v[8:9], v[12:13], 1, s[10:11]
	global_load_dwordx4 v[8:11], v[8:9], off
	v_lshrrev_b32_e32 v3, 8, v12
	v_add_u32_e32 v12, 0x400, v4
	v_mad_i32_i24 v3, v3, s58, v2
	v_ashrrev_i32_e32 v13, 31, v12
	v_add_u32_e32 v4, 0x600, v4
	v_ashrrev_i32_e32 v5, 31, v4
	s_waitcnt vmcnt(0)
	ds_write_b128 v3, v[8:11]
	v_lshl_add_u64 v[8:9], v[12:13], 1, s[10:11]
	global_load_dwordx4 v[8:11], v[8:9], off
	v_lshrrev_b32_e32 v3, 8, v12
	v_mad_i32_i24 v3, v3, s58, v2
	s_waitcnt vmcnt(0)
	ds_write_b128 v3, v[8:11]
	v_lshl_add_u64 v[8:9], v[4:5], 1, s[10:11]
	global_load_dwordx4 v[8:11], v[8:9], off
	v_lshrrev_b32_e32 v3, 8, v4
	v_mad_i32_i24 v3, v3, s58, v2
	s_waitcnt vmcnt(0)
	ds_write_b128 v3, v[8:11]
	s_cbranch_scc0 .LBB0_728
	v_mov_b32_e32 v2, v1
	v_cmp_gt_i32_e32 vcc, 33, v0
	s_and_saveexec_b64 s[10:11], vcc
	v_mov_b32_e32 v3, v2
	v_mov_b32_e32 v4, v2
	v_mov_b32_e32 v5, v2
	v_add_u32_e32 v6, s37, v6
	ds_write_b128 v6, v[2:5] offset:16896
	s_or_b64 exec, exec, s[10:11]
	v_lshrrev_b32_e32 v2, 1, v0
	v_and_b32_e32 v3, 15, v0
	v_lshlrev_b32_e32 v3, 1, v3
	v_and_b32_e32 v2, 56, v2
	v_sub_u32_e32 v215, v2, v3
	v_add_u32_e32 v2, 0xfffff820, v215
	s_add_u32 s10, s19, 0x53a01000
	v_min_i32_e32 v2, 0x7f8, v2
	s_addc_u32 s11, s22, 0
	v_ashrrev_i32_e32 v3, 31, v2
	v_add_u32_e32 v6, 0xfffff840, v215
	v_lshl_add_u64 v[8:9], v[2:3], 1, s[10:11]
	v_min_i32_e32 v10, 0x7f8, v6
	global_load_dwordx4 v[2:5], v[8:9], off
	v_ashrrev_i32_e32 v11, 31, v10
	v_lshl_add_u64 v[14:15], v[10:11], 1, s[10:11]
	global_load_dword v16, v[8:9], off offset:-4
	global_load_dwordx4 v[10:13], v[14:15], off
	v_add_u32_e32 v8, 0xfffff860, v215
	v_min_i32_e32 v8, 0x7f8, v8
	v_ashrrev_i32_e32 v9, 31, v8
	v_mov_b32_e32 v6, v1
	v_lshl_add_u64 v[8:9], v[8:9], 1, s[10:11]
	global_load_dword v20, v[14:15], off offset:-4
	global_load_dwordx4 v[22:25], v[8:9], off
	global_load_dword v46, v[8:9], off offset:-4
	v_and_b32_e32 v7, 24, v7
	v_and_b32_e32 v8, 0x70, v0
	v_bfe_u32 v216, v0, 2, 2
	v_mul_u32_u24_e32 v0, 0x210, v7
	v_sub_u32_e32 v214, 32, v7
	v_or_b32_e32 v217, 4, v216
	v_add3_u32 v0, s37, v8, v0
	v_mov_b32_e32 v7, v6
	v_mov_b32_e32 v8, v6
	v_mov_b32_e32 v9, v6
	s_waitcnt vmcnt(5)
	v_perm_b32 v15, v2, v3, s67
	v_perm_b32 v17, v4, v5, s67
	s_waitcnt vmcnt(4)
	v_perm_b32 v14, v16, v2, s67
	v_perm_b32 v16, v3, v4, s67

	v_add_u32_e32 v18, -3, v216
	v_cmp_gt_u32_e32 vcc, 8, v18
	v_mfma_f32_16x16x32_bf16 v[26:29], v[14:17], v[6:9], 0
	s_nop 0
	v_cndmask_b32_e32 v14, v214, v18, vcc
	v_mad_i32_i24 v102, v14, s58, v0
	ds_read_b128 v[14:17], v102 offset:64
	v_mfma_f32_16x16x32_bf16 v[2:5], v[2:5], v[6:9], 0

	v_add_u32_e32 v18, 0xfffff880, v215
	v_min_i32_e32 v18, 0x7f8, v18
	v_ashrrev_i32_e32 v19, 31, v18
	v_lshl_add_u64 v[18:19], v[18:19], 1, s[10:11]
	global_load_dwordx4 v[30:33], v[18:19], off
	global_load_dword v58, v[18:19], off offset:-4
	s_waitcnt vmcnt(4)
	v_perm_b32 v34, v20, v10, s67
	v_perm_b32 v35, v10, v11, s67
	v_perm_b32 v36, v11, v12, s67
	v_perm_b32 v37, v12, v13, s67
	s_nop 0
	ds_read_b128 v[18:21], v102 offset:128
	v_mfma_f32_16x16x32_bf16 v[38:41], v[34:37], v[6:9], v[26:29]
	v_mfma_f32_16x16x32_bf16 v[42:45], v[10:13], v[6:9], v[2:5]
	s_waitcnt lgkmcnt(1)
	v_mfma_f32_16x16x32_bf16 v[2:5], v[10:13], v[14:17], v[2:5]
	v_mfma_f32_16x16x32_bf16 v[10:13], v[34:37], v[14:17], v[26:29]
	s_nop 0
	s_nop 1
	v_add_u32_e32 v26, 0xfffff8a0, v215
	v_min_i32_e32 v26, 0x7f8, v26
	v_ashrrev_i32_e32 v27, 31, v26
	v_lshl_add_u64 v[26:27], v[26:27], 1, s[10:11]
	global_load_dwordx4 v[34:37], v[26:27], off
	global_load_dword v70, v[26:27], off offset:-4
	s_waitcnt vmcnt(4)
	v_perm_b32 v26, v46, v22, s67
	v_perm_b32 v27, v22, v23, s67
	v_perm_b32 v28, v23, v24, s67
	v_perm_b32 v29, v24, v25, s67

	v_mfma_f32_16x16x32_bf16 v[50:53], v[22:25], v[6:9], v[42:45]
	v_mfma_f32_16x16x32_bf16 v[42:45], v[22:25], v[14:17], v[42:45]
	s_waitcnt lgkmcnt(0)
	v_mfma_f32_16x16x32_bf16 v[2:5], v[22:25], v[18:21], v[2:5]
	ds_read_b128 v[22:25], v102 offset:192
	v_mfma_f32_16x16x32_bf16 v[46:49], v[26:29], v[6:9], v[38:41]
	v_mfma_f32_16x16x32_bf16 v[38:41], v[26:29], v[14:17], v[38:41]
	v_mfma_f32_16x16x32_bf16 v[10:13], v[26:29], v[18:21], v[10:13]

	v_add_u32_e32 v26, 0xfffff8c0, v215
	v_min_i32_e32 v26, 0x7f8, v26
	v_ashrrev_i32_e32 v27, 31, v26
	v_lshl_add_u64 v[26:27], v[26:27], 1, s[10:11]
	global_load_dwordx4 v[54:57], v[26:27], off
	global_load_dword v82, v[26:27], off offset:-4
	s_waitcnt vmcnt(4)
	v_perm_b32 v58, v58, v30, s67
	v_perm_b32 v59, v30, v31, s67
	v_perm_b32 v60, v31, v32, s67
	v_perm_b32 v61, v32, v33, s67
	s_nop 0
	ds_read_b128 v[26:29], v102 offset:256
	v_mfma_f32_16x16x32_bf16 v[62:65], v[58:61], v[6:9], v[46:49]
	v_mfma_f32_16x16x32_bf16 v[66:69], v[30:33], v[6:9], v[50:53]
	v_mfma_f32_16x16x32_bf16 v[50:53], v[30:33], v[14:17], v[50:53]
	v_mfma_f32_16x16x32_bf16 v[46:49], v[58:61], v[14:17], v[46:49]
	v_mfma_f32_16x16x32_bf16 v[42:45], v[30:33], v[18:21], v[42:45]
	v_mfma_f32_16x16x32_bf16 v[38:41], v[58:61], v[18:21], v[38:41]
	s_waitcnt lgkmcnt(1)
	v_mfma_f32_16x16x32_bf16 v[2:5], v[30:33], v[22:25], v[2:5]
	v_mfma_f32_16x16x32_bf16 v[10:13], v[58:61], v[22:25], v[10:13]

	v_add_u32_e32 v30, 0xfffff8e0, v215
	v_min_i32_e32 v30, 0x7f8, v30
	v_ashrrev_i32_e32 v31, 31, v30
	v_lshl_add_u64 v[30:31], v[30:31], 1, s[10:11]
	global_load_dwordx4 v[58:61], v[30:31], off
	global_load_dword v94, v[30:31], off offset:-4
	s_waitcnt vmcnt(4)
	v_perm_b32 v30, v70, v34, s67
	v_perm_b32 v31, v34, v35, s67
	v_perm_b32 v32, v35, v36, s67
	v_perm_b32 v33, v36, v37, s67

	v_mfma_f32_16x16x32_bf16 v[74:77], v[34:37], v[6:9], v[66:69]
	v_mfma_f32_16x16x32_bf16 v[66:69], v[34:37], v[14:17], v[66:69]
	v_mfma_f32_16x16x32_bf16 v[50:53], v[34:37], v[18:21], v[50:53]
	v_mfma_f32_16x16x32_bf16 v[42:45], v[34:37], v[22:25], v[42:45]
	s_waitcnt lgkmcnt(0)
	v_mfma_f32_16x16x32_bf16 v[2:5], v[34:37], v[26:29], v[2:5]
	ds_read_b128 v[34:37], v102 offset:320
	v_mfma_f32_16x16x32_bf16 v[70:73], v[30:33], v[6:9], v[62:65]
	v_mfma_f32_16x16x32_bf16 v[62:65], v[30:33], v[14:17], v[62:65]
	v_mfma_f32_16x16x32_bf16 v[46:49], v[30:33], v[18:21], v[46:49]
	v_mfma_f32_16x16x32_bf16 v[38:41], v[30:33], v[22:25], v[38:41]
	v_mfma_f32_16x16x32_bf16 v[10:13], v[30:33], v[26:29], v[10:13]

	v_add_u32_e32 v30, 0xfffff900, v215
	v_min_i32_e32 v30, 0x7f8, v30
	v_ashrrev_i32_e32 v31, 31, v30
	v_lshl_add_u64 v[30:31], v[30:31], 1, s[10:11]
	global_load_dwordx4 v[78:81], v[30:31], off
	global_load_dword v104, v[30:31], off offset:-4
	s_waitcnt vmcnt(4)
	v_perm_b32 v82, v82, v54, s67
	v_perm_b32 v83, v54, v55, s67
	v_perm_b32 v84, v55, v56, s67
	v_perm_b32 v85, v56, v57, s67
	s_nop 0
	ds_read_b128 v[30:33], v102 offset:384
	v_mfma_f32_16x16x32_bf16 v[86:89], v[82:85], v[6:9], v[70:73]
	v_mfma_f32_16x16x32_bf16 v[90:93], v[54:57], v[6:9], v[74:77]
	v_mfma_f32_16x16x32_bf16 v[74:77], v[54:57], v[14:17], v[74:77]
	v_mfma_f32_16x16x32_bf16 v[70:73], v[82:85], v[14:17], v[70:73]
	v_mfma_f32_16x16x32_bf16 v[66:69], v[54:57], v[18:21], v[66:69]
	v_mfma_f32_16x16x32_bf16 v[62:65], v[82:85], v[18:21], v[62:65]
	v_mfma_f32_16x16x32_bf16 v[50:53], v[54:57], v[22:25], v[50:53]
	v_mfma_f32_16x16x32_bf16 v[46:49], v[82:85], v[22:25], v[46:49]
	v_mfma_f32_16x16x32_bf16 v[42:45], v[54:57], v[26:29], v[42:45]
	v_mfma_f32_16x16x32_bf16 v[38:41], v[82:85], v[26:29], v[38:41]
	s_waitcnt lgkmcnt(1)
	v_mfma_f32_16x16x32_bf16 v[2:5], v[54:57], v[34:37], v[2:5]
	v_mfma_f32_16x16x32_bf16 v[10:13], v[82:85], v[34:37], v[10:13]

	v_add_u32_e32 v54, 0xfffff920, v215
	v_min_i32_e32 v54, 0x7f8, v54
	v_ashrrev_i32_e32 v55, 31, v54
	v_lshl_add_u64 v[82:83], v[54:55], 1, s[10:11]
	global_load_dwordx4 v[54:57], v[82:83], off
	global_load_dword v118, v[82:83], off offset:-4
	s_waitcnt vmcnt(4)
	v_perm_b32 v82, v94, v58, s67
	v_perm_b32 v83, v58, v59, s67
	v_perm_b32 v84, v59, v60, s67
	v_perm_b32 v85, v60, v61, s67

	v_mfma_f32_16x16x32_bf16 v[98:101], v[58:61], v[6:9], v[90:93]
	v_mfma_f32_16x16x32_bf16 v[90:93], v[58:61], v[14:17], v[90:93]
	v_mfma_f32_16x16x32_bf16 v[74:77], v[58:61], v[18:21], v[74:77]
	v_mfma_f32_16x16x32_bf16 v[66:69], v[58:61], v[22:25], v[66:69]
	v_mfma_f32_16x16x32_bf16 v[50:53], v[58:61], v[26:29], v[50:53]
	v_mfma_f32_16x16x32_bf16 v[42:45], v[58:61], v[34:37], v[42:45]
	s_waitcnt lgkmcnt(0)
	v_mfma_f32_16x16x32_bf16 v[58:61], v[58:61], v[30:33], v[2:5]
	s_nop 2
	ds_read_b128 v[2:5], v102 offset:448
	v_mfma_f32_16x16x32_bf16 v[94:97], v[82:85], v[6:9], v[86:89]
	v_mfma_f32_16x16x32_bf16 v[86:89], v[82:85], v[14:17], v[86:89]
	v_mfma_f32_16x16x32_bf16 v[70:73], v[82:85], v[18:21], v[70:73]
	v_mfma_f32_16x16x32_bf16 v[62:65], v[82:85], v[22:25], v[62:65]
	v_mfma_f32_16x16x32_bf16 v[46:49], v[82:85], v[26:29], v[46:49]
	v_mfma_f32_16x16x32_bf16 v[38:41], v[82:85], v[34:37], v[38:41]
	v_mfma_f32_16x16x32_bf16 v[10:13], v[82:85], v[30:33], v[10:13]

	v_add_u32_e32 v82, 0xfffff940, v215
	v_min_i32_e32 v82, 0x7f8, v82
	v_ashrrev_i32_e32 v83, 31, v82
	v_lshl_add_u64 v[102:103], v[82:83], 1, s[10:11]
	global_load_dwordx4 v[82:85], v[102:103], off
	global_load_dword v120, v[102:103], off offset:-4
	s_waitcnt vmcnt(4)
	v_perm_b32 v102, v104, v78, s67
	v_perm_b32 v103, v78, v79, s67
	v_perm_b32 v104, v79, v80, s67
	v_perm_b32 v105, v80, v81, s67
	s_nop 1

	v_mfma_f32_16x16x32_bf16 v[114:117], v[102:105], v[30:33], v[38:41]
	s_nop 2
	v_add_u32_e32 v38, -2, v216
	v_cmp_gt_u32_e32 vcc, 8, v38
	v_mfma_f32_16x16x32_bf16 v[106:109], v[102:105], v[6:9], v[94:97]
	s_nop 0
	v_cndmask_b32_e32 v38, v214, v38, vcc
	v_mad_i32_i24 v122, v38, s58, v0
	ds_read_b128 v[38:41], v122
	v_mfma_f32_16x16x32_bf16 v[110:113], v[78:81], v[14:17], v[98:101]
	v_mfma_f32_16x16x32_bf16 v[94:97], v[102:105], v[14:17], v[94:97]
	v_mfma_f32_16x16x32_bf16 v[90:93], v[78:81], v[18:21], v[90:93]
	v_mfma_f32_16x16x32_bf16 v[86:89], v[102:105], v[18:21], v[86:89]
	v_mfma_f32_16x16x32_bf16 v[74:77], v[78:81], v[22:25], v[74:77]
	v_mfma_f32_16x16x32_bf16 v[70:73], v[102:105], v[22:25], v[70:73]
	v_mfma_f32_16x16x32_bf16 v[66:69], v[78:81], v[26:29], v[66:69]
	v_mfma_f32_16x16x32_bf16 v[62:65], v[102:105], v[26:29], v[62:65]
	v_mfma_f32_16x16x32_bf16 v[50:53], v[78:81], v[34:37], v[50:53]
	v_mfma_f32_16x16x32_bf16 v[46:49], v[102:105], v[34:37], v[46:49]
	v_mfma_f32_16x16x32_bf16 v[42:45], v[78:81], v[30:33], v[42:45]
	s_waitcnt lgkmcnt(1)
	v_mfma_f32_16x16x32_bf16 v[58:61], v[78:81], v[2:5], v[58:61]
	v_mfma_f32_16x16x32_bf16 v[10:13], v[102:105], v[2:5], v[10:13]
	v_mfma_f32_16x16x32_bf16 v[78:81], v[78:81], v[6:9], v[98:101]

	v_add_u32_e32 v6, 0xfffff960, v215
	v_min_i32_e32 v6, 0x7f8, v6
	v_ashrrev_i32_e32 v7, 31, v6
	v_lshl_add_u64 v[6:7], v[6:7], 1, s[10:11]
	global_load_dwordx4 v[98:101], v[6:7], off
	global_load_dword v123, v[6:7], off offset:-4
	s_waitcnt vmcnt(4)
	v_perm_b32 v102, v118, v54, s67
	v_perm_b32 v103, v54, v55, s67
	v_perm_b32 v104, v55, v56, s67
	v_perm_b32 v105, v56, v57, s67
	s_nop 0
	ds_read_b128 v[6:9], v122 offset:64
	v_mfma_f32_16x16x32_bf16 v[106:109], v[102:105], v[14:17], v[106:109]
	v_mfma_f32_16x16x32_bf16 v[110:113], v[54:57], v[18:21], v[110:113]
	v_mfma_f32_16x16x32_bf16 v[94:97], v[102:105], v[18:21], v[94:97]
	v_mfma_f32_16x16x32_bf16 v[90:93], v[54:57], v[22:25], v[90:93]
	v_mfma_f32_16x16x32_bf16 v[86:89], v[102:105], v[22:25], v[86:89]
	v_mfma_f32_16x16x32_bf16 v[74:77], v[54:57], v[26:29], v[74:77]
	v_mfma_f32_16x16x32_bf16 v[70:73], v[102:105], v[26:29], v[70:73]
	v_mfma_f32_16x16x32_bf16 v[66:69], v[54:57], v[34:37], v[66:69]
	v_mfma_f32_16x16x32_bf16 v[62:65], v[102:105], v[34:37], v[62:65]
	v_mfma_f32_16x16x32_bf16 v[50:53], v[54:57], v[30:33], v[50:53]
	v_mfma_f32_16x16x32_bf16 v[46:49], v[102:105], v[30:33], v[46:49]
	v_mfma_f32_16x16x32_bf16 v[42:45], v[54:57], v[2:5], v[42:45]
	v_mfma_f32_16x16x32_bf16 v[114:117], v[102:105], v[2:5], v[114:117]
	s_waitcnt lgkmcnt(1)
	v_mfma_f32_16x16x32_bf16 v[58:61], v[54:57], v[38:41], v[58:61]
	v_mfma_f32_16x16x32_bf16 v[10:13], v[102:105], v[38:41], v[10:13]

	v_add_u32_e32 v102, 0xfffff980, v215
	v_min_i32_e32 v102, 0x7f8, v102
	v_ashrrev_i32_e32 v103, 31, v102
	v_lshl_add_u64 v[118:119], v[102:103], 1, s[10:11]
	global_load_dwordx4 v[102:105], v[118:119], off
	global_load_dword v124, v[118:119], off offset:-4
	s_waitcnt vmcnt(4)
	v_perm_b32 v118, v120, v82, s67
	v_perm_b32 v119, v82, v83, s67
	v_perm_b32 v120, v83, v84, s67
	v_perm_b32 v121, v84, v85, s67
	s_nop 1

	v_mfma_f32_16x16x32_bf16 v[106:109], v[118:121], v[18:21], v[106:109]
	v_mfma_f32_16x16x32_bf16 v[94:97], v[118:121], v[22:25], v[94:97]
	v_mfma_f32_16x16x32_bf16 v[86:89], v[118:121], v[26:29], v[86:89]
	v_mfma_f32_16x16x32_bf16 v[70:73], v[118:121], v[34:37], v[70:73]
	v_mfma_f32_16x16x32_bf16 v[62:65], v[118:121], v[30:33], v[62:65]
	v_mfma_f32_16x16x32_bf16 v[46:49], v[118:121], v[2:5], v[46:49]
	v_mfma_f32_16x16x32_bf16 v[114:117], v[118:121], v[38:41], v[114:117]
	s_waitcnt lgkmcnt(0)
	v_mfma_f32_16x16x32_bf16 v[118:121], v[118:121], v[6:9], v[10:13]
	s_nop 2
	ds_read_b128 v[10:13], v122 offset:128
	v_mfma_f32_16x16x32_bf16 v[110:113], v[82:85], v[22:25], v[110:113]
	v_mfma_f32_16x16x32_bf16 v[90:93], v[82:85], v[26:29], v[90:93]
	v_mfma_f32_16x16x32_bf16 v[74:77], v[82:85], v[34:37], v[74:77]
	v_mfma_f32_16x16x32_bf16 v[66:69], v[82:85], v[30:33], v[66:69]
	v_mfma_f32_16x16x32_bf16 v[50:53], v[82:85], v[2:5], v[50:53]
	v_mfma_f32_16x16x32_bf16 v[42:45], v[82:85], v[38:41], v[42:45]
	v_mfma_f32_16x16x32_bf16 v[58:61], v[82:85], v[6:9], v[58:61]
	v_mfma_f32_16x16x32_bf16 v[54:57], v[54:57], v[14:17], v[78:81]

	v_add_u32_e32 v14, 0xfffff9a0, v215
	v_min_i32_e32 v14, 0x7f8, v14
	v_ashrrev_i32_e32 v15, 31, v14
	v_lshl_add_u64 v[14:15], v[14:15], 1, s[10:11]
	global_load_dwordx4 v[78:81], v[14:15], off
	global_load_dword v125, v[14:15], off offset:-4
	s_waitcnt vmcnt(4)
	v_perm_b32 v14, v123, v98, s67
	v_perm_b32 v15, v98, v99, s67
	v_perm_b32 v16, v99, v100, s67
	v_perm_b32 v17, v100, v101, s67
	s_nop 1

	v_mfma_f32_16x16x32_bf16 v[106:109], v[14:17], v[22:25], v[106:109]
	v_mfma_f32_16x16x32_bf16 v[94:97], v[14:17], v[26:29], v[94:97]
	v_mfma_f32_16x16x32_bf16 v[86:89], v[14:17], v[34:37], v[86:89]
	v_mfma_f32_16x16x32_bf16 v[70:73], v[14:17], v[30:33], v[70:73]
	v_mfma_f32_16x16x32_bf16 v[62:65], v[14:17], v[2:5], v[62:65]
	v_mfma_f32_16x16x32_bf16 v[46:49], v[14:17], v[38:41], v[46:49]
	v_mfma_f32_16x16x32_bf16 v[114:117], v[14:17], v[6:9], v[114:117]
	s_waitcnt lgkmcnt(0)
	v_mfma_f32_16x16x32_bf16 v[118:121], v[14:17], v[10:13], v[118:121]
	ds_read_b128 v[14:17], v122 offset:192
	v_mfma_f32_16x16x32_bf16 v[110:113], v[98:101], v[26:29], v[110:113]
	v_mfma_f32_16x16x32_bf16 v[90:93], v[98:101], v[34:37], v[90:93]
	v_mfma_f32_16x16x32_bf16 v[74:77], v[98:101], v[30:33], v[74:77]
	v_mfma_f32_16x16x32_bf16 v[66:69], v[98:101], v[2:5], v[66:69]
	v_mfma_f32_16x16x32_bf16 v[50:53], v[98:101], v[38:41], v[50:53]
	v_mfma_f32_16x16x32_bf16 v[42:45], v[98:101], v[6:9], v[42:45]
	v_mfma_f32_16x16x32_bf16 v[58:61], v[98:101], v[10:13], v[58:61]
	v_mfma_f32_16x16x32_bf16 v[54:57], v[82:85], v[18:21], v[54:57]

	v_add_u32_e32 v18, 0xfffff9c0, v215
	v_min_i32_e32 v18, 0x7f8, v18
	v_ashrrev_i32_e32 v19, 31, v18
	v_lshl_add_u64 v[18:19], v[18:19], 1, s[10:11]
	global_load_dwordx4 v[82:85], v[18:19], off
	global_load_dword v123, v[18:19], off offset:-4
	s_waitcnt vmcnt(4)
	v_perm_b32 v18, v124, v102, s67
	v_perm_b32 v19, v102, v103, s67
	v_perm_b32 v20, v103, v104, s67
	v_perm_b32 v21, v104, v105, s67
	s_nop 1

	v_mfma_f32_16x16x32_bf16 v[106:109], v[18:21], v[26:29], v[106:109]
	v_mfma_f32_16x16x32_bf16 v[94:97], v[18:21], v[34:37], v[94:97]
	v_mfma_f32_16x16x32_bf16 v[86:89], v[18:21], v[30:33], v[86:89]
	v_mfma_f32_16x16x32_bf16 v[70:73], v[18:21], v[2:5], v[70:73]
	v_mfma_f32_16x16x32_bf16 v[62:65], v[18:21], v[38:41], v[62:65]
	v_mfma_f32_16x16x32_bf16 v[46:49], v[18:21], v[6:9], v[46:49]
	v_mfma_f32_16x16x32_bf16 v[114:117], v[18:21], v[10:13], v[114:117]
	s_waitcnt lgkmcnt(0)
	v_mfma_f32_16x16x32_bf16 v[118:121], v[18:21], v[14:17], v[118:121]
	ds_read_b128 v[18:21], v122 offset:256
	v_mfma_f32_16x16x32_bf16 v[110:113], v[102:105], v[34:37], v[110:113]
	v_mfma_f32_16x16x32_bf16 v[90:93], v[102:105], v[30:33], v[90:93]
	v_mfma_f32_16x16x32_bf16 v[74:77], v[102:105], v[2:5], v[74:77]
	v_mfma_f32_16x16x32_bf16 v[66:69], v[102:105], v[38:41], v[66:69]
	v_mfma_f32_16x16x32_bf16 v[50:53], v[102:105], v[6:9], v[50:53]
	v_mfma_f32_16x16x32_bf16 v[42:45], v[102:105], v[10:13], v[42:45]
	v_mfma_f32_16x16x32_bf16 v[58:61], v[102:105], v[14:17], v[58:61]
	v_mfma_f32_16x16x32_bf16 v[54:57], v[98:101], v[22:25], v[54:57]

	v_add_u32_e32 v22, 0xfffff9e0, v215
	v_min_i32_e32 v22, 0x7f8, v22
	v_ashrrev_i32_e32 v23, 31, v22
	v_lshl_add_u64 v[22:23], v[22:23], 1, s[10:11]
	global_load_dwordx4 v[98:101], v[22:23], off
	global_load_dword v124, v[22:23], off offset:-4
	s_waitcnt vmcnt(4)
	v_perm_b32 v22, v125, v78, s67
	v_perm_b32 v23, v78, v79, s67
	v_perm_b32 v24, v79, v80, s67
	v_perm_b32 v25, v80, v81, s67
	s_nop 1

	v_mfma_f32_16x16x32_bf16 v[106:109], v[22:25], v[34:37], v[106:109]
	v_mfma_f32_16x16x32_bf16 v[94:97], v[22:25], v[30:33], v[94:97]
	v_mfma_f32_16x16x32_bf16 v[86:89], v[22:25], v[2:5], v[86:89]
	v_mfma_f32_16x16x32_bf16 v[70:73], v[22:25], v[38:41], v[70:73]
	v_mfma_f32_16x16x32_bf16 v[62:65], v[22:25], v[6:9], v[62:65]
	v_mfma_f32_16x16x32_bf16 v[46:49], v[22:25], v[10:13], v[46:49]
	v_mfma_f32_16x16x32_bf16 v[114:117], v[22:25], v[14:17], v[114:117]
	s_waitcnt lgkmcnt(0)
	v_mfma_f32_16x16x32_bf16 v[118:121], v[22:25], v[18:21], v[118:121]
	ds_read_b128 v[22:25], v122 offset:320
	v_mfma_f32_16x16x32_bf16 v[110:113], v[78:81], v[30:33], v[110:113]
	v_mfma_f32_16x16x32_bf16 v[90:93], v[78:81], v[2:5], v[90:93]
	v_mfma_f32_16x16x32_bf16 v[74:77], v[78:81], v[38:41], v[74:77]
	v_mfma_f32_16x16x32_bf16 v[66:69], v[78:81], v[6:9], v[66:69]
	v_mfma_f32_16x16x32_bf16 v[50:53], v[78:81], v[10:13], v[50:53]
	v_mfma_f32_16x16x32_bf16 v[42:45], v[78:81], v[14:17], v[42:45]
	v_mfma_f32_16x16x32_bf16 v[58:61], v[78:81], v[18:21], v[58:61]
	v_mfma_f32_16x16x32_bf16 v[54:57], v[102:105], v[26:29], v[54:57]

	v_add_u32_e32 v26, 0xfffffa00, v215
	v_min_i32_e32 v26, 0x7f8, v26
	v_ashrrev_i32_e32 v27, 31, v26
	v_lshl_add_u64 v[26:27], v[26:27], 1, s[10:11]
	global_load_dwordx4 v[102:105], v[26:27], off
	global_load_dword v125, v[26:27], off offset:-4
	s_waitcnt vmcnt(4)
	v_perm_b32 v26, v123, v82, s67
	v_perm_b32 v27, v82, v83, s67
	v_perm_b32 v28, v83, v84, s67
	v_perm_b32 v29, v84, v85, s67
	s_nop 1

	v_mfma_f32_16x16x32_bf16 v[106:109], v[26:29], v[30:33], v[106:109]
	v_mfma_f32_16x16x32_bf16 v[94:97], v[26:29], v[2:5], v[94:97]
	v_mfma_f32_16x16x32_bf16 v[86:89], v[26:29], v[38:41], v[86:89]
	v_mfma_f32_16x16x32_bf16 v[70:73], v[26:29], v[6:9], v[70:73]
	v_mfma_f32_16x16x32_bf16 v[62:65], v[26:29], v[10:13], v[62:65]
	v_mfma_f32_16x16x32_bf16 v[46:49], v[26:29], v[14:17], v[46:49]
	v_mfma_f32_16x16x32_bf16 v[114:117], v[26:29], v[18:21], v[114:117]
	s_waitcnt lgkmcnt(0)
	v_mfma_f32_16x16x32_bf16 v[118:121], v[26:29], v[22:25], v[118:121]
	ds_read_b128 v[26:29], v122 offset:384
	v_mfma_f32_16x16x32_bf16 v[110:113], v[82:85], v[2:5], v[110:113]
	v_mfma_f32_16x16x32_bf16 v[90:93], v[82:85], v[38:41], v[90:93]
	v_mfma_f32_16x16x32_bf16 v[74:77], v[82:85], v[6:9], v[74:77]
	v_mfma_f32_16x16x32_bf16 v[66:69], v[82:85], v[10:13], v[66:69]
	v_mfma_f32_16x16x32_bf16 v[50:53], v[82:85], v[14:17], v[50:53]
	v_mfma_f32_16x16x32_bf16 v[42:45], v[82:85], v[18:21], v[42:45]
	v_mfma_f32_16x16x32_bf16 v[58:61], v[82:85], v[22:25], v[58:61]
	v_mfma_f32_16x16x32_bf16 v[54:57], v[78:81], v[34:37], v[54:57]

	v_add_u32_e32 v34, 0xfffffa20, v215
	v_min_i32_e32 v34, 0x7f8, v34
	v_ashrrev_i32_e32 v35, 31, v34
	v_lshl_add_u64 v[34:35], v[34:35], 1, s[10:11]
	global_load_dwordx4 v[78:81], v[34:35], off
	global_load_dword v126, v[34:35], off offset:-4
	s_waitcnt vmcnt(4)
	v_perm_b32 v34, v124, v98, s67
	v_perm_b32 v35, v98, v99, s67
	v_perm_b32 v36, v99, v100, s67
	v_perm_b32 v37, v100, v101, s67
	s_nop 1

	v_mfma_f32_16x16x32_bf16 v[106:109], v[34:37], v[2:5], v[106:109]
	v_mfma_f32_16x16x32_bf16 v[94:97], v[34:37], v[38:41], v[94:97]
	v_mfma_f32_16x16x32_bf16 v[86:89], v[34:37], v[6:9], v[86:89]
	v_mfma_f32_16x16x32_bf16 v[70:73], v[34:37], v[10:13], v[70:73]
	v_mfma_f32_16x16x32_bf16 v[62:65], v[34:37], v[14:17], v[62:65]
	v_mfma_f32_16x16x32_bf16 v[46:49], v[34:37], v[18:21], v[46:49]
	v_mfma_f32_16x16x32_bf16 v[114:117], v[34:37], v[22:25], v[114:117]
	s_waitcnt lgkmcnt(0)
	v_mfma_f32_16x16x32_bf16 v[118:121], v[34:37], v[26:29], v[118:121]
	ds_read_b128 v[34:37], v122 offset:448
	v_mfma_f32_16x16x32_bf16 v[110:113], v[98:101], v[38:41], v[110:113]
	v_mfma_f32_16x16x32_bf16 v[90:93], v[98:101], v[6:9], v[90:93]
	v_mfma_f32_16x16x32_bf16 v[74:77], v[98:101], v[10:13], v[74:77]
	v_mfma_f32_16x16x32_bf16 v[66:69], v[98:101], v[14:17], v[66:69]
	v_mfma_f32_16x16x32_bf16 v[50:53], v[98:101], v[18:21], v[50:53]
	v_mfma_f32_16x16x32_bf16 v[42:45], v[98:101], v[22:25], v[42:45]
	v_mfma_f32_16x16x32_bf16 v[58:61], v[98:101], v[26:29], v[58:61]
	v_mfma_f32_16x16x32_bf16 v[30:33], v[82:85], v[30:33], v[54:57]
	s_nop 0
	s_nop 1
	v_add_u32_e32 v54, 0xfffffa40, v215
	v_min_i32_e32 v54, 0x7f8, v54
	v_ashrrev_i32_e32 v55, 31, v54
	v_lshl_add_u64 v[82:83], v[54:55], 1, s[10:11]
	global_load_dwordx4 v[54:57], v[82:83], off
	global_load_dword v127, v[82:83], off offset:-4
	s_waitcnt vmcnt(4)
	v_perm_b32 v82, v125, v102, s67
	v_perm_b32 v83, v102, v103, s67
	v_perm_b32 v84, v103, v104, s67
	v_perm_b32 v85, v104, v105, s67

	v_mfma_f32_16x16x32_bf16 v[122:125], v[102:105], v[26:29], v[42:45]
	s_nop 2
	v_add_u32_e32 v42, -1, v216
	v_mfma_f32_16x16x32_bf16 v[2:5], v[98:101], v[2:5], v[30:33]
	v_cmp_gt_u32_e32 vcc, 8, v42
	s_nop 1
	v_cndmask_b32_e32 v30, v214, v42, vcc
	v_mad_i32_i24 v130, v30, s58, v0
	ds_read_b128 v[42:45], v130
	v_mfma_f32_16x16x32_bf16 v[106:109], v[82:85], v[38:41], v[106:109]
	v_mfma_f32_16x16x32_bf16 v[110:113], v[102:105], v[6:9], v[110:113]
	v_mfma_f32_16x16x32_bf16 v[94:97], v[82:85], v[6:9], v[94:97]
	v_mfma_f32_16x16x32_bf16 v[90:93], v[102:105], v[10:13], v[90:93]
	v_mfma_f32_16x16x32_bf16 v[86:89], v[82:85], v[10:13], v[86:89]
	v_mfma_f32_16x16x32_bf16 v[74:77], v[102:105], v[14:17], v[74:77]
	v_mfma_f32_16x16x32_bf16 v[70:73], v[82:85], v[14:17], v[70:73]
	v_mfma_f32_16x16x32_bf16 v[66:69], v[102:105], v[18:21], v[66:69]
	v_mfma_f32_16x16x32_bf16 v[62:65], v[82:85], v[18:21], v[62:65]
	v_mfma_f32_16x16x32_bf16 v[50:53], v[102:105], v[22:25], v[50:53]
	v_mfma_f32_16x16x32_bf16 v[46:49], v[82:85], v[22:25], v[46:49]
	v_mfma_f32_16x16x32_bf16 v[114:117], v[82:85], v[26:29], v[114:117]
	s_waitcnt lgkmcnt(1)
	v_mfma_f32_16x16x32_bf16 v[58:61], v[102:105], v[34:37], v[58:61]
	v_mfma_f32_16x16x32_bf16 v[82:85], v[82:85], v[34:37], v[118:121]
	v_mfma_f32_16x16x32_bf16 v[2:5], v[102:105], v[38:41], v[2:5]

	v_add_u32_e32 v30, 0xfffffa60, v215
	v_min_i32_e32 v30, 0x7f8, v30
	v_ashrrev_i32_e32 v31, 31, v30
	v_lshl_add_u64 v[38:39], v[30:31], 1, s[10:11]
	global_load_dwordx4 v[30:33], v[38:39], off
	global_load_dword v128, v[38:39], off offset:-4
	s_waitcnt vmcnt(4)
	v_perm_b32 v38, v126, v78, s67
	v_perm_b32 v39, v78, v79, s67
	v_perm_b32 v40, v79, v80, s67
	v_perm_b32 v41, v80, v81, s67
	s_nop 1

	v_mfma_f32_16x16x32_bf16 v[98:101], v[38:41], v[6:9], v[106:109]
	v_mfma_f32_16x16x32_bf16 v[106:109], v[78:81], v[18:21], v[74:77]
	s_nop 2
	ds_read_b128 v[74:77], v130 offset:64
	v_mfma_f32_16x16x32_bf16 v[102:105], v[78:81], v[10:13], v[110:113]
	v_mfma_f32_16x16x32_bf16 v[94:97], v[38:41], v[10:13], v[94:97]
	v_mfma_f32_16x16x32_bf16 v[90:93], v[78:81], v[14:17], v[90:93]
	v_mfma_f32_16x16x32_bf16 v[86:89], v[38:41], v[14:17], v[86:89]
	v_mfma_f32_16x16x32_bf16 v[70:73], v[38:41], v[18:21], v[70:73]
	v_mfma_f32_16x16x32_bf16 v[66:69], v[78:81], v[22:25], v[66:69]
	v_mfma_f32_16x16x32_bf16 v[62:65], v[38:41], v[22:25], v[62:65]
	v_mfma_f32_16x16x32_bf16 v[50:53], v[78:81], v[26:29], v[50:53]
	v_mfma_f32_16x16x32_bf16 v[46:49], v[38:41], v[26:29], v[46:49]
	v_mfma_f32_16x16x32_bf16 v[110:113], v[78:81], v[34:37], v[122:125]
	v_mfma_f32_16x16x32_bf16 v[114:117], v[38:41], v[34:37], v[114:117]
	s_waitcnt lgkmcnt(1)
	v_mfma_f32_16x16x32_bf16 v[58:61], v[78:81], v[42:45], v[58:61]
	v_mfma_f32_16x16x32_bf16 v[38:41], v[38:41], v[42:45], v[82:85]
	s_nop 0
	s_nop 1
	v_add_u32_e32 v82, 0xfffffa80, v215
	v_min_i32_e32 v82, 0x7f8, v82
	v_ashrrev_i32_e32 v83, 31, v82
	v_lshl_add_u64 v[82:83], v[82:83], 1, s[10:11]
	global_load_dwordx4 v[118:121], v[82:83], off
	global_load_dword v126, v[82:83], off offset:-4
	s_waitcnt vmcnt(4)
	v_perm_b32 v82, v127, v54, s67
	v_perm_b32 v83, v54, v55, s67
	v_perm_b32 v84, v55, v56, s67
	v_perm_b32 v85, v56, v57, s67
	s_nop 1

	v_mfma_f32_16x16x32_bf16 v[98:101], v[82:85], v[10:13], v[98:101]
	v_mfma_f32_16x16x32_bf16 v[94:97], v[82:85], v[14:17], v[94:97]
	v_mfma_f32_16x16x32_bf16 v[86:89], v[82:85], v[18:21], v[86:89]
	v_mfma_f32_16x16x32_bf16 v[70:73], v[82:85], v[22:25], v[70:73]
	v_mfma_f32_16x16x32_bf16 v[62:65], v[82:85], v[26:29], v[62:65]
	v_mfma_f32_16x16x32_bf16 v[46:49], v[82:85], v[34:37], v[46:49]
	v_mfma_f32_16x16x32_bf16 v[114:117], v[82:85], v[42:45], v[114:117]
	s_waitcnt lgkmcnt(0)
	v_mfma_f32_16x16x32_bf16 v[38:41], v[82:85], v[74:77], v[38:41]
	ds_read_b128 v[82:85], v130 offset:128
	v_mfma_f32_16x16x32_bf16 v[102:105], v[54:57], v[14:17], v[102:105]
	v_mfma_f32_16x16x32_bf16 v[90:93], v[54:57], v[18:21], v[90:93]
	v_mfma_f32_16x16x32_bf16 v[106:109], v[54:57], v[22:25], v[106:109]
	v_mfma_f32_16x16x32_bf16 v[66:69], v[54:57], v[26:29], v[66:69]
	v_mfma_f32_16x16x32_bf16 v[50:53], v[54:57], v[34:37], v[50:53]
	v_mfma_f32_16x16x32_bf16 v[110:113], v[54:57], v[42:45], v[110:113]
	v_mfma_f32_16x16x32_bf16 v[58:61], v[54:57], v[74:77], v[58:61]
	v_mfma_f32_16x16x32_bf16 v[2:5], v[78:81], v[6:9], v[2:5]

	v_add_u32_e32 v6, 0xfffffaa0, v215
	v_min_i32_e32 v6, 0x7f8, v6
	v_ashrrev_i32_e32 v7, 31, v6
	v_lshl_add_u64 v[78:79], v[6:7], 1, s[10:11]
	global_load_dwordx4 v[6:9], v[78:79], off
	global_load_dword v127, v[78:79], off offset:-4
	s_waitcnt vmcnt(4)
	v_perm_b32 v78, v128, v30, s67
	v_perm_b32 v79, v30, v31, s67
	v_perm_b32 v80, v31, v32, s67
	v_perm_b32 v81, v32, v33, s67

	v_mfma_f32_16x16x32_bf16 v[122:125], v[30:33], v[22:25], v[90:93]
	s_nop 2
	ds_read_b128 v[90:93], v130 offset:192
	v_mfma_f32_16x16x32_bf16 v[98:101], v[78:81], v[14:17], v[98:101]
	v_mfma_f32_16x16x32_bf16 v[102:105], v[30:33], v[18:21], v[102:105]
	v_mfma_f32_16x16x32_bf16 v[94:97], v[78:81], v[18:21], v[94:97]
	v_mfma_f32_16x16x32_bf16 v[86:89], v[78:81], v[22:25], v[86:89]
	v_mfma_f32_16x16x32_bf16 v[106:109], v[30:33], v[26:29], v[106:109]
	v_mfma_f32_16x16x32_bf16 v[70:73], v[78:81], v[26:29], v[70:73]
	v_mfma_f32_16x16x32_bf16 v[66:69], v[30:33], v[34:37], v[66:69]
	v_mfma_f32_16x16x32_bf16 v[62:65], v[78:81], v[34:37], v[62:65]
	v_mfma_f32_16x16x32_bf16 v[50:53], v[30:33], v[42:45], v[50:53]
	v_mfma_f32_16x16x32_bf16 v[46:49], v[78:81], v[42:45], v[46:49]
	v_mfma_f32_16x16x32_bf16 v[110:113], v[30:33], v[74:77], v[110:113]
	v_mfma_f32_16x16x32_bf16 v[114:117], v[78:81], v[74:77], v[114:117]
	s_waitcnt lgkmcnt(1)
	v_mfma_f32_16x16x32_bf16 v[58:61], v[30:33], v[82:85], v[58:61]
	v_mfma_f32_16x16x32_bf16 v[38:41], v[78:81], v[82:85], v[38:41]
	v_mfma_f32_16x16x32_bf16 v[2:5], v[54:57], v[10:13], v[2:5]

	v_add_u32_e32 v10, 0xfffffac0, v215
	v_min_i32_e32 v10, 0x7f8, v10
	v_ashrrev_i32_e32 v11, 31, v10
	v_lshl_add_u64 v[54:55], v[10:11], 1, s[10:11]
	global_load_dwordx4 v[10:13], v[54:55], off
	global_load_dword v131, v[54:55], off offset:-4
	s_waitcnt vmcnt(4)
	v_perm_b32 v54, v126, v118, s67
	v_perm_b32 v55, v118, v119, s67
	v_perm_b32 v56, v119, v120, s67
	v_perm_b32 v57, v120, v121, s67
	s_nop 1

	v_mfma_f32_16x16x32_bf16 v[78:81], v[54:57], v[18:21], v[98:101]
	v_mfma_f32_16x16x32_bf16 v[98:101], v[118:121], v[22:25], v[102:105]
	s_nop 2
	ds_read_b128 v[102:105], v130 offset:256
	v_mfma_f32_16x16x32_bf16 v[94:97], v[54:57], v[22:25], v[94:97]
	v_mfma_f32_16x16x32_bf16 v[122:125], v[118:121], v[26:29], v[122:125]
	v_mfma_f32_16x16x32_bf16 v[86:89], v[54:57], v[26:29], v[86:89]
	v_mfma_f32_16x16x32_bf16 v[106:109], v[118:121], v[34:37], v[106:109]
	v_mfma_f32_16x16x32_bf16 v[70:73], v[54:57], v[34:37], v[70:73]
	v_mfma_f32_16x16x32_bf16 v[66:69], v[118:121], v[42:45], v[66:69]
	v_mfma_f32_16x16x32_bf16 v[62:65], v[54:57], v[42:45], v[62:65]
	v_mfma_f32_16x16x32_bf16 v[50:53], v[118:121], v[74:77], v[50:53]
	v_mfma_f32_16x16x32_bf16 v[46:49], v[54:57], v[74:77], v[46:49]
	v_mfma_f32_16x16x32_bf16 v[110:113], v[118:121], v[82:85], v[110:113]
	v_mfma_f32_16x16x32_bf16 v[114:117], v[54:57], v[82:85], v[114:117]
	s_waitcnt lgkmcnt(1)
	v_mfma_f32_16x16x32_bf16 v[58:61], v[118:121], v[90:93], v[58:61]
	v_mfma_f32_16x16x32_bf16 v[38:41], v[54:57], v[90:93], v[38:41]
	v_mfma_f32_16x16x32_bf16 v[2:5], v[30:33], v[14:17], v[2:5]

	v_add_u32_e32 v14, 0xfffffae0, v215
	v_min_i32_e32 v14, 0x7f8, v14
	v_ashrrev_i32_e32 v15, 31, v14
	v_lshl_add_u64 v[14:15], v[14:15], 1, s[10:11]
	global_load_dwordx4 v[54:57], v[14:15], off
	global_load_dword v132, v[14:15], off offset:-4
	s_waitcnt vmcnt(4)
	v_perm_b32 v14, v127, v6, s67
	v_perm_b32 v15, v6, v7, s67
	v_perm_b32 v16, v7, v8, s67
	v_perm_b32 v17, v8, v9, s67
	s_nop 0
	ds_read_b128 v[126:129], v130 offset:320
	v_mfma_f32_16x16x32_bf16 v[30:33], v[14:17], v[22:25], v[78:81]
	v_mfma_f32_16x16x32_bf16 v[78:81], v[6:9], v[26:29], v[98:101]
	v_mfma_f32_16x16x32_bf16 v[94:97], v[14:17], v[26:29], v[94:97]
	v_mfma_f32_16x16x32_bf16 v[98:101], v[6:9], v[34:37], v[122:125]
	v_mfma_f32_16x16x32_bf16 v[86:89], v[14:17], v[34:37], v[86:89]
	v_mfma_f32_16x16x32_bf16 v[106:109], v[6:9], v[42:45], v[106:109]
	v_mfma_f32_16x16x32_bf16 v[70:73], v[14:17], v[42:45], v[70:73]
	v_mfma_f32_16x16x32_bf16 v[66:69], v[6:9], v[74:77], v[66:69]
	v_mfma_f32_16x16x32_bf16 v[62:65], v[14:17], v[74:77], v[62:65]
	v_mfma_f32_16x16x32_bf16 v[50:53], v[6:9], v[82:85], v[50:53]
	v_mfma_f32_16x16x32_bf16 v[46:49], v[14:17], v[82:85], v[46:49]
	v_mfma_f32_16x16x32_bf16 v[110:113], v[6:9], v[90:93], v[110:113]
	v_mfma_f32_16x16x32_bf16 v[114:117], v[14:17], v[90:93], v[114:117]
	s_waitcnt lgkmcnt(1)
	v_mfma_f32_16x16x32_bf16 v[58:61], v[6:9], v[102:105], v[58:61]
	v_mfma_f32_16x16x32_bf16 v[14:17], v[14:17], v[102:105], v[38:41]
	v_mfma_f32_16x16x32_bf16 v[2:5], v[118:121], v[18:21], v[2:5]

	v_add_u32_e32 v18, 0xfffffb00, v215
	v_min_i32_e32 v18, 0x7f8, v18
	v_ashrrev_i32_e32 v19, 31, v18
	v_lshl_add_u64 v[18:19], v[18:19], 1, s[10:11]
	global_load_dwordx4 v[38:41], v[18:19], off
	global_load_dword v118, v[18:19], off offset:-4
	s_waitcnt vmcnt(4)
	v_perm_b32 v18, v131, v10, s67
	v_perm_b32 v19, v10, v11, s67
	v_perm_b32 v20, v11, v12, s67
	v_perm_b32 v21, v12, v13, s67
	s_nop 0
	ds_read_b128 v[142:145], v130 offset:384
	v_mfma_f32_16x16x32_bf16 v[30:33], v[18:21], v[26:29], v[30:33]
	v_mfma_f32_16x16x32_bf16 v[78:81], v[10:13], v[34:37], v[78:81]
	v_mfma_f32_16x16x32_bf16 v[94:97], v[18:21], v[34:37], v[94:97]
	v_mfma_f32_16x16x32_bf16 v[98:101], v[10:13], v[42:45], v[98:101]
	v_mfma_f32_16x16x32_bf16 v[86:89], v[18:21], v[42:45], v[86:89]
	v_mfma_f32_16x16x32_bf16 v[106:109], v[10:13], v[74:77], v[106:109]
	v_mfma_f32_16x16x32_bf16 v[70:73], v[18:21], v[74:77], v[70:73]
	v_mfma_f32_16x16x32_bf16 v[66:69], v[10:13], v[82:85], v[66:69]
	v_mfma_f32_16x16x32_bf16 v[62:65], v[18:21], v[82:85], v[62:65]
	v_mfma_f32_16x16x32_bf16 v[50:53], v[10:13], v[90:93], v[50:53]
	v_mfma_f32_16x16x32_bf16 v[46:49], v[18:21], v[90:93], v[46:49]
	v_mfma_f32_16x16x32_bf16 v[110:113], v[10:13], v[102:105], v[110:113]
	v_mfma_f32_16x16x32_bf16 v[114:117], v[18:21], v[102:105], v[114:117]
	s_waitcnt lgkmcnt(1)
	v_mfma_f32_16x16x32_bf16 v[58:61], v[10:13], v[126:129], v[58:61]
	v_mfma_f32_16x16x32_bf16 v[14:17], v[18:21], v[126:129], v[14:17]
	v_mfma_f32_16x16x32_bf16 v[2:5], v[6:9], v[22:25], v[2:5]

; #define CONV_LOADA(e_, k_) do { const int xh_ = min(32 * (e_) + xa, L - 8); rh[k_] = *(const u32x4a4*)(Rc + xh_); asm volatile("" ::: "memory"); rl[k_] = *(const unsigned*)(Rc + xh_ - 2); } while (0)
; #define CONV_BLOCK(DO0, DO1) do { CONV_STEP(0, DO0, DO1); CONV_STEP(1, DO0, DO1); CONV_STEP(2, DO0, DO1); CONV_STEP(3, DO0, DO1); CONV_STEP(4, DO0, DO1); CONV_STEP(5, DO0, DO1); CONV_STEP(6, DO0, DO1); CONV_STEP(7, DO0, DO1); } while (0)
; template <bool PROMPT, int HALF>
; __device__ __forceinline__ void conv_item(unsigned char* ws, KArgs ka, int ib, int oct, int g, LAS unsigned char* lds, int tid, int lane, int wave) {
;     ...
; #pragma unroll
;     for (int k = 0; k < DA; ++k) CONV_LOADA(E0 + k, k);
;     { unsigned zz_ = 0u; asm volatile("" : "+v"(zz_));
; #pragma unroll
;       for (int k = 0; k < W; ++k) F1[k] = (u32x4){zz_, zz_, zz_, zz_}; }
;     for (int e = E0; e < E1; e += 8) CONV_BLOCK(false, true);
;     { unsigned zz_ = 0u; asm volatile("" : "+v"(zz_));
; #pragma unroll
;       for (int k = 0; k < W; ++k) F0[k] = (u32x4){zz_, zz_, zz_, zz_}; }
;     for (int e = E1; e < E2; e += 8) CONV_BLOCK(true, true);
	v_add_u32_e32 v6, 0xfffffb20, v215
	v_min_i32_e32 v6, 0x7f8, v6
	v_ashrrev_i32_e32 v7, 31, v6
	v_lshl_add_u64 v[6:7], v[6:7], 1, s[10:11]
	global_load_dwordx4 v[162:165], v[6:7], off
	global_load_dword v219, v[6:7], off offset:-4
	s_waitcnt vmcnt(4)
	v_perm_b32 v6, v132, v54, s67
	v_perm_b32 v7, v54, v55, s67
	v_perm_b32 v8, v55, v56, s67
	v_perm_b32 v9, v56, v57, s67
	s_nop 0
	ds_read_b128 v[150:153], v130 offset:448
	v_mfma_f32_16x16x32_bf16 v[18:21], v[6:9], v[34:37], v[30:33]
	v_mfma_f32_16x16x32_bf16 v[22:25], v[54:57], v[42:45], v[78:81]
	v_mfma_f32_16x16x32_bf16 v[30:33], v[6:9], v[42:45], v[94:97]
	v_mfma_f32_16x16x32_bf16 v[78:81], v[54:57], v[74:77], v[98:101]
	v_mfma_f32_16x16x32_bf16 v[86:89], v[6:9], v[74:77], v[86:89]
	v_mfma_f32_16x16x32_bf16 v[94:97], v[54:57], v[82:85], v[106:109]
	v_mfma_f32_16x16x32_bf16 v[70:73], v[6:9], v[82:85], v[70:73]
	v_mfma_f32_16x16x32_bf16 v[66:69], v[54:57], v[90:93], v[66:69]
	v_mfma_f32_16x16x32_bf16 v[62:65], v[6:9], v[90:93], v[62:65]
	v_mfma_f32_16x16x32_bf16 v[50:53], v[54:57], v[102:105], v[50:53]
	v_mfma_f32_16x16x32_bf16 v[46:49], v[6:9], v[102:105], v[46:49]
	v_mfma_f32_16x16x32_bf16 v[110:113], v[54:57], v[126:129], v[110:113]
	v_mfma_f32_16x16x32_bf16 v[134:137], v[6:9], v[126:129], v[114:117]
	s_waitcnt lgkmcnt(1)
	v_mfma_f32_16x16x32_bf16 v[58:61], v[54:57], v[142:145], v[58:61]
	v_mfma_f32_16x16x32_bf16 v[138:141], v[6:9], v[142:145], v[14:17]
	v_mfma_f32_16x16x32_bf16 v[146:149], v[10:13], v[26:29], v[2:5]
	s_nop 0
	s_nop 1
	v_add_u32_e32 v2, 0xfffffb40, v215
	v_min_i32_e32 v2, 0x7f8, v2
	v_ashrrev_i32_e32 v3, 31, v2
	v_lshl_add_u64 v[2:3], v[2:3], 1, s[10:11]
	global_load_dwordx4 v[166:169], v[2:3], off
	global_load_dword v220, v[2:3], off offset:-4
	s_waitcnt vmcnt(4)
	v_perm_b32 v2, v118, v38, s67
	v_perm_b32 v3, v38, v39, s67
	v_perm_b32 v4, v39, v40, s67
	v_perm_b32 v5, v40, v41, s67
	s_nop 0
	v_mfma_f32_16x16x32_bf16 v[34:37], v[54:57], v[34:37], v[146:149]
	v_mfma_f32_16x16x32_bf16 v[130:133], v[2:5], v[42:45], v[18:21]
	v_mfma_f32_16x16x32_bf16 v[18:21], v[2:5], v[126:129], v[46:49]
	s_nop 2
	v_mad_u32_u24 v46, v216, s58, v0
	ds_read_b128 v[158:161], v46
	v_mfma_f32_16x16x32_bf16 v[122:125], v[38:41], v[74:77], v[22:25]
	v_mfma_f32_16x16x32_bf16 v[118:121], v[2:5], v[74:77], v[30:33]
	v_mfma_f32_16x16x32_bf16 v[114:117], v[38:41], v[82:85], v[78:81]
	v_mfma_f32_16x16x32_bf16 v[106:109], v[2:5], v[82:85], v[86:89]
	v_mfma_f32_16x16x32_bf16 v[98:101], v[38:41], v[90:93], v[94:97]
	v_mfma_f32_16x16x32_bf16 v[94:97], v[2:5], v[90:93], v[70:73]
	v_mfma_f32_16x16x32_bf16 v[30:33], v[38:41], v[102:105], v[66:69]
	v_mfma_f32_16x16x32_bf16 v[26:29], v[2:5], v[102:105], v[62:65]
	v_mfma_f32_16x16x32_bf16 v[22:25], v[38:41], v[126:129], v[50:53]
	v_mfma_f32_16x16x32_bf16 v[14:17], v[38:41], v[142:145], v[110:113]
	v_mfma_f32_16x16x32_bf16 v[10:13], v[2:5], v[142:145], v[134:137]
	s_waitcnt lgkmcnt(1)
	v_mfma_f32_16x16x32_bf16 v[6:9], v[38:41], v[150:153], v[58:61]
	v_mfma_f32_16x16x32_bf16 v[2:5], v[2:5], v[150:153], v[138:141]
	v_mfma_f32_16x16x32_bf16 v[138:141], v[38:41], v[42:45], v[34:37]
	s_nop 0
	v_mov_b32_e32 v66, v1
	s_nop 0
	v_mov_b32_e32 v34, 0
	v_add_u32_e32 v218, 0xfffffb60, v215
	s_movk_i32 s19, 0xffd1
	s_movk_i32 s22, 0xf640
	v_mov_b32_e32 v35, v34
	v_mov_b32_e32 v36, v34
	v_mov_b32_e32 v37, v34
	v_mov_b32_e32 v38, v34
	v_mov_b32_e32 v39, v34
	v_mov_b32_e32 v40, v34
	v_mov_b32_e32 v41, v34
	v_mov_b32_e32 v46, v34
	v_mov_b32_e32 v47, v34
	v_mov_b32_e32 v48, v34
	v_mov_b32_e32 v49, v34
	v_mov_b32_e32 v54, v34
	v_mov_b32_e32 v55, v34
	v_mov_b32_e32 v56, v34
	v_mov_b32_e32 v57, v34
	v_mov_b32_e32 v170, v34
	v_mov_b32_e32 v171, v34
	v_mov_b32_e32 v172, v34
	v_mov_b32_e32 v173, v34
	v_mov_b32_e32 v174, v34
	v_mov_b32_e32 v175, v34
	v_mov_b32_e32 v176, v34
	v_mov_b32_e32 v177, v34
	v_mov_b32_e32 v182, v34
	v_mov_b32_e32 v183, v34
	v_mov_b32_e32 v184, v34
	v_mov_b32_e32 v185, v34
	v_mov_b32_e32 v190, v34
	v_mov_b32_e32 v191, v34
	v_mov_b32_e32 v192, v34
	v_mov_b32_e32 v193, v34
	v_mov_b32_e32 v42, v34
	v_mov_b32_e32 v43, v34
	v_mov_b32_e32 v44, v34
	v_mov_b32_e32 v45, v34
	v_mov_b32_e32 v50, v34
	v_mov_b32_e32 v51, v34
	v_mov_b32_e32 v52, v34
	v_mov_b32_e32 v53, v34
	v_mov_b32_e32 v58, v34
	v_mov_b32_e32 v59, v34
	v_mov_b32_e32 v60, v34
	v_mov_b32_e32 v61, v34
	v_mov_b32_e32 v62, v34
	v_mov_b32_e32 v63, v34
	v_mov_b32_e32 v64, v34
	v_mov_b32_e32 v65, v34
	v_mov_b32_e32 v178, v34
	v_mov_b32_e32 v179, v34
	v_mov_b32_e32 v180, v34
	v_mov_b32_e32 v181, v34
	v_mov_b32_e32 v186, v34
	v_mov_b32_e32 v187, v34
	v_mov_b32_e32 v188, v34
	v_mov_b32_e32 v189, v34
	v_mov_b32_e32 v198, v34
	v_mov_b32_e32 v199, v34
	v_mov_b32_e32 v200, v34
	v_mov_b32_e32 v201, v34
	v_mov_b32_e32 v194, v34
	v_mov_b32_e32 v195, v34
	v_mov_b32_e32 v196, v34
	v_mov_b32_e32 v197, v34
	v_mov_b32_e32 v67, v66
	v_mov_b32_e32 v68, v66
	v_mov_b32_e32 v69, v66
	v_mov_b32_e32 v70, v66
	v_mov_b32_e32 v71, v66
	v_mov_b32_e32 v72, v66
	v_mov_b32_e32 v73, v66
	v_mov_b32_e32 v78, v66
	v_mov_b32_e32 v79, v66
	v_mov_b32_e32 v80, v66
	v_mov_b32_e32 v81, v66
	v_mov_b32_e32 v86, v66
	v_mov_b32_e32 v87, v66
	v_mov_b32_e32 v88, v66
	v_mov_b32_e32 v89, v66
	v_mov_b32_e32 v110, v66
	v_mov_b32_e32 v111, v66
	v_mov_b32_e32 v112, v66
	v_mov_b32_e32 v113, v66
	v_mov_b32_e32 v134, v66
	v_mov_b32_e32 v135, v66
	v_mov_b32_e32 v136, v66
	v_mov_b32_e32 v137, v66
	v_mov_b32_e32 v146, v66
	v_mov_b32_e32 v147, v66
	v_mov_b32_e32 v148, v66
	v_mov_b32_e32 v149, v66
	v_mov_b32_e32 v154, v66
	v_mov_b32_e32 v155, v66
	v_mov_b32_e32 v156, v66
	v_mov_b32_e32 v157, v66
.LBB0_732:
	v_min_i32_e32 v210, 0x7f8, v218
	v_ashrrev_i32_e32 v211, 31, v210
	v_lshl_add_u64 v[210:211], v[210:211], 1, s[10:11]
	global_load_dwordx4 v[222:225], v[210:211], off
	global_load_dword v221, v[210:211], off offset:-4
	s_waitcnt vmcnt(4)
	v_perm_b32 v226, v219, v162, s67
	v_perm_b32 v227, v162, v163, s67
	v_perm_b32 v228, v163, v164, s67
	v_perm_b32 v229, v164, v165, s67

	s_add_i32 s23, s19, 16
	s_ashr_i32 s23, s23, 3
	v_mfma_f32_16x16x32_bf16 v[138:141], v[162:165], v[74:77], v[138:141]
	s_and_b32 s30, s22, 0x1c0
	v_mfma_f32_16x16x32_bf16 v[130:133], v[226:229], v[74:77], v[130:133]
	v_add_u32_e32 v74, s23, v216
	v_add_u32_e32 v75, s23, v217
	v_cmp_gt_u32_e32 vcc, 8, v74
	v_mfma_f32_16x16x32_bf16 v[194:197], v[162:165], v[154:157], v[194:197]
	s_nop 0
	v_cndmask_b32_e32 v74, v214, v74, vcc
	v_cmp_gt_u32_e32 vcc, 8, v75
	v_mul_lo_u32 v74, v74, s58
	v_add3_u32 v74, v0, v74, s30
	v_cndmask_b32_e32 v75, v214, v75, vcc
	v_mul_lo_u32 v75, v75, s58
	v_add3_u32 v75, v0, v75, s30
	v_mfma_f32_16x16x32_bf16 v[190:193], v[226:229], v[154:157], v[190:193]
	ds_read_b128 v[154:157], v74
	ds_read_b128 v[74:77], v75
	v_mfma_f32_16x16x32_bf16 v[198:201], v[162:165], v[146:149], v[198:201]
	v_mfma_f32_16x16x32_bf16 v[182:185], v[226:229], v[146:149], v[182:185]
	v_mfma_f32_16x16x32_bf16 v[122:125], v[162:165], v[82:85], v[122:125]
	v_mfma_f32_16x16x32_bf16 v[118:121], v[226:229], v[82:85], v[118:121]
	v_mfma_f32_16x16x32_bf16 v[186:189], v[162:165], v[134:137], v[186:189]
	v_mfma_f32_16x16x32_bf16 v[174:177], v[226:229], v[134:137], v[174:177]
	v_mfma_f32_16x16x32_bf16 v[114:117], v[162:165], v[90:93], v[114:117]
	v_mfma_f32_16x16x32_bf16 v[106:109], v[226:229], v[90:93], v[106:109]
	v_mfma_f32_16x16x32_bf16 v[178:181], v[162:165], v[110:113], v[178:181]
	v_mfma_f32_16x16x32_bf16 v[170:173], v[226:229], v[110:113], v[170:173]
	v_mfma_f32_16x16x32_bf16 v[98:101], v[162:165], v[102:105], v[98:101]
	v_mfma_f32_16x16x32_bf16 v[94:97], v[226:229], v[102:105], v[94:97]
	v_mfma_f32_16x16x32_bf16 v[62:65], v[162:165], v[86:89], v[62:65]
	v_mfma_f32_16x16x32_bf16 v[54:57], v[226:229], v[86:89], v[54:57]
	v_mfma_f32_16x16x32_bf16 v[30:33], v[162:165], v[126:129], v[30:33]
	v_mfma_f32_16x16x32_bf16 v[26:29], v[226:229], v[126:129], v[26:29]
	v_mfma_f32_16x16x32_bf16 v[58:61], v[162:165], v[78:81], v[58:61]
	v_mfma_f32_16x16x32_bf16 v[46:49], v[226:229], v[78:81], v[46:49]
	v_mfma_f32_16x16x32_bf16 v[22:25], v[162:165], v[142:145], v[22:25]
	v_mfma_f32_16x16x32_bf16 v[18:21], v[226:229], v[142:145], v[18:21]
	v_mfma_f32_16x16x32_bf16 v[50:53], v[162:165], v[70:73], v[50:53]
	v_mfma_f32_16x16x32_bf16 v[38:41], v[226:229], v[70:73], v[38:41]
	v_mfma_f32_16x16x32_bf16 v[14:17], v[162:165], v[150:153], v[14:17]
	v_mfma_f32_16x16x32_bf16 v[10:13], v[226:229], v[150:153], v[10:13]
	s_waitcnt lgkmcnt(3)
	v_mfma_f32_16x16x32_bf16 v[42:45], v[162:165], v[66:69], v[42:45]
	v_mfma_f32_16x16x32_bf16 v[34:37], v[226:229], v[66:69], v[34:37]
	s_waitcnt lgkmcnt(2)
	v_mfma_f32_16x16x32_bf16 v[6:9], v[162:165], v[158:161], v[6:9]
	v_mfma_f32_16x16x32_bf16 v[2:5], v[226:229], v[158:161], v[2:5]

	v_add_u32_e32 v162, 32, v218
	v_min_i32_e32 v162, 0x7f8, v162
	v_ashrrev_i32_e32 v163, 31, v162
	v_lshl_add_u64 v[210:211], v[162:163], 1, s[10:11]
	global_load_dwordx4 v[162:165], v[210:211], off
	global_load_dword v219, v[210:211], off offset:-4
	s_waitcnt vmcnt(4)
	v_perm_b32 v226, v220, v166, s67
	v_perm_b32 v227, v166, v167, s67
	v_perm_b32 v228, v167, v168, s67
	v_perm_b32 v229, v168, v169, s67

	s_add_i32 s23, s19, 17
	s_ashr_i32 s23, s23, 3
	v_mfma_f32_16x16x32_bf16 v[138:141], v[166:169], v[82:85], v[138:141]
	s_add_i32 s30, s22, 0x240
	s_and_b32 s30, s30, 0x1c0
	v_mfma_f32_16x16x32_bf16 v[130:133], v[226:229], v[82:85], v[130:133]
	v_add_u32_e32 v82, s23, v216
	v_add_u32_e32 v83, s23, v217
	v_cmp_gt_u32_e32 vcc, 8, v82
	v_mfma_f32_16x16x32_bf16 v[194:197], v[166:169], v[146:149], v[194:197]
	s_nop 0
	v_cndmask_b32_e32 v82, v214, v82, vcc
	v_cmp_gt_u32_e32 vcc, 8, v83
	v_mul_lo_u32 v82, v82, s58
	v_add3_u32 v82, v0, v82, s30
	v_cndmask_b32_e32 v83, v214, v83, vcc
	v_mul_lo_u32 v83, v83, s58
	v_add3_u32 v83, v0, v83, s30
	v_mfma_f32_16x16x32_bf16 v[190:193], v[226:229], v[146:149], v[190:193]
	ds_read_b128 v[146:149], v82
	ds_read_b128 v[82:85], v83
	v_mfma_f32_16x16x32_bf16 v[198:201], v[166:169], v[134:137], v[198:201]
	v_mfma_f32_16x16x32_bf16 v[182:185], v[226:229], v[134:137], v[182:185]
	v_mfma_f32_16x16x32_bf16 v[122:125], v[166:169], v[90:93], v[122:125]
	v_mfma_f32_16x16x32_bf16 v[118:121], v[226:229], v[90:93], v[118:121]
	v_mfma_f32_16x16x32_bf16 v[186:189], v[166:169], v[110:113], v[186:189]
	v_mfma_f32_16x16x32_bf16 v[174:177], v[226:229], v[110:113], v[174:177]
	v_mfma_f32_16x16x32_bf16 v[114:117], v[166:169], v[102:105], v[114:117]
	v_mfma_f32_16x16x32_bf16 v[106:109], v[226:229], v[102:105], v[106:109]
	v_mfma_f32_16x16x32_bf16 v[178:181], v[166:169], v[86:89], v[178:181]
	v_mfma_f32_16x16x32_bf16 v[170:173], v[226:229], v[86:89], v[170:173]
	v_mfma_f32_16x16x32_bf16 v[98:101], v[166:169], v[126:129], v[98:101]
	v_mfma_f32_16x16x32_bf16 v[94:97], v[226:229], v[126:129], v[94:97]
	v_mfma_f32_16x16x32_bf16 v[62:65], v[166:169], v[78:81], v[62:65]
	v_mfma_f32_16x16x32_bf16 v[54:57], v[226:229], v[78:81], v[54:57]
	v_mfma_f32_16x16x32_bf16 v[30:33], v[166:169], v[142:145], v[30:33]
	v_mfma_f32_16x16x32_bf16 v[26:29], v[226:229], v[142:145], v[26:29]
	v_mfma_f32_16x16x32_bf16 v[58:61], v[166:169], v[70:73], v[58:61]
	v_mfma_f32_16x16x32_bf16 v[46:49], v[226:229], v[70:73], v[46:49]
	v_mfma_f32_16x16x32_bf16 v[22:25], v[166:169], v[150:153], v[22:25]
	v_mfma_f32_16x16x32_bf16 v[18:21], v[226:229], v[150:153], v[18:21]
	v_mfma_f32_16x16x32_bf16 v[50:53], v[166:169], v[66:69], v[50:53]
	v_mfma_f32_16x16x32_bf16 v[38:41], v[226:229], v[66:69], v[38:41]
	v_mfma_f32_16x16x32_bf16 v[14:17], v[166:169], v[158:161], v[14:17]
	v_mfma_f32_16x16x32_bf16 v[10:13], v[226:229], v[158:161], v[10:13]
	s_waitcnt lgkmcnt(3)
	v_mfma_f32_16x16x32_bf16 v[42:45], v[166:169], v[154:157], v[42:45]
	v_mfma_f32_16x16x32_bf16 v[34:37], v[226:229], v[154:157], v[34:37]
	s_waitcnt lgkmcnt(2)
	v_mfma_f32_16x16x32_bf16 v[6:9], v[166:169], v[74:77], v[6:9]
	v_mfma_f32_16x16x32_bf16 v[2:5], v[226:229], v[74:77], v[2:5]

	v_add_u32_e32 v166, 64, v218
	v_min_i32_e32 v166, 0x7f8, v166
	v_ashrrev_i32_e32 v167, 31, v166
	v_lshl_add_u64 v[210:211], v[166:167], 1, s[10:11]
	global_load_dwordx4 v[166:169], v[210:211], off
	global_load_dword v230, v[210:211], off offset:-4
	s_waitcnt vmcnt(4)
	v_perm_b32 v226, v221, v222, s67
	v_perm_b32 v227, v222, v223, s67
	v_perm_b32 v228, v223, v224, s67
	v_perm_b32 v229, v224, v225, s67

	s_add_i32 s23, s19, 18
	s_ashr_i32 s23, s23, 3
	v_mfma_f32_16x16x32_bf16 v[138:141], v[222:225], v[90:93], v[138:141]
	s_add_i32 s30, s22, 0x280
	s_and_b32 s30, s30, 0x1c0
	v_mfma_f32_16x16x32_bf16 v[130:133], v[226:229], v[90:93], v[130:133]
	v_add_u32_e32 v90, s23, v216
	v_add_u32_e32 v91, s23, v217
	v_cmp_gt_u32_e32 vcc, 8, v90
	v_mfma_f32_16x16x32_bf16 v[194:197], v[222:225], v[134:137], v[194:197]
	s_nop 0
	v_cndmask_b32_e32 v90, v214, v90, vcc
	v_cmp_gt_u32_e32 vcc, 8, v91
	v_mul_lo_u32 v90, v90, s58
	v_add3_u32 v90, v0, v90, s30
	v_cndmask_b32_e32 v91, v214, v91, vcc
	v_mul_lo_u32 v91, v91, s58
	v_add3_u32 v91, v0, v91, s30
	v_mfma_f32_16x16x32_bf16 v[190:193], v[226:229], v[134:137], v[190:193]
	ds_read_b128 v[134:137], v90
	ds_read_b128 v[90:93], v91
	v_mfma_f32_16x16x32_bf16 v[198:201], v[222:225], v[110:113], v[198:201]
	v_mfma_f32_16x16x32_bf16 v[182:185], v[226:229], v[110:113], v[182:185]
	v_mfma_f32_16x16x32_bf16 v[122:125], v[222:225], v[102:105], v[122:125]
	v_mfma_f32_16x16x32_bf16 v[118:121], v[226:229], v[102:105], v[118:121]
	v_mfma_f32_16x16x32_bf16 v[186:189], v[222:225], v[86:89], v[186:189]
	v_mfma_f32_16x16x32_bf16 v[174:177], v[226:229], v[86:89], v[174:177]
	v_mfma_f32_16x16x32_bf16 v[114:117], v[222:225], v[126:129], v[114:117]
	v_mfma_f32_16x16x32_bf16 v[106:109], v[226:229], v[126:129], v[106:109]
	v_mfma_f32_16x16x32_bf16 v[178:181], v[222:225], v[78:81], v[178:181]
	v_mfma_f32_16x16x32_bf16 v[170:173], v[226:229], v[78:81], v[170:173]
	v_mfma_f32_16x16x32_bf16 v[98:101], v[222:225], v[142:145], v[98:101]
	v_mfma_f32_16x16x32_bf16 v[94:97], v[226:229], v[142:145], v[94:97]
	v_mfma_f32_16x16x32_bf16 v[62:65], v[222:225], v[70:73], v[62:65]
	v_mfma_f32_16x16x32_bf16 v[54:57], v[226:229], v[70:73], v[54:57]
	v_mfma_f32_16x16x32_bf16 v[30:33], v[222:225], v[150:153], v[30:33]
	v_mfma_f32_16x16x32_bf16 v[26:29], v[226:229], v[150:153], v[26:29]
	v_mfma_f32_16x16x32_bf16 v[58:61], v[222:225], v[66:69], v[58:61]
	v_mfma_f32_16x16x32_bf16 v[46:49], v[226:229], v[66:69], v[46:49]
	v_mfma_f32_16x16x32_bf16 v[22:25], v[222:225], v[158:161], v[22:25]
	v_mfma_f32_16x16x32_bf16 v[18:21], v[226:229], v[158:161], v[18:21]
	v_mfma_f32_16x16x32_bf16 v[50:53], v[222:225], v[154:157], v[50:53]
	v_mfma_f32_16x16x32_bf16 v[38:41], v[226:229], v[154:157], v[38:41]
	v_mfma_f32_16x16x32_bf16 v[14:17], v[222:225], v[74:77], v[14:17]
	v_mfma_f32_16x16x32_bf16 v[10:13], v[226:229], v[74:77], v[10:13]
	s_waitcnt lgkmcnt(3)
	v_mfma_f32_16x16x32_bf16 v[42:45], v[222:225], v[146:149], v[42:45]
	v_mfma_f32_16x16x32_bf16 v[34:37], v[226:229], v[146:149], v[34:37]
	s_waitcnt lgkmcnt(2)
	v_mfma_f32_16x16x32_bf16 v[6:9], v[222:225], v[82:85], v[6:9]
	v_mfma_f32_16x16x32_bf16 v[2:5], v[226:229], v[82:85], v[2:5]

	v_add_u32_e32 v210, 0x60, v218
	v_min_i32_e32 v210, 0x7f8, v210
	v_ashrrev_i32_e32 v211, 31, v210
	v_lshl_add_u64 v[210:211], v[210:211], 1, s[10:11]
	global_load_dwordx4 v[220:223], v[210:211], off
	global_load_dword v210, v[210:211], off offset:-4
	s_waitcnt vmcnt(4)
	v_perm_b32 v224, v219, v162, s67
	v_perm_b32 v225, v162, v163, s67
	v_perm_b32 v226, v163, v164, s67
	v_perm_b32 v227, v164, v165, s67

	s_add_i32 s23, s19, 19
	s_ashr_i32 s23, s23, 3
	v_mfma_f32_16x16x32_bf16 v[138:141], v[162:165], v[102:105], v[138:141]
	s_add_i32 s30, s22, 0x2c0
	s_and_b32 s30, s30, 0x1c0
	v_mfma_f32_16x16x32_bf16 v[130:133], v[224:227], v[102:105], v[130:133]
	v_add_u32_e32 v102, s23, v216
	v_add_u32_e32 v103, s23, v217
	v_cmp_gt_u32_e32 vcc, 8, v102
	v_mfma_f32_16x16x32_bf16 v[194:197], v[162:165], v[110:113], v[194:197]
	s_nop 0
	v_cndmask_b32_e32 v102, v214, v102, vcc
	v_cmp_gt_u32_e32 vcc, 8, v103
	v_mul_lo_u32 v102, v102, s58
	v_add3_u32 v102, v0, v102, s30
	v_cndmask_b32_e32 v103, v214, v103, vcc
	v_mul_lo_u32 v103, v103, s58
	v_add3_u32 v103, v0, v103, s30
	v_mfma_f32_16x16x32_bf16 v[190:193], v[224:227], v[110:113], v[190:193]
	ds_read_b128 v[110:113], v102
	ds_read_b128 v[102:105], v103
	v_mfma_f32_16x16x32_bf16 v[198:201], v[162:165], v[86:89], v[198:201]
	v_mfma_f32_16x16x32_bf16 v[182:185], v[224:227], v[86:89], v[182:185]
	v_mfma_f32_16x16x32_bf16 v[122:125], v[162:165], v[126:129], v[122:125]
	v_mfma_f32_16x16x32_bf16 v[118:121], v[224:227], v[126:129], v[118:121]
	v_mfma_f32_16x16x32_bf16 v[186:189], v[162:165], v[78:81], v[186:189]
	v_mfma_f32_16x16x32_bf16 v[174:177], v[224:227], v[78:81], v[174:177]
	v_mfma_f32_16x16x32_bf16 v[114:117], v[162:165], v[142:145], v[114:117]
	v_mfma_f32_16x16x32_bf16 v[106:109], v[224:227], v[142:145], v[106:109]
	v_mfma_f32_16x16x32_bf16 v[178:181], v[162:165], v[70:73], v[178:181]
	v_mfma_f32_16x16x32_bf16 v[170:173], v[224:227], v[70:73], v[170:173]
	v_mfma_f32_16x16x32_bf16 v[98:101], v[162:165], v[150:153], v[98:101]
	v_mfma_f32_16x16x32_bf16 v[94:97], v[224:227], v[150:153], v[94:97]
	v_mfma_f32_16x16x32_bf16 v[62:65], v[162:165], v[66:69], v[62:65]
	v_mfma_f32_16x16x32_bf16 v[54:57], v[224:227], v[66:69], v[54:57]
	v_mfma_f32_16x16x32_bf16 v[30:33], v[162:165], v[158:161], v[30:33]
	v_mfma_f32_16x16x32_bf16 v[26:29], v[224:227], v[158:161], v[26:29]
	v_mfma_f32_16x16x32_bf16 v[58:61], v[162:165], v[154:157], v[58:61]
	v_mfma_f32_16x16x32_bf16 v[46:49], v[224:227], v[154:157], v[46:49]
	v_mfma_f32_16x16x32_bf16 v[22:25], v[162:165], v[74:77], v[22:25]
	v_mfma_f32_16x16x32_bf16 v[18:21], v[224:227], v[74:77], v[18:21]
	v_mfma_f32_16x16x32_bf16 v[50:53], v[162:165], v[146:149], v[50:53]
	v_mfma_f32_16x16x32_bf16 v[38:41], v[224:227], v[146:149], v[38:41]
	v_mfma_f32_16x16x32_bf16 v[14:17], v[162:165], v[82:85], v[14:17]
	v_mfma_f32_16x16x32_bf16 v[10:13], v[224:227], v[82:85], v[10:13]
	s_waitcnt lgkmcnt(3)
	v_mfma_f32_16x16x32_bf16 v[42:45], v[162:165], v[134:137], v[42:45]
	v_mfma_f32_16x16x32_bf16 v[34:37], v[224:227], v[134:137], v[34:37]
	s_waitcnt lgkmcnt(2)
	v_mfma_f32_16x16x32_bf16 v[6:9], v[162:165], v[90:93], v[6:9]
	v_mfma_f32_16x16x32_bf16 v[2:5], v[224:227], v[90:93], v[2:5]

	v_add_u32_e32 v162, 0x80, v218
	v_min_i32_e32 v162, 0x7f8, v162
	v_ashrrev_i32_e32 v163, 31, v162
	v_lshl_add_u64 v[162:163], v[162:163], 1, s[10:11]
	global_load_dwordx4 v[224:227], v[162:163], off
	global_load_dword v211, v[162:163], off offset:-4
	s_waitcnt vmcnt(4)
	v_perm_b32 v162, v230, v166, s67
	v_perm_b32 v163, v166, v167, s67
	v_perm_b32 v164, v167, v168, s67
	v_perm_b32 v165, v168, v169, s67

	s_add_i32 s23, s19, 20
	s_ashr_i32 s23, s23, 3
	v_mfma_f32_16x16x32_bf16 v[194:197], v[166:169], v[86:89], v[194:197]
	s_add_i32 s30, s22, 0x300
	s_and_b32 s30, s30, 0x1c0
	v_mfma_f32_16x16x32_bf16 v[190:193], v[162:165], v[86:89], v[190:193]
	v_add_u32_e32 v86, s23, v216
	v_add_u32_e32 v87, s23, v217
	v_cmp_gt_u32_e32 vcc, 8, v86
	v_mfma_f32_16x16x32_bf16 v[138:141], v[166:169], v[126:129], v[138:141]
	s_nop 0
	v_cndmask_b32_e32 v86, v214, v86, vcc
	v_cmp_gt_u32_e32 vcc, 8, v87
	v_mul_lo_u32 v86, v86, s58
	v_mfma_f32_16x16x32_bf16 v[130:133], v[162:165], v[126:129], v[130:133]
	v_cndmask_b32_e32 v87, v214, v87, vcc
	v_mul_lo_u32 v87, v87, s58
	v_add3_u32 v86, v0, v86, s30
	v_add3_u32 v126, v0, v87, s30
	ds_read_b128 v[86:89], v86
	ds_read_b128 v[126:129], v126
	v_mfma_f32_16x16x32_bf16 v[198:201], v[166:169], v[78:81], v[198:201]
	v_mfma_f32_16x16x32_bf16 v[182:185], v[162:165], v[78:81], v[182:185]
	v_mfma_f32_16x16x32_bf16 v[122:125], v[166:169], v[142:145], v[122:125]
	v_mfma_f32_16x16x32_bf16 v[118:121], v[162:165], v[142:145], v[118:121]
	v_mfma_f32_16x16x32_bf16 v[186:189], v[166:169], v[70:73], v[186:189]
	v_mfma_f32_16x16x32_bf16 v[174:177], v[162:165], v[70:73], v[174:177]
	v_mfma_f32_16x16x32_bf16 v[114:117], v[166:169], v[150:153], v[114:117]
	v_mfma_f32_16x16x32_bf16 v[106:109], v[162:165], v[150:153], v[106:109]
	v_mfma_f32_16x16x32_bf16 v[178:181], v[166:169], v[66:69], v[178:181]
	v_mfma_f32_16x16x32_bf16 v[170:173], v[162:165], v[66:69], v[170:173]
	v_mfma_f32_16x16x32_bf16 v[98:101], v[166:169], v[158:161], v[98:101]
	v_mfma_f32_16x16x32_bf16 v[94:97], v[162:165], v[158:161], v[94:97]
	v_mfma_f32_16x16x32_bf16 v[62:65], v[166:169], v[154:157], v[62:65]
	v_mfma_f32_16x16x32_bf16 v[54:57], v[162:165], v[154:157], v[54:57]
	v_mfma_f32_16x16x32_bf16 v[30:33], v[166:169], v[74:77], v[30:33]
	v_mfma_f32_16x16x32_bf16 v[26:29], v[162:165], v[74:77], v[26:29]
	v_mfma_f32_16x16x32_bf16 v[58:61], v[166:169], v[146:149], v[58:61]
	v_mfma_f32_16x16x32_bf16 v[46:49], v[162:165], v[146:149], v[46:49]
	v_mfma_f32_16x16x32_bf16 v[22:25], v[166:169], v[82:85], v[22:25]
	v_mfma_f32_16x16x32_bf16 v[18:21], v[162:165], v[82:85], v[18:21]
	v_mfma_f32_16x16x32_bf16 v[50:53], v[166:169], v[134:137], v[50:53]
	v_mfma_f32_16x16x32_bf16 v[38:41], v[162:165], v[134:137], v[38:41]
	v_mfma_f32_16x16x32_bf16 v[14:17], v[166:169], v[90:93], v[14:17]
	v_mfma_f32_16x16x32_bf16 v[10:13], v[162:165], v[90:93], v[10:13]
	s_waitcnt lgkmcnt(3)
	v_mfma_f32_16x16x32_bf16 v[42:45], v[166:169], v[110:113], v[42:45]
	v_mfma_f32_16x16x32_bf16 v[34:37], v[162:165], v[110:113], v[34:37]
	s_waitcnt lgkmcnt(2)
	v_mfma_f32_16x16x32_bf16 v[6:9], v[166:169], v[102:105], v[6:9]
	v_mfma_f32_16x16x32_bf16 v[2:5], v[162:165], v[102:105], v[2:5]

	v_add_u32_e32 v162, 0xa0, v218
	v_min_i32_e32 v162, 0x7f8, v162
	v_ashrrev_i32_e32 v163, 31, v162
	v_lshl_add_u64 v[162:163], v[162:163], 1, s[10:11]
	global_load_dwordx4 v[228:231], v[162:163], off
	global_load_dword v236, v[162:163], off offset:-4
	s_waitcnt vmcnt(4)
	v_perm_b32 v162, v210, v220, s67
	v_perm_b32 v163, v220, v221, s67
	v_perm_b32 v164, v221, v222, s67
	v_perm_b32 v165, v222, v223, s67

	s_add_i32 s23, s19, 21
	s_ashr_i32 s23, s23, 3
	v_mfma_f32_16x16x32_bf16 v[166:169], v[220:223], v[78:81], v[194:197]
	s_add_i32 s30, s22, 0x340
	s_and_b32 s30, s30, 0x1c0
	v_mfma_f32_16x16x32_bf16 v[190:193], v[162:165], v[78:81], v[190:193]
	v_add_u32_e32 v78, s23, v216
	v_add_u32_e32 v79, s23, v217
	v_cmp_gt_u32_e32 vcc, 8, v78
	v_mfma_f32_16x16x32_bf16 v[138:141], v[220:223], v[142:145], v[138:141]
	s_nop 0
	v_cndmask_b32_e32 v78, v214, v78, vcc
	v_cmp_gt_u32_e32 vcc, 8, v79
	v_mul_lo_u32 v78, v78, s58
	v_mfma_f32_16x16x32_bf16 v[130:133], v[162:165], v[142:145], v[130:133]
	v_cndmask_b32_e32 v79, v214, v79, vcc
	v_mul_lo_u32 v79, v79, s58
	v_add3_u32 v78, v0, v78, s30
	v_add3_u32 v142, v0, v79, s30
	ds_read_b128 v[78:81], v78
	ds_read_b128 v[142:145], v142
	v_mfma_f32_16x16x32_bf16 v[194:197], v[220:223], v[70:73], v[198:201]
	v_mfma_f32_16x16x32_bf16 v[182:185], v[162:165], v[70:73], v[182:185]
	v_mfma_f32_16x16x32_bf16 v[122:125], v[220:223], v[150:153], v[122:125]
	v_mfma_f32_16x16x32_bf16 v[118:121], v[162:165], v[150:153], v[118:121]
	v_mfma_f32_16x16x32_bf16 v[186:189], v[220:223], v[66:69], v[186:189]
	v_mfma_f32_16x16x32_bf16 v[174:177], v[162:165], v[66:69], v[174:177]
	v_mfma_f32_16x16x32_bf16 v[114:117], v[220:223], v[158:161], v[114:117]
	v_mfma_f32_16x16x32_bf16 v[106:109], v[162:165], v[158:161], v[106:109]
	v_mfma_f32_16x16x32_bf16 v[178:181], v[220:223], v[154:157], v[178:181]
	v_mfma_f32_16x16x32_bf16 v[170:173], v[162:165], v[154:157], v[170:173]
	v_mfma_f32_16x16x32_bf16 v[98:101], v[220:223], v[74:77], v[98:101]
	v_mfma_f32_16x16x32_bf16 v[94:97], v[162:165], v[74:77], v[94:97]
	v_mfma_f32_16x16x32_bf16 v[62:65], v[220:223], v[146:149], v[62:65]
	v_mfma_f32_16x16x32_bf16 v[54:57], v[162:165], v[146:149], v[54:57]
	v_mfma_f32_16x16x32_bf16 v[30:33], v[220:223], v[82:85], v[30:33]
	v_mfma_f32_16x16x32_bf16 v[26:29], v[162:165], v[82:85], v[26:29]
	v_mfma_f32_16x16x32_bf16 v[58:61], v[220:223], v[134:137], v[58:61]
	v_mfma_f32_16x16x32_bf16 v[46:49], v[162:165], v[134:137], v[46:49]
	v_mfma_f32_16x16x32_bf16 v[22:25], v[220:223], v[90:93], v[22:25]
	v_mfma_f32_16x16x32_bf16 v[18:21], v[162:165], v[90:93], v[18:21]
	v_mfma_f32_16x16x32_bf16 v[50:53], v[220:223], v[110:113], v[50:53]
	v_mfma_f32_16x16x32_bf16 v[38:41], v[162:165], v[110:113], v[38:41]
	v_mfma_f32_16x16x32_bf16 v[14:17], v[220:223], v[102:105], v[14:17]
	v_mfma_f32_16x16x32_bf16 v[10:13], v[162:165], v[102:105], v[10:13]
	s_waitcnt lgkmcnt(3)
	v_mfma_f32_16x16x32_bf16 v[42:45], v[220:223], v[86:89], v[42:45]
	v_mfma_f32_16x16x32_bf16 v[34:37], v[162:165], v[86:89], v[34:37]
	s_waitcnt lgkmcnt(2)
	v_mfma_f32_16x16x32_bf16 v[6:9], v[220:223], v[126:129], v[6:9]
	v_mfma_f32_16x16x32_bf16 v[2:5], v[162:165], v[126:129], v[2:5]

	v_add_u32_e32 v162, 0xc0, v218
	v_min_i32_e32 v162, 0x7f8, v162
	v_ashrrev_i32_e32 v163, 31, v162
	v_lshl_add_u64 v[198:199], v[162:163], 1, s[10:11]
	global_load_dwordx4 v[162:165], v[198:199], off
	global_load_dword v219, v[198:199], off offset:-4
	s_waitcnt vmcnt(4)
	v_perm_b32 v198, v211, v224, s67
	v_perm_b32 v199, v224, v225, s67
	v_perm_b32 v200, v225, v226, s67
	v_perm_b32 v201, v226, v227, s67

	s_add_i32 s23, s19, 22
	s_ashr_i32 s23, s23, 3
	v_mfma_f32_16x16x32_bf16 v[232:235], v[224:227], v[70:73], v[166:169]
	s_add_i32 s30, s22, 0x380
	s_and_b32 s30, s30, 0x1c0
	v_mfma_f32_16x16x32_bf16 v[190:193], v[198:201], v[70:73], v[190:193]
	v_add_u32_e32 v70, s23, v216
	v_add_u32_e32 v71, s23, v217
	v_cmp_gt_u32_e32 vcc, 8, v70
	v_mfma_f32_16x16x32_bf16 v[138:141], v[224:227], v[150:153], v[138:141]
	s_nop 0
	v_cndmask_b32_e32 v70, v214, v70, vcc
	v_cmp_gt_u32_e32 vcc, 8, v71
	v_mul_lo_u32 v70, v70, s58
	v_mfma_f32_16x16x32_bf16 v[130:133], v[198:201], v[150:153], v[130:133]
	v_cndmask_b32_e32 v71, v214, v71, vcc
	v_mul_lo_u32 v71, v71, s58
	v_add3_u32 v70, v0, v70, s30
	v_add3_u32 v150, v0, v71, s30
	ds_read_b128 v[70:73], v70
	ds_read_b128 v[150:153], v150
	v_mfma_f32_16x16x32_bf16 v[182:185], v[198:201], v[66:69], v[182:185]
	v_mfma_f32_16x16x32_bf16 v[122:125], v[224:227], v[158:161], v[122:125]
	v_mfma_f32_16x16x32_bf16 v[118:121], v[198:201], v[158:161], v[118:121]
	v_mfma_f32_16x16x32_bf16 v[186:189], v[224:227], v[154:157], v[186:189]
	v_mfma_f32_16x16x32_bf16 v[174:177], v[198:201], v[154:157], v[174:177]
	v_mfma_f32_16x16x32_bf16 v[114:117], v[224:227], v[74:77], v[114:117]
	v_mfma_f32_16x16x32_bf16 v[106:109], v[198:201], v[74:77], v[106:109]
	v_mfma_f32_16x16x32_bf16 v[178:181], v[224:227], v[146:149], v[178:181]
	v_mfma_f32_16x16x32_bf16 v[170:173], v[198:201], v[146:149], v[170:173]
	v_mfma_f32_16x16x32_bf16 v[98:101], v[224:227], v[82:85], v[98:101]
	v_mfma_f32_16x16x32_bf16 v[94:97], v[198:201], v[82:85], v[94:97]
	v_mfma_f32_16x16x32_bf16 v[62:65], v[224:227], v[134:137], v[62:65]
	v_mfma_f32_16x16x32_bf16 v[54:57], v[198:201], v[134:137], v[54:57]
	v_mfma_f32_16x16x32_bf16 v[30:33], v[224:227], v[90:93], v[30:33]
	v_mfma_f32_16x16x32_bf16 v[26:29], v[198:201], v[90:93], v[26:29]
	v_mfma_f32_16x16x32_bf16 v[58:61], v[224:227], v[110:113], v[58:61]
	v_mfma_f32_16x16x32_bf16 v[46:49], v[198:201], v[110:113], v[46:49]
	v_mfma_f32_16x16x32_bf16 v[22:25], v[224:227], v[102:105], v[22:25]
	v_mfma_f32_16x16x32_bf16 v[18:21], v[198:201], v[102:105], v[18:21]
	v_mfma_f32_16x16x32_bf16 v[50:53], v[224:227], v[86:89], v[50:53]
	v_mfma_f32_16x16x32_bf16 v[38:41], v[198:201], v[86:89], v[38:41]
	v_mfma_f32_16x16x32_bf16 v[14:17], v[224:227], v[126:129], v[14:17]
	v_mfma_f32_16x16x32_bf16 v[10:13], v[198:201], v[126:129], v[10:13]
	s_waitcnt lgkmcnt(3)
	v_mfma_f32_16x16x32_bf16 v[42:45], v[224:227], v[78:81], v[42:45]
	v_mfma_f32_16x16x32_bf16 v[34:37], v[198:201], v[78:81], v[34:37]
	s_waitcnt lgkmcnt(2)
	v_mfma_f32_16x16x32_bf16 v[6:9], v[224:227], v[142:145], v[6:9]
	v_mfma_f32_16x16x32_bf16 v[2:5], v[198:201], v[142:145], v[2:5]
	v_mfma_f32_16x16x32_bf16 v[242:245], v[224:227], v[66:69], v[194:197]

	v_add_u32_e32 v166, 0xe0, v218
	v_min_i32_e32 v166, 0x7f8, v166
	v_ashrrev_i32_e32 v167, 31, v166
	v_lshl_add_u64 v[194:195], v[166:167], 1, s[10:11]
	global_load_dwordx4 v[166:169], v[194:195], off
	global_load_dword v220, v[194:195], off offset:-4
	s_waitcnt vmcnt(4)
	v_perm_b32 v222, v236, v228, s67
	v_perm_b32 v223, v228, v229, s67
	v_perm_b32 v224, v229, v230, s67
	v_perm_b32 v225, v230, v231, s67

; #define CONV_BLOCK(DO0, DO1) do { CONV_STEP(0, DO0, DO1); CONV_STEP(1, DO0, DO1); CONV_STEP(2, DO0, DO1); CONV_STEP(3, DO0, DO1); CONV_STEP(4, DO0, DO1); CONV_STEP(5, DO0, DO1); CONV_STEP(6, DO0, DO1); CONV_STEP(7, DO0, DO1); } while (0)
; template <bool PROMPT, int HALF>
; __device__ __forceinline__ void conv_item(unsigned char* ws, KArgs ka, int ib, int oct, int g, LAS unsigned char* lds, int tid, int lane, int wave) {
;     ...
;     for (int e = E1; e < E2; e += 8) CONV_BLOCK(true, true);
;     for (int e = E2; e < E3; e += 8) CONV_BLOCK(true, false);
	s_add_i32 s23, s19, 23
	s_ashr_i32 s23, s23, 3
	v_mfma_f32_16x16x32_bf16 v[194:197], v[228:231], v[66:69], v[232:235]
	s_add_i32 s30, s22, 0x3c0
	s_and_b32 s30, s30, 0x1c0
	v_mfma_f32_16x16x32_bf16 v[190:193], v[222:225], v[66:69], v[190:193]
	v_add_u32_e32 v66, s23, v216
	v_add_u32_e32 v67, s23, v217
	v_cmp_gt_u32_e32 vcc, 8, v66
	v_mfma_f32_16x16x32_bf16 v[138:141], v[228:231], v[158:161], v[138:141]
	s_nop 0
	v_cndmask_b32_e32 v66, v214, v66, vcc
	v_cmp_gt_u32_e32 vcc, 8, v67
	v_mul_lo_u32 v66, v66, s58
	v_mfma_f32_16x16x32_bf16 v[130:133], v[222:225], v[158:161], v[130:133]
	v_cndmask_b32_e32 v67, v214, v67, vcc
	v_mul_lo_u32 v67, v67, s58
	v_add3_u32 v66, v0, v66, s30
	v_add3_u32 v158, v0, v67, s30
	ds_read_b128 v[66:69], v66
	ds_read_b128 v[158:161], v158
	v_mfma_f32_16x16x32_bf16 v[198:201], v[228:231], v[154:157], v[242:245]
	v_mfma_f32_16x16x32_bf16 v[182:185], v[222:225], v[154:157], v[182:185]
	v_mfma_f32_16x16x32_bf16 v[122:125], v[228:231], v[74:77], v[122:125]
	v_mfma_f32_16x16x32_bf16 v[118:121], v[222:225], v[74:77], v[118:121]
	v_mfma_f32_16x16x32_bf16 v[186:189], v[228:231], v[146:149], v[186:189]
	v_mfma_f32_16x16x32_bf16 v[174:177], v[222:225], v[146:149], v[174:177]
	v_mfma_f32_16x16x32_bf16 v[114:117], v[228:231], v[82:85], v[114:117]
	v_mfma_f32_16x16x32_bf16 v[106:109], v[222:225], v[82:85], v[106:109]
	v_mfma_f32_16x16x32_bf16 v[178:181], v[228:231], v[134:137], v[178:181]
	v_mfma_f32_16x16x32_bf16 v[170:173], v[222:225], v[134:137], v[170:173]
	v_mfma_f32_16x16x32_bf16 v[98:101], v[228:231], v[90:93], v[98:101]
	v_mfma_f32_16x16x32_bf16 v[94:97], v[222:225], v[90:93], v[94:97]
	v_mfma_f32_16x16x32_bf16 v[62:65], v[228:231], v[110:113], v[62:65]
	v_mfma_f32_16x16x32_bf16 v[54:57], v[222:225], v[110:113], v[54:57]
	v_mfma_f32_16x16x32_bf16 v[30:33], v[228:231], v[102:105], v[30:33]
	v_mfma_f32_16x16x32_bf16 v[26:29], v[222:225], v[102:105], v[26:29]
	v_mfma_f32_16x16x32_bf16 v[58:61], v[228:231], v[86:89], v[58:61]
	v_mfma_f32_16x16x32_bf16 v[46:49], v[222:225], v[86:89], v[46:49]
	v_mfma_f32_16x16x32_bf16 v[22:25], v[228:231], v[126:129], v[22:25]
	v_mfma_f32_16x16x32_bf16 v[18:21], v[222:225], v[126:129], v[18:21]
	v_mfma_f32_16x16x32_bf16 v[50:53], v[228:231], v[78:81], v[50:53]
	v_mfma_f32_16x16x32_bf16 v[38:41], v[222:225], v[78:81], v[38:41]
	v_mfma_f32_16x16x32_bf16 v[14:17], v[228:231], v[142:145], v[14:17]
	v_mfma_f32_16x16x32_bf16 v[10:13], v[222:225], v[142:145], v[10:13]
	s_waitcnt lgkmcnt(3)
	v_mfma_f32_16x16x32_bf16 v[42:45], v[228:231], v[70:73], v[42:45]
	v_mfma_f32_16x16x32_bf16 v[34:37], v[222:225], v[70:73], v[34:37]
	s_waitcnt lgkmcnt(2)
	v_mfma_f32_16x16x32_bf16 v[6:9], v[228:231], v[150:153], v[6:9]
	v_mfma_f32_16x16x32_bf16 v[2:5], v[222:225], v[150:153], v[2:5]
	s_nop 0
	s_add_i32 s19, s19, 8
	s_addk_i32 s22, 0x200
	s_cmp_lt_i32 s19, 25
	v_add_u32_e32 v218, 0x100, v218
	s_cbranch_scc1 .LBB0_732
	v_add_u32_e32 v90, 6, v216
	v_add_u32_e32 v91, 0x540, v215
	s_mov_b32 s19, 25
.LBB0_734:
	v_add_u32_e32 v74, 0xffffff20, v91
	v_min_i32_e32 v74, 0x7f8, v74
	v_ashrrev_i32_e32 v75, 31, v74
	v_lshl_add_u64 v[74:75], v[74:75], 1, s[10:11]
	global_load_dwordx4 v[102:105], v[74:75], off
	global_load_dword v210, v[74:75], off offset:-4
	s_waitcnt vmcnt(4)
	v_perm_b32 v82, v219, v162, s67
	v_perm_b32 v83, v162, v163, s67
	v_perm_b32 v84, v163, v164, s67
	v_perm_b32 v85, v164, v165, s67

	v_add_u32_e32 v74, -1, v90
	v_cmp_gt_u32_e32 vcc, 8, v74
	v_mfma_f32_16x16x32_bf16 v[174:177], v[82:85], v[134:137], v[174:177]
	s_nop 0
	v_cndmask_b32_e32 v74, v214, v74, vcc
	v_mad_u64_u32 v[92:93], s[22:23], v74, s58, v[0:1]
	v_mfma_f32_16x16x32_bf16 v[178:181], v[162:165], v[110:113], v[178:181]
	ds_read_b128 v[74:77], v92 offset:64
	v_mfma_f32_16x16x32_bf16 v[170:173], v[82:85], v[110:113], v[170:173]
	v_mfma_f32_16x16x32_bf16 v[62:65], v[162:165], v[86:89], v[62:65]
	v_mfma_f32_16x16x32_bf16 v[54:57], v[82:85], v[86:89], v[54:57]
	v_mfma_f32_16x16x32_bf16 v[58:61], v[162:165], v[78:81], v[58:61]
	v_mfma_f32_16x16x32_bf16 v[46:49], v[82:85], v[78:81], v[46:49]
	v_mfma_f32_16x16x32_bf16 v[50:53], v[162:165], v[70:73], v[50:53]
	v_mfma_f32_16x16x32_bf16 v[38:41], v[82:85], v[70:73], v[38:41]
	s_waitcnt lgkmcnt(2)
	v_mfma_f32_16x16x32_bf16 v[42:45], v[162:165], v[66:69], v[42:45]
	v_mfma_f32_16x16x32_bf16 v[34:37], v[82:85], v[66:69], v[34:37]
	v_mfma_f32_16x16x32_bf16 v[126:129], v[82:85], v[154:157], v[190:193]
	v_mfma_f32_16x16x32_bf16 v[142:145], v[162:165], v[146:149], v[198:201]
	v_mfma_f32_16x16x32_bf16 v[150:153], v[82:85], v[146:149], v[182:185]
	s_waitcnt lgkmcnt(1)
	v_mfma_f32_16x16x32_bf16 v[158:161], v[162:165], v[134:137], v[186:189]

	v_add_u32_e32 v82, 0xffffff40, v91
	v_min_i32_e32 v82, 0x7f8, v82
	v_ashrrev_i32_e32 v83, 31, v82
	v_lshl_add_u64 v[82:83], v[82:83], 1, s[10:11]
	global_load_dwordx4 v[182:185], v[82:83], off
	global_load_dword v93, v[82:83], off offset:-4
	s_waitcnt vmcnt(4)
	v_perm_b32 v82, v220, v166, s67
	v_perm_b32 v83, v166, v167, s67
	v_perm_b32 v84, v167, v168, s67
	v_perm_b32 v85, v168, v169, s67
	s_nop 1

	v_mfma_f32_16x16x32_bf16 v[126:129], v[82:85], v[146:149], v[126:129]
	v_mfma_f32_16x16x32_bf16 v[150:153], v[82:85], v[134:137], v[150:153]
	v_mfma_f32_16x16x32_bf16 v[174:177], v[82:85], v[110:113], v[174:177]
	v_mfma_f32_16x16x32_bf16 v[178:181], v[166:169], v[86:89], v[178:181]
	v_mfma_f32_16x16x32_bf16 v[170:173], v[82:85], v[86:89], v[170:173]
	v_mfma_f32_16x16x32_bf16 v[62:65], v[166:169], v[78:81], v[62:65]
	v_mfma_f32_16x16x32_bf16 v[54:57], v[82:85], v[78:81], v[54:57]
	v_mfma_f32_16x16x32_bf16 v[58:61], v[166:169], v[70:73], v[58:61]
	v_mfma_f32_16x16x32_bf16 v[46:49], v[82:85], v[70:73], v[46:49]
	v_mfma_f32_16x16x32_bf16 v[50:53], v[166:169], v[66:69], v[50:53]
	v_mfma_f32_16x16x32_bf16 v[38:41], v[82:85], v[66:69], v[38:41]
	s_waitcnt lgkmcnt(0)
	v_mfma_f32_16x16x32_bf16 v[42:45], v[166:169], v[74:77], v[42:45]
	v_mfma_f32_16x16x32_bf16 v[34:37], v[82:85], v[74:77], v[34:37]
	ds_read_b128 v[82:85], v92 offset:128
	v_mfma_f32_16x16x32_bf16 v[154:157], v[162:165], v[154:157], v[194:197]
	v_mfma_f32_16x16x32_bf16 v[142:145], v[166:169], v[134:137], v[142:145]
	v_mfma_f32_16x16x32_bf16 v[158:161], v[166:169], v[110:113], v[158:161]

	v_add_u32_e32 v162, 0xffffff60, v91
	v_min_i32_e32 v162, 0x7f8, v162
	v_ashrrev_i32_e32 v163, 31, v162
	v_lshl_add_u64 v[186:187], v[162:163], 1, s[10:11]
	global_load_dwordx4 v[162:165], v[186:187], off
	global_load_dword v190, v[186:187], off offset:-4
	s_waitcnt vmcnt(4)
	v_perm_b32 v186, v210, v102, s67
	v_perm_b32 v187, v102, v103, s67
	v_perm_b32 v188, v103, v104, s67
	v_perm_b32 v189, v104, v105, s67
	s_nop 1

	v_mfma_f32_16x16x32_bf16 v[174:177], v[186:189], v[86:89], v[174:177]
	ds_read_b128 v[222:225], v92 offset:192
	v_mfma_f32_16x16x32_bf16 v[178:181], v[102:105], v[78:81], v[178:181]
	v_mfma_f32_16x16x32_bf16 v[170:173], v[186:189], v[78:81], v[170:173]
	v_mfma_f32_16x16x32_bf16 v[62:65], v[102:105], v[70:73], v[62:65]
	v_mfma_f32_16x16x32_bf16 v[54:57], v[186:189], v[70:73], v[54:57]
	v_mfma_f32_16x16x32_bf16 v[58:61], v[102:105], v[66:69], v[58:61]
	v_mfma_f32_16x16x32_bf16 v[46:49], v[186:189], v[66:69], v[46:49]
	v_mfma_f32_16x16x32_bf16 v[50:53], v[102:105], v[74:77], v[50:53]
	v_mfma_f32_16x16x32_bf16 v[38:41], v[186:189], v[74:77], v[38:41]
	s_waitcnt lgkmcnt(1)
	v_mfma_f32_16x16x32_bf16 v[42:45], v[102:105], v[82:85], v[42:45]
	v_mfma_f32_16x16x32_bf16 v[34:37], v[186:189], v[82:85], v[34:37]
	v_mfma_f32_16x16x32_bf16 v[146:149], v[166:169], v[146:149], v[154:157]
	v_mfma_f32_16x16x32_bf16 v[126:129], v[186:189], v[134:137], v[126:129]
	v_mfma_f32_16x16x32_bf16 v[142:145], v[102:105], v[110:113], v[142:145]
	v_mfma_f32_16x16x32_bf16 v[150:153], v[186:189], v[110:113], v[150:153]
	v_mfma_f32_16x16x32_bf16 v[158:161], v[102:105], v[86:89], v[158:161]

	v_add_u32_e32 v154, 0xffffff80, v91
	v_min_i32_e32 v154, 0x7f8, v154
	v_ashrrev_i32_e32 v155, 31, v154
	v_lshl_add_u64 v[166:167], v[154:155], 1, s[10:11]
	global_load_dwordx4 v[154:157], v[166:167], off
	global_load_dword v186, v[166:167], off offset:-4
	s_waitcnt vmcnt(4)
	v_perm_b32 v166, v93, v182, s67
	v_perm_b32 v167, v182, v183, s67
	v_perm_b32 v168, v183, v184, s67
	v_perm_b32 v169, v184, v185, s67
	s_nop 1

	v_mfma_f32_16x16x32_bf16 v[174:177], v[166:169], v[78:81], v[174:177]
	ds_read_b128 v[226:229], v92 offset:256
	v_mfma_f32_16x16x32_bf16 v[178:181], v[182:185], v[70:73], v[178:181]
	v_mfma_f32_16x16x32_bf16 v[170:173], v[166:169], v[70:73], v[170:173]
	v_mfma_f32_16x16x32_bf16 v[62:65], v[182:185], v[66:69], v[62:65]
	v_mfma_f32_16x16x32_bf16 v[54:57], v[166:169], v[66:69], v[54:57]
	v_mfma_f32_16x16x32_bf16 v[58:61], v[182:185], v[74:77], v[58:61]
	v_mfma_f32_16x16x32_bf16 v[46:49], v[166:169], v[74:77], v[46:49]
	v_mfma_f32_16x16x32_bf16 v[50:53], v[182:185], v[82:85], v[50:53]
	v_mfma_f32_16x16x32_bf16 v[38:41], v[166:169], v[82:85], v[38:41]
	s_waitcnt lgkmcnt(1)
	v_mfma_f32_16x16x32_bf16 v[42:45], v[182:185], v[222:225], v[42:45]
	v_mfma_f32_16x16x32_bf16 v[34:37], v[166:169], v[222:225], v[34:37]
	v_mfma_f32_16x16x32_bf16 v[126:129], v[166:169], v[110:113], v[126:129]
	v_mfma_f32_16x16x32_bf16 v[142:145], v[182:185], v[86:89], v[142:145]
	v_mfma_f32_16x16x32_bf16 v[150:153], v[166:169], v[86:89], v[150:153]
	v_mfma_f32_16x16x32_bf16 v[158:161], v[182:185], v[78:81], v[158:161]
	v_mfma_f32_16x16x32_bf16 v[102:105], v[102:105], v[134:137], v[146:149]

	v_add_u32_e32 v93, 0xffffffa0, v91
	v_min_i32_e32 v134, 0x7f8, v93
	v_ashrrev_i32_e32 v135, 31, v134
	v_lshl_add_u64 v[146:147], v[134:135], 1, s[10:11]
	global_load_dwordx4 v[134:137], v[146:147], off
	global_load_dword v93, v[146:147], off offset:-4
	s_waitcnt vmcnt(4)
	v_perm_b32 v146, v190, v162, s67
	v_perm_b32 v147, v162, v163, s67
	v_perm_b32 v148, v163, v164, s67
	v_perm_b32 v149, v164, v165, s67
	s_nop 1

	v_mfma_f32_16x16x32_bf16 v[126:129], v[146:149], v[86:89], v[126:129]
	v_mfma_f32_16x16x32_bf16 v[150:153], v[146:149], v[78:81], v[150:153]
	v_mfma_f32_16x16x32_bf16 v[166:169], v[146:149], v[70:73], v[174:177]
	v_mfma_f32_16x16x32_bf16 v[170:173], v[146:149], v[66:69], v[170:173]
	v_mfma_f32_16x16x32_bf16 v[54:57], v[146:149], v[74:77], v[54:57]
	v_mfma_f32_16x16x32_bf16 v[46:49], v[146:149], v[82:85], v[46:49]
	v_mfma_f32_16x16x32_bf16 v[38:41], v[146:149], v[222:225], v[38:41]
	s_waitcnt lgkmcnt(0)
	v_mfma_f32_16x16x32_bf16 v[34:37], v[146:149], v[226:229], v[34:37]
	ds_read_b128 v[146:149], v92 offset:320
	v_mfma_f32_16x16x32_bf16 v[174:177], v[162:165], v[66:69], v[178:181]
	v_mfma_f32_16x16x32_bf16 v[62:65], v[162:165], v[74:77], v[62:65]
	v_mfma_f32_16x16x32_bf16 v[58:61], v[162:165], v[82:85], v[58:61]
	v_mfma_f32_16x16x32_bf16 v[50:53], v[162:165], v[222:225], v[50:53]
	v_mfma_f32_16x16x32_bf16 v[42:45], v[162:165], v[226:229], v[42:45]
	v_mfma_f32_16x16x32_bf16 v[142:145], v[162:165], v[78:81], v[142:145]
	v_mfma_f32_16x16x32_bf16 v[158:161], v[162:165], v[70:73], v[158:161]
	v_mfma_f32_16x16x32_bf16 v[102:105], v[182:185], v[110:113], v[102:105]

	v_subrev_u32_e32 v110, 64, v91
	v_min_i32_e32 v110, 0x7f8, v110
	v_ashrrev_i32_e32 v111, 31, v110
	v_lshl_add_u64 v[178:179], v[110:111], 1, s[10:11]
	global_load_dwordx4 v[110:113], v[178:179], off
	global_load_dword v182, v[178:179], off offset:-4
	s_waitcnt vmcnt(4)
	v_perm_b32 v178, v186, v154, s67
	v_perm_b32 v179, v154, v155, s67
	v_perm_b32 v180, v155, v156, s67
	v_perm_b32 v181, v156, v157, s67
	s_nop 1

	v_mfma_f32_16x16x32_bf16 v[166:169], v[178:181], v[66:69], v[166:169]
	ds_read_b128 v[230:233], v92 offset:384
	v_mfma_f32_16x16x32_bf16 v[174:177], v[154:157], v[74:77], v[174:177]
	v_mfma_f32_16x16x32_bf16 v[170:173], v[178:181], v[74:77], v[170:173]
	v_mfma_f32_16x16x32_bf16 v[62:65], v[154:157], v[82:85], v[62:65]
	v_mfma_f32_16x16x32_bf16 v[54:57], v[178:181], v[82:85], v[54:57]
	v_mfma_f32_16x16x32_bf16 v[58:61], v[154:157], v[222:225], v[58:61]
	v_mfma_f32_16x16x32_bf16 v[46:49], v[178:181], v[222:225], v[46:49]
	v_mfma_f32_16x16x32_bf16 v[50:53], v[154:157], v[226:229], v[50:53]
	v_mfma_f32_16x16x32_bf16 v[38:41], v[178:181], v[226:229], v[38:41]
	s_waitcnt lgkmcnt(1)
	v_mfma_f32_16x16x32_bf16 v[42:45], v[154:157], v[146:149], v[42:45]
	v_mfma_f32_16x16x32_bf16 v[34:37], v[178:181], v[146:149], v[34:37]
	v_mfma_f32_16x16x32_bf16 v[86:89], v[162:165], v[86:89], v[102:105]
	v_mfma_f32_16x16x32_bf16 v[126:129], v[178:181], v[78:81], v[126:129]
	v_mfma_f32_16x16x32_bf16 v[142:145], v[154:157], v[70:73], v[142:145]
	v_mfma_f32_16x16x32_bf16 v[150:153], v[178:181], v[70:73], v[150:153]
	v_mfma_f32_16x16x32_bf16 v[158:161], v[154:157], v[66:69], v[158:161]

	v_subrev_u32_e32 v102, 32, v91
	v_min_i32_e32 v102, 0x7f8, v102
	v_ashrrev_i32_e32 v103, 31, v102
	v_lshl_add_u64 v[102:103], v[102:103], 1, s[10:11]
	global_load_dwordx4 v[162:165], v[102:103], off
	global_load_dword v219, v[102:103], off offset:-4
	s_waitcnt vmcnt(4)
	v_perm_b32 v102, v93, v134, s67
	v_perm_b32 v103, v134, v135, s67
	v_perm_b32 v104, v135, v136, s67
	v_perm_b32 v105, v136, v137, s67
	s_nop 1

	v_mfma_f32_16x16x32_bf16 v[126:129], v[102:105], v[70:73], v[126:129]
	v_mfma_f32_16x16x32_bf16 v[150:153], v[102:105], v[66:69], v[150:153]
	v_mfma_f32_16x16x32_bf16 v[178:181], v[102:105], v[74:77], v[166:169]
	v_mfma_f32_16x16x32_bf16 v[194:197], v[134:137], v[82:85], v[174:177]
	v_mfma_f32_16x16x32_bf16 v[170:173], v[102:105], v[82:85], v[170:173]
	v_mfma_f32_16x16x32_bf16 v[62:65], v[134:137], v[222:225], v[62:65]
	v_mfma_f32_16x16x32_bf16 v[54:57], v[102:105], v[222:225], v[54:57]
	v_mfma_f32_16x16x32_bf16 v[58:61], v[134:137], v[226:229], v[58:61]
	v_mfma_f32_16x16x32_bf16 v[46:49], v[102:105], v[226:229], v[46:49]
	v_mfma_f32_16x16x32_bf16 v[50:53], v[134:137], v[146:149], v[50:53]
	v_mfma_f32_16x16x32_bf16 v[38:41], v[102:105], v[146:149], v[38:41]
	s_waitcnt lgkmcnt(0)
	v_mfma_f32_16x16x32_bf16 v[42:45], v[134:137], v[230:233], v[42:45]
	v_mfma_f32_16x16x32_bf16 v[34:37], v[102:105], v[230:233], v[34:37]
	ds_read_b128 v[102:105], v92 offset:448
	v_mfma_f32_16x16x32_bf16 v[78:81], v[154:157], v[78:81], v[86:89]
	v_mfma_f32_16x16x32_bf16 v[142:145], v[134:137], v[66:69], v[142:145]
	v_mfma_f32_16x16x32_bf16 v[158:161], v[134:137], v[74:77], v[158:161]
	s_nop 0
	v_min_i32_e32 v86, 0x7f8, v91
	v_ashrrev_i32_e32 v87, 31, v86
	v_lshl_add_u64 v[86:87], v[86:87], 1, s[10:11]
	global_load_dwordx4 v[166:169], v[86:87], off
	global_load_dword v220, v[86:87], off offset:-4
	s_waitcnt vmcnt(4)
	v_perm_b32 v86, v182, v110, s67
	v_perm_b32 v87, v110, v111, s67
	v_perm_b32 v88, v111, v112, s67
	v_perm_b32 v89, v112, v113, s67

	v_cmp_gt_u32_e32 vcc, 8, v90
	v_mfma_f32_16x16x32_bf16 v[70:73], v[134:137], v[70:73], v[78:81]
	v_mfma_f32_16x16x32_bf16 v[190:193], v[86:89], v[66:69], v[126:129]
	v_mfma_f32_16x16x32_bf16 v[182:185], v[86:89], v[74:77], v[150:153]
	v_mfma_f32_16x16x32_bf16 v[174:177], v[86:89], v[82:85], v[178:181]
	v_mfma_f32_16x16x32_bf16 v[170:173], v[86:89], v[222:225], v[170:173]
	v_mfma_f32_16x16x32_bf16 v[54:57], v[86:89], v[226:229], v[54:57]
	v_mfma_f32_16x16x32_bf16 v[46:49], v[86:89], v[146:149], v[46:49]
	v_mfma_f32_16x16x32_bf16 v[38:41], v[86:89], v[230:233], v[38:41]
	s_waitcnt lgkmcnt(0)
	v_mfma_f32_16x16x32_bf16 v[34:37], v[86:89], v[102:105], v[34:37]
	v_cndmask_b32_e32 v86, v214, v90, vcc
	v_mad_u64_u32 v[78:79], s[22:23], v86, s58, v[0:1]
	ds_read_b128 v[78:81], v78
	v_mfma_f32_16x16x32_bf16 v[198:201], v[110:113], v[74:77], v[142:145]
	v_mfma_f32_16x16x32_bf16 v[186:189], v[110:113], v[82:85], v[158:161]
	v_mfma_f32_16x16x32_bf16 v[178:181], v[110:113], v[222:225], v[194:197]
	v_mfma_f32_16x16x32_bf16 v[62:65], v[110:113], v[226:229], v[62:65]
	v_mfma_f32_16x16x32_bf16 v[58:61], v[110:113], v[146:149], v[58:61]
	v_mfma_f32_16x16x32_bf16 v[50:53], v[110:113], v[230:233], v[50:53]
	v_mfma_f32_16x16x32_bf16 v[42:45], v[110:113], v[102:105], v[42:45]
	v_mfma_f32_16x16x32_bf16 v[194:197], v[110:113], v[66:69], v[70:73]

; #define CONV_BLOCK(DO0, DO1) do { CONV_STEP(0, DO0, DO1); CONV_STEP(1, DO0, DO1); CONV_STEP(2, DO0, DO1); CONV_STEP(3, DO0, DO1); CONV_STEP(4, DO0, DO1); CONV_STEP(5, DO0, DO1); CONV_STEP(6, DO0, DO1); CONV_STEP(7, DO0, DO1); } while (0)
; template <bool PROMPT, int HALF>
; __device__ __forceinline__ void conv_item(unsigned char* ws, KArgs ka, int ib, int oct, int g, LAS unsigned char* lds, int tid, int lane, int wave) {
;     ...
;     for (int e = E2; e < E3; e += 8) CONV_BLOCK(true, false);
;     ...
;     __syncthreads();
;     int lane2; { unsigned ones_ = ~0u; asm volatile("" : "+s"(ones_)); lane2 = (int)__builtin_amdgcn_mbcnt_hi(ones_, __builtin_amdgcn_mbcnt_lo(ones_, 0u)); }
;     const int nn2 = lane2 & 15, kq2 = lane2 >> 4;
;     float nsum = 0.f;
;     { const float* kq_ = (const float*)(ws + WS_KPART) + ((size_t)ib * 320 + (PROMPT ? 0 : 256)) * 2048; constexpr int ntile = PROMPT ? 256 : 64;
;       for (int q = lane2; q < ntile; q += 64) nsum += kq_[(size_t)q * 2048 + c] + kq_[(size_t)q * 2048 + 1024 + c];
	s_waitcnt lgkmcnt(0)
	v_mov_b64_e32 v[66:67], v[78:79]
	v_mov_b64_e32 v[86:87], v[146:147]
	s_add_i32 s19, s19, 8
	v_mov_b64_e32 v[68:69], v[80:81]
	v_mov_b64_e32 v[70:71], v[102:103]
	v_mov_b64_e32 v[78:79], v[230:231]
	v_mov_b64_e32 v[88:89], v[148:149]
	v_mov_b64_e32 v[110:111], v[226:227]
	v_mov_b64_e32 v[134:135], v[222:223]
	v_mov_b64_e32 v[148:149], v[84:85]
	v_mov_b64_e32 v[156:157], v[76:77]
	v_add_u32_e32 v90, 1, v90
	v_add_u32_e32 v91, 0x100, v91
	s_cmp_gt_u32 s19, 56
	v_mov_b64_e32 v[72:73], v[104:105]
	v_mov_b64_e32 v[80:81], v[232:233]
	v_mov_b64_e32 v[112:113], v[228:229]
	v_mov_b64_e32 v[136:137], v[224:225]
	v_mov_b64_e32 v[146:147], v[82:83]
	v_mov_b64_e32 v[154:155], v[74:75]
	s_cbranch_scc0 .LBB0_734
	s_mov_b32 s10, -1
	s_barrier
	s_nop 0
	v_mbcnt_lo_u32_b32 v0, s10, 0
	v_mbcnt_hi_u32_b32 v74, s10, v0
	v_cmp_gt_i32_e32 vcc, 64, v74
	v_mov_b32_e32 v0, 0
	s_and_saveexec_b64 s[10:11], vcc
	s_cbranch_execz .LBB0_739
	s_lshl_b32 s19, s34, 2
	s_and_b32 s19, s19, -8
	v_readlane_b32 s22, v253, 4
	s_add_i32 s30, s22, s19
	s_lshl_b64 s[22:23], s[30:31], 2
	s_add_u32 s22, s49, s22
	v_lshlrev_b32_e32 v0, 13, v74
	s_addc_u32 s23, s50, s23
	v_subrev_u32_e32 v68, 64, v74
	v_lshl_add_u64 v[66:67], s[22:23], 0, v[0:1]
	v_mov_b32_e32 v0, 0
	s_mov_b64 s[22:23], 0

.LBB0_751:
	v_min_i32_e32 v68, 0x1ff8, v66
	v_ashrrev_i32_e32 v69, 31, v68
	v_lshl_add_u64 v[72:73], v[68:69], 1, s[22:23]
	global_load_dwordx4 v[68:71], v[72:73], off
	global_load_dword v67, v[72:73], off offset:-4
	s_waitcnt vmcnt(8)
	v_perm_b32 v72, v125, v2, s67
	v_perm_b32 v73, v2, v3, s67
	v_perm_b32 v74, v3, v4, s67
	v_perm_b32 v75, v4, v5, s67

	s_add_i32 s43, s11, 16
	s_ashr_i32 s43, s43, 3
	v_add_u32_e32 v76, s43, v124
	v_min_u32_e32 v76, 32, v76
	v_mad_u32_u24 v76, v76, s58, v0
	v_mfma_f32_16x16x32_bf16 v[38:41], v[72:75], v[62:65], v[38:41]
	ds_read_b128 v[76:79], v76 offset:64
	v_mfma_f32_16x16x32_bf16 v[42:45], v[2:5], v[58:61], v[42:45]
	v_mfma_f32_16x16x32_bf16 v[34:37], v[72:75], v[58:61], v[34:37]
	v_mfma_f32_16x16x32_bf16 v[30:33], v[2:5], v[54:57], v[30:33]
	v_mfma_f32_16x16x32_bf16 v[26:29], v[72:75], v[54:57], v[26:29]
	s_waitcnt lgkmcnt(1)
	v_mfma_f32_16x16x32_bf16 v[22:25], v[2:5], v[50:53], v[22:25]
	v_mfma_f32_16x16x32_bf16 v[18:21], v[72:75], v[50:53], v[18:21]

	v_add_u32_e32 v72, 32, v66
	v_min_i32_e32 v72, 0x1ff8, v72
	v_ashrrev_i32_e32 v73, 31, v72
	v_lshl_add_u64 v[80:81], v[72:73], 1, s[22:23]
	global_load_dwordx4 v[72:75], v[80:81], off
	global_load_dword v96, v[80:81], off offset:-4
	s_waitcnt vmcnt(8)
	v_perm_b32 v80, v126, v6, s67
	v_perm_b32 v81, v6, v7, s67
	v_perm_b32 v82, v7, v8, s67
	v_perm_b32 v83, v8, v9, s67

	s_add_i32 s43, s11, 17
	s_ashr_i32 s43, s43, 3
	v_add_u32_e32 v84, s43, v124
	v_mfma_f32_16x16x32_bf16 v[38:41], v[80:83], v[58:61], v[38:41]
	v_mfma_f32_16x16x32_bf16 v[34:37], v[80:83], v[54:57], v[34:37]
	v_mfma_f32_16x16x32_bf16 v[26:29], v[80:83], v[50:53], v[26:29]
	s_waitcnt lgkmcnt(0)
	v_mfma_f32_16x16x32_bf16 v[18:21], v[80:83], v[76:79], v[18:21]
	v_min_u32_e32 v80, 32, v84
	v_mad_u32_u24 v80, v80, s58, v0
	ds_read_b128 v[80:83], v80 offset:128
	v_mfma_f32_16x16x32_bf16 v[42:45], v[6:9], v[54:57], v[42:45]
	v_mfma_f32_16x16x32_bf16 v[30:33], v[6:9], v[50:53], v[30:33]
	v_mfma_f32_16x16x32_bf16 v[22:25], v[6:9], v[76:79], v[22:25]
	v_mfma_f32_16x16x32_bf16 v[2:5], v[2:5], v[62:65], v[46:49]
	s_nop 0
	s_nop 1
	v_add_u32_e32 v46, 64, v66
	v_min_i32_e32 v46, 0x1ff8, v46
	v_ashrrev_i32_e32 v47, 31, v46
	v_lshl_add_u64 v[62:63], v[46:47], 1, s[22:23]
	global_load_dwordx4 v[46:49], v[62:63], off
	global_load_dword v97, v[62:63], off offset:-4
	s_waitcnt vmcnt(8)
	v_perm_b32 v62, v127, v10, s67
	v_perm_b32 v63, v10, v11, s67
	v_perm_b32 v64, v11, v12, s67
	v_perm_b32 v65, v12, v13, s67

	s_add_i32 s43, s11, 18
	s_ashr_i32 s43, s43, 3
	v_add_u32_e32 v84, s43, v124
	v_mfma_f32_16x16x32_bf16 v[38:41], v[62:65], v[54:57], v[38:41]
	v_mfma_f32_16x16x32_bf16 v[34:37], v[62:65], v[50:53], v[34:37]
	v_mfma_f32_16x16x32_bf16 v[26:29], v[62:65], v[76:79], v[26:29]
	s_waitcnt lgkmcnt(0)
	v_mfma_f32_16x16x32_bf16 v[18:21], v[62:65], v[80:83], v[18:21]
	v_min_u32_e32 v62, 32, v84
	v_mad_u32_u24 v62, v62, s58, v0
	ds_read_b128 v[84:87], v62 offset:192
	v_mfma_f32_16x16x32_bf16 v[42:45], v[10:13], v[50:53], v[42:45]
	v_mfma_f32_16x16x32_bf16 v[30:33], v[10:13], v[76:79], v[30:33]
	v_mfma_f32_16x16x32_bf16 v[22:25], v[10:13], v[80:83], v[22:25]
	v_mfma_f32_16x16x32_bf16 v[2:5], v[6:9], v[58:61], v[2:5]

	v_add_u32_e32 v6, 0x60, v66
	v_min_i32_e32 v6, 0x1ff8, v6
	v_ashrrev_i32_e32 v7, 31, v6
	v_lshl_add_u64 v[6:7], v[6:7], 1, s[22:23]
	global_load_dwordx4 v[88:91], v[6:7], off
	global_load_dword v98, v[6:7], off offset:-4
	s_waitcnt vmcnt(8)
	v_perm_b32 v6, v128, v14, s67
	v_perm_b32 v7, v14, v15, s67
	v_perm_b32 v8, v15, v16, s67
	v_perm_b32 v9, v16, v17, s67

	s_add_i32 s43, s11, 19
	s_ashr_i32 s43, s43, 3
	v_add_u32_e32 v58, s43, v124
	v_mfma_f32_16x16x32_bf16 v[38:41], v[6:9], v[50:53], v[38:41]
	v_mfma_f32_16x16x32_bf16 v[34:37], v[6:9], v[76:79], v[34:37]
	v_mfma_f32_16x16x32_bf16 v[26:29], v[6:9], v[80:83], v[26:29]
	s_waitcnt lgkmcnt(0)
	v_mfma_f32_16x16x32_bf16 v[6:9], v[6:9], v[84:87], v[18:21]
	s_nop 2
	v_min_u32_e32 v18, 32, v58
	v_mad_u32_u24 v18, v18, s58, v0
	v_mfma_f32_16x16x32_bf16 v[42:45], v[14:17], v[76:79], v[42:45]
	ds_read_b128 v[92:95], v18 offset:256
	v_mfma_f32_16x16x32_bf16 v[30:33], v[14:17], v[80:83], v[30:33]
	v_mfma_f32_16x16x32_bf16 v[22:25], v[14:17], v[84:87], v[22:25]
	v_mfma_f32_16x16x32_bf16 v[10:13], v[10:13], v[54:57], v[2:5]
	s_nop 0
	s_nop 1
	v_add_u32_e32 v2, 0x80, v66
	v_min_i32_e32 v2, 0x1ff8, v2
	v_ashrrev_i32_e32 v3, 31, v2
	v_lshl_add_u64 v[18:19], v[2:3], 1, s[22:23]
	global_load_dwordx4 v[2:5], v[18:19], off
	global_load_dword v125, v[18:19], off offset:-4
	s_waitcnt vmcnt(8)
	v_perm_b32 v18, v67, v68, s67
	v_perm_b32 v19, v68, v69, s67
	v_perm_b32 v20, v69, v70, s67
	v_perm_b32 v21, v70, v71, s67

	s_add_i32 s43, s11, 20
	s_ashr_i32 s43, s43, 3
	v_add_u32_e32 v54, s43, v124
	v_mfma_f32_16x16x32_bf16 v[38:41], v[18:21], v[76:79], v[38:41]
	v_mfma_f32_16x16x32_bf16 v[34:37], v[18:21], v[80:83], v[34:37]
	v_mfma_f32_16x16x32_bf16 v[26:29], v[18:21], v[84:87], v[26:29]
	s_waitcnt lgkmcnt(0)
	v_mfma_f32_16x16x32_bf16 v[18:21], v[18:21], v[92:95], v[6:9]
	s_nop 2
	v_min_u32_e32 v6, 32, v54
	v_mad_u32_u24 v6, v6, s58, v0
	ds_read_b128 v[62:65], v6 offset:320
	v_mfma_f32_16x16x32_bf16 v[42:45], v[68:71], v[80:83], v[42:45]
	v_mfma_f32_16x16x32_bf16 v[30:33], v[68:71], v[84:87], v[30:33]
	v_mfma_f32_16x16x32_bf16 v[22:25], v[68:71], v[92:95], v[22:25]
	v_mfma_f32_16x16x32_bf16 v[10:13], v[14:17], v[50:53], v[10:13]

	v_add_u32_e32 v6, 0xa0, v66
	v_min_i32_e32 v6, 0x1ff8, v6
	v_ashrrev_i32_e32 v7, 31, v6
	v_lshl_add_u64 v[14:15], v[6:7], 1, s[22:23]
	global_load_dwordx4 v[6:9], v[14:15], off
	global_load_dword v126, v[14:15], off offset:-4
	s_waitcnt vmcnt(8)
	v_perm_b32 v14, v96, v72, s67
	v_perm_b32 v15, v72, v73, s67
	v_perm_b32 v16, v73, v74, s67
	v_perm_b32 v17, v74, v75, s67

	s_add_i32 s43, s11, 21
	s_ashr_i32 s43, s43, 3
	v_add_u32_e32 v50, s43, v124
	v_mfma_f32_16x16x32_bf16 v[38:41], v[14:17], v[80:83], v[38:41]
	v_mfma_f32_16x16x32_bf16 v[34:37], v[14:17], v[84:87], v[34:37]
	v_mfma_f32_16x16x32_bf16 v[26:29], v[14:17], v[92:95], v[26:29]
	s_waitcnt lgkmcnt(0)
	v_mfma_f32_16x16x32_bf16 v[14:17], v[14:17], v[62:65], v[18:21]
	s_nop 2
	v_min_u32_e32 v18, 32, v50
	v_mad_u32_u24 v18, v18, s58, v0
	ds_read_b128 v[58:61], v18 offset:384
	v_mfma_f32_16x16x32_bf16 v[42:45], v[72:75], v[84:87], v[42:45]
	v_mfma_f32_16x16x32_bf16 v[30:33], v[72:75], v[92:95], v[30:33]
	v_mfma_f32_16x16x32_bf16 v[22:25], v[72:75], v[62:65], v[22:25]
	v_mfma_f32_16x16x32_bf16 v[18:21], v[68:71], v[76:79], v[10:13]
	s_nop 0
	s_nop 1
	v_add_u32_e32 v10, 0xc0, v66
	v_min_i32_e32 v10, 0x1ff8, v10
	v_ashrrev_i32_e32 v11, 31, v10
	v_lshl_add_u64 v[50:51], v[10:11], 1, s[22:23]
	global_load_dwordx4 v[10:13], v[50:51], off
	global_load_dword v127, v[50:51], off offset:-4
	s_waitcnt vmcnt(8)
	v_perm_b32 v50, v97, v46, s67
	v_perm_b32 v51, v46, v47, s67
	v_perm_b32 v52, v47, v48, s67
	v_perm_b32 v53, v48, v49, s67

	s_add_i32 s43, s11, 22
	s_ashr_i32 s43, s43, 3
	v_add_u32_e32 v54, s43, v124
	v_mfma_f32_16x16x32_bf16 v[38:41], v[50:53], v[84:87], v[38:41]
	v_mfma_f32_16x16x32_bf16 v[34:37], v[50:53], v[92:95], v[34:37]
	v_mfma_f32_16x16x32_bf16 v[26:29], v[50:53], v[62:65], v[26:29]
	s_waitcnt lgkmcnt(0)
	v_mfma_f32_16x16x32_bf16 v[50:53], v[50:53], v[58:61], v[14:17]
	s_nop 2
	v_min_u32_e32 v14, 32, v54
	v_mad_u32_u24 v14, v14, s58, v0
	ds_read_b128 v[54:57], v14 offset:448
	v_mfma_f32_16x16x32_bf16 v[42:45], v[46:49], v[92:95], v[42:45]
	v_mfma_f32_16x16x32_bf16 v[30:33], v[46:49], v[62:65], v[30:33]
	v_mfma_f32_16x16x32_bf16 v[22:25], v[46:49], v[58:61], v[22:25]
	v_mfma_f32_16x16x32_bf16 v[68:71], v[72:75], v[80:83], v[18:21]

	v_add_u32_e32 v14, 0xe0, v66
	v_min_i32_e32 v14, 0x1ff8, v14
	v_ashrrev_i32_e32 v15, 31, v14
	v_lshl_add_u64 v[18:19], v[14:15], 1, s[22:23]
	global_load_dwordx4 v[14:17], v[18:19], off
	global_load_dword v128, v[18:19], off offset:-4
	s_waitcnt vmcnt(8)
	v_perm_b32 v18, v98, v88, s67
	v_perm_b32 v19, v88, v89, s67
	v_perm_b32 v20, v89, v90, s67
	v_perm_b32 v21, v90, v91, s67

; #define CONV_BLOCK(DO0, DO1) do { CONV_STEP(0, DO0, DO1); CONV_STEP(1, DO0, DO1); CONV_STEP(2, DO0, DO1); CONV_STEP(3, DO0, DO1); CONV_STEP(4, DO0, DO1); CONV_STEP(5, DO0, DO1); CONV_STEP(6, DO0, DO1); CONV_STEP(7, DO0, DO1); } while (0)
; template <bool PROMPT, int HALF>
; __device__ __forceinline__ void conv_item(unsigned char* ws, KArgs ka, int ib, int oct, int g, LAS unsigned char* lds, int tid, int lane, int wave) {
;     ...
;     f32x4 acc[2][W][2];
; #pragma unroll
;     for (int r = 0; r < 2; ++r)
; #pragma unroll
;         for (int q = 0; q < W; ++q)
; #pragma unroll
;             for (int gg = 0; gg < 2; ++gg) acc[r][q][gg] = (f32x4){0.f, 0.f, 0.f, 0.f};
;     ...
;     { unsigned zz_ = 0u; asm volatile("" : "+v"(zz_));
; #pragma unroll
;       for (int k = 0; k < W; ++k) F0[k] = (u32x4){zz_, zz_, zz_, zz_}; }
;     for (int e = E1; e < E2; e += 8) CONV_BLOCK(true, true);
	s_add_i32 s43, s11, 23
	s_ashr_i32 s43, s43, 3
	v_mfma_f32_16x16x32_bf16 v[38:41], v[18:21], v[92:95], v[38:41]
	v_mfma_f32_16x16x32_bf16 v[34:37], v[18:21], v[62:65], v[34:37]
	v_mfma_f32_16x16x32_bf16 v[26:29], v[18:21], v[58:61], v[26:29]
	s_waitcnt lgkmcnt(0)
	v_mfma_f32_16x16x32_bf16 v[18:21], v[18:21], v[54:57], v[50:53]
	s_nop 2
	v_add_u32_e32 v50, s43, v124
	v_mfma_f32_16x16x32_bf16 v[46:49], v[46:49], v[84:87], v[68:71]
	v_min_u32_e32 v50, 32, v50
	v_mad_u32_u24 v50, v50, s58, v0
	ds_read_b128 v[50:53], v50
	v_mfma_f32_16x16x32_bf16 v[42:45], v[88:91], v[62:65], v[42:45]
	v_mfma_f32_16x16x32_bf16 v[30:33], v[88:91], v[58:61], v[30:33]
	v_mfma_f32_16x16x32_bf16 v[22:25], v[88:91], v[54:57], v[22:25]
	v_mfma_f32_16x16x32_bf16 v[46:49], v[88:91], v[92:95], v[46:49]
	s_nop 0
	s_add_i32 s11, s11, 8
	s_cmp_gt_u32 s11, 0xffffff70
	v_add_u32_e32 v66, 0x100, v66
	s_cbranch_scc0 .LBB0_751
	v_mov_b32_e32 v66, v1
	v_mov_b32_e32 v70, 0
	v_add_u32_e32 v129, 0xffffefa0, v123
	s_movk_i32 s11, 0xff71
	s_movk_i32 s43, 0xde40
	v_mov_b32_e32 v71, v70
	v_mov_b32_e32 v72, v70
	v_mov_b32_e32 v73, v70
	v_mov_b32_e32 v78, v70
	v_mov_b32_e32 v79, v70
	v_mov_b32_e32 v80, v70
	v_mov_b32_e32 v81, v70
	v_mov_b32_e32 v94, v70
	v_mov_b32_e32 v95, v70
	v_mov_b32_e32 v96, v70
	v_mov_b32_e32 v97, v70
	v_mov_b32_e32 v106, v70
	v_mov_b32_e32 v107, v70
	v_mov_b32_e32 v108, v70
	v_mov_b32_e32 v109, v70
	v_mov_b32_e32 v82, v70
	v_mov_b32_e32 v83, v70
	v_mov_b32_e32 v84, v70
	v_mov_b32_e32 v85, v70
	v_mov_b32_e32 v98, v70
	v_mov_b32_e32 v99, v70
	v_mov_b32_e32 v100, v70
	v_mov_b32_e32 v101, v70
	v_mov_b32_e32 v110, v70
	v_mov_b32_e32 v111, v70
	v_mov_b32_e32 v112, v70
	v_mov_b32_e32 v113, v70
	v_mov_b32_e32 v102, v70
	v_mov_b32_e32 v103, v70
	v_mov_b32_e32 v104, v70
	v_mov_b32_e32 v105, v70
	v_mov_b32_e32 v67, v66
	v_mov_b32_e32 v68, v66
	v_mov_b32_e32 v69, v66
	v_mov_b32_e32 v74, v66
	v_mov_b32_e32 v75, v66
	v_mov_b32_e32 v76, v66
	v_mov_b32_e32 v77, v66
	v_mov_b32_e32 v86, v66
	v_mov_b32_e32 v87, v66
	v_mov_b32_e32 v88, v66
	v_mov_b32_e32 v89, v66
	v_mov_b32_e32 v90, v66
	v_mov_b32_e32 v91, v66
	v_mov_b32_e32 v92, v66
	v_mov_b32_e32 v93, v66
.LBB0_753:
	v_min_i32_e32 v114, 0x1ff8, v129
	v_ashrrev_i32_e32 v115, 31, v114
	v_lshl_add_u64 v[114:115], v[114:115], 1, s[22:23]
	global_load_dwordx4 v[118:121], v[114:115], off
	global_load_dword v138, v[114:115], off offset:-4
	s_waitcnt vmcnt(8)
	v_perm_b32 v114, v125, v2, s67
	v_perm_b32 v115, v2, v3, s67
	v_perm_b32 v116, v3, v4, s67
	v_perm_b32 v117, v4, v5, s67

	s_add_i32 s54, s11, 16
	s_ashr_i32 s54, s54, 3
	v_mfma_f32_16x16x32_bf16 v[102:105], v[2:5], v[90:93], v[102:105]
	s_and_b32 s55, s43, 0x1c0
	v_mfma_f32_16x16x32_bf16 v[90:93], v[114:117], v[90:93], v[106:109]
	s_nop 2
	v_add_u32_e32 v106, s54, v122
	v_min_u32_e32 v106, 32, v106
	v_add_u32_e32 v107, s54, v124
	v_mul_u32_u24_e32 v106, 0x210, v106
	v_min_u32_e32 v107, 32, v107
	v_add3_u32 v106, v0, v106, s55
	v_mul_u32_u24_e32 v107, 0x210, v107
	v_mfma_f32_16x16x32_bf16 v[46:49], v[2:5], v[62:65], v[46:49]
	v_mfma_f32_16x16x32_bf16 v[38:41], v[114:117], v[62:65], v[38:41]
	v_mfma_f32_16x16x32_bf16 v[62:65], v[2:5], v[86:89], v[110:113]
	v_mfma_f32_16x16x32_bf16 v[42:45], v[2:5], v[58:61], v[42:45]
	v_mfma_f32_16x16x32_bf16 v[98:101], v[2:5], v[74:77], v[98:101]
	v_mfma_f32_16x16x32_bf16 v[30:33], v[2:5], v[54:57], v[30:33]
	s_waitcnt lgkmcnt(1)
	v_mfma_f32_16x16x32_bf16 v[82:85], v[2:5], v[66:69], v[82:85]
	s_waitcnt lgkmcnt(0)
	v_mfma_f32_16x16x32_bf16 v[2:5], v[2:5], v[50:53], v[22:25]
	s_nop 2
	v_add3_u32 v22, v0, v107, s55
	ds_read_b128 v[106:109], v106
	ds_read_b128 v[110:113], v22
	v_mfma_f32_16x16x32_bf16 v[94:97], v[114:117], v[86:89], v[94:97]
	v_mfma_f32_16x16x32_bf16 v[34:37], v[114:117], v[58:61], v[34:37]
	v_mfma_f32_16x16x32_bf16 v[78:81], v[114:117], v[74:77], v[78:81]
	v_mfma_f32_16x16x32_bf16 v[26:29], v[114:117], v[54:57], v[26:29]
	v_mfma_f32_16x16x32_bf16 v[70:73], v[114:117], v[66:69], v[70:73]
	v_mfma_f32_16x16x32_bf16 v[22:25], v[114:117], v[50:53], v[18:21]
	s_nop 0
	s_nop 1
	v_add_u32_e32 v18, 32, v129
	v_min_i32_e32 v18, 0x1ff8, v18
	v_ashrrev_i32_e32 v19, 31, v18
	v_lshl_add_u64 v[114:115], v[18:19], 1, s[22:23]
	global_load_dwordx4 v[18:21], v[114:115], off
	global_load_dword v139, v[114:115], off offset:-4
	s_waitcnt vmcnt(8)
	v_perm_b32 v114, v126, v6, s67
	v_perm_b32 v115, v6, v7, s67
	v_perm_b32 v116, v7, v8, s67
	v_perm_b32 v117, v8, v9, s67

	s_add_i32 s54, s11, 17
	s_ashr_i32 s54, s54, 3
	v_mfma_f32_16x16x32_bf16 v[46:49], v[6:9], v[58:61], v[46:49]
	s_add_i32 s55, s43, 0x240
	s_and_b32 s55, s55, 0x1c0
	v_mfma_f32_16x16x32_bf16 v[38:41], v[114:117], v[58:61], v[38:41]
	v_mfma_f32_16x16x32_bf16 v[58:61], v[6:9], v[74:77], v[62:65]
	v_mfma_f32_16x16x32_bf16 v[62:65], v[114:117], v[74:77], v[94:97]
	s_nop 2
	v_add_u32_e32 v94, s54, v122
	v_min_u32_e32 v94, 32, v94
	v_add_u32_e32 v95, s54, v124
	v_mul_u32_u24_e32 v94, 0x210, v94
	v_min_u32_e32 v95, 32, v95
	v_add3_u32 v94, v0, v94, s55
	v_mul_u32_u24_e32 v95, 0x210, v95
	v_mfma_f32_16x16x32_bf16 v[102:105], v[6:9], v[86:89], v[102:105]
	v_mfma_f32_16x16x32_bf16 v[86:89], v[114:117], v[86:89], v[90:93]
	v_mfma_f32_16x16x32_bf16 v[42:45], v[6:9], v[54:57], v[42:45]
	v_mfma_f32_16x16x32_bf16 v[90:93], v[6:9], v[66:69], v[98:101]
	v_mfma_f32_16x16x32_bf16 v[30:33], v[6:9], v[50:53], v[30:33]
	s_waitcnt lgkmcnt(1)
	v_mfma_f32_16x16x32_bf16 v[82:85], v[6:9], v[106:109], v[82:85]
	s_waitcnt lgkmcnt(0)
	v_mfma_f32_16x16x32_bf16 v[2:5], v[6:9], v[110:113], v[2:5]
	v_add3_u32 v6, v0, v95, s55
	ds_read_b128 v[94:97], v94
	ds_read_b128 v[98:101], v6
	v_mfma_f32_16x16x32_bf16 v[34:37], v[114:117], v[54:57], v[34:37]
	v_mfma_f32_16x16x32_bf16 v[78:81], v[114:117], v[66:69], v[78:81]
	v_mfma_f32_16x16x32_bf16 v[26:29], v[114:117], v[50:53], v[26:29]
	v_mfma_f32_16x16x32_bf16 v[70:73], v[114:117], v[106:109], v[70:73]
	v_mfma_f32_16x16x32_bf16 v[6:9], v[114:117], v[110:113], v[22:25]
	s_nop 0
	s_nop 1
	v_add_u32_e32 v22, 64, v129
	v_min_i32_e32 v22, 0x1ff8, v22
	v_ashrrev_i32_e32 v23, 31, v22
	v_lshl_add_u64 v[114:115], v[22:23], 1, s[22:23]
	global_load_dwordx4 v[22:25], v[114:115], off
	global_load_dword v140, v[114:115], off offset:-4
	s_waitcnt vmcnt(8)
	v_perm_b32 v114, v127, v10, s67
	v_perm_b32 v115, v10, v11, s67
	v_perm_b32 v116, v11, v12, s67
	v_perm_b32 v117, v12, v13, s67

	s_add_i32 s54, s11, 18
	s_ashr_i32 s54, s54, 3
	v_mfma_f32_16x16x32_bf16 v[102:105], v[10:13], v[74:77], v[102:105]
	s_add_i32 s55, s43, 0x280
	s_and_b32 s55, s55, 0x1c0
	v_mfma_f32_16x16x32_bf16 v[74:77], v[114:117], v[74:77], v[86:89]
	s_nop 2
	v_add_u32_e32 v86, s54, v122
	v_min_u32_e32 v86, 32, v86
	v_add_u32_e32 v87, s54, v124
	v_mul_u32_u24_e32 v86, 0x210, v86
	v_min_u32_e32 v87, 32, v87
	v_add3_u32 v86, v0, v86, s55
	v_mul_u32_u24_e32 v87, 0x210, v87
	v_mfma_f32_16x16x32_bf16 v[46:49], v[10:13], v[54:57], v[46:49]
	v_mfma_f32_16x16x32_bf16 v[38:41], v[114:117], v[54:57], v[38:41]
	v_mfma_f32_16x16x32_bf16 v[54:57], v[10:13], v[66:69], v[58:61]
	v_mfma_f32_16x16x32_bf16 v[58:61], v[114:117], v[66:69], v[62:65]
	v_mfma_f32_16x16x32_bf16 v[42:45], v[10:13], v[50:53], v[42:45]
	v_mfma_f32_16x16x32_bf16 v[62:65], v[10:13], v[106:109], v[90:93]
	v_mfma_f32_16x16x32_bf16 v[30:33], v[10:13], v[110:113], v[30:33]
	s_waitcnt lgkmcnt(1)
	v_mfma_f32_16x16x32_bf16 v[82:85], v[10:13], v[94:97], v[82:85]
	s_waitcnt lgkmcnt(0)
	v_mfma_f32_16x16x32_bf16 v[2:5], v[10:13], v[98:101], v[2:5]
	v_add3_u32 v10, v0, v87, s55
	ds_read_b128 v[130:133], v86
	ds_read_b128 v[134:137], v10
	v_mfma_f32_16x16x32_bf16 v[34:37], v[114:117], v[50:53], v[34:37]
	v_mfma_f32_16x16x32_bf16 v[78:81], v[114:117], v[106:109], v[78:81]
	v_mfma_f32_16x16x32_bf16 v[26:29], v[114:117], v[110:113], v[26:29]
	v_mfma_f32_16x16x32_bf16 v[70:73], v[114:117], v[94:97], v[70:73]
	v_mfma_f32_16x16x32_bf16 v[6:9], v[114:117], v[98:101], v[6:9]

	v_add_u32_e32 v10, 0x60, v129
	v_min_i32_e32 v10, 0x1ff8, v10
	v_ashrrev_i32_e32 v11, 31, v10
	v_lshl_add_u64 v[10:11], v[10:11], 1, s[22:23]
	global_load_dwordx4 v[114:117], v[10:11], off
	global_load_dword v142, v[10:11], off offset:-4
	s_waitcnt vmcnt(8)
	v_perm_b32 v10, v128, v14, s67
	v_perm_b32 v11, v14, v15, s67
	v_perm_b32 v12, v15, v16, s67
	v_perm_b32 v13, v16, v17, s67

	s_add_i32 s54, s11, 19
	s_ashr_i32 s54, s54, 3
	v_mfma_f32_16x16x32_bf16 v[86:89], v[14:17], v[66:69], v[102:105]
	s_add_i32 s55, s43, 0x2c0
	s_and_b32 s55, s55, 0x1c0
	v_mfma_f32_16x16x32_bf16 v[66:69], v[10:13], v[66:69], v[74:77]
	s_nop 2
	v_add_u32_e32 v74, s54, v122
	v_mfma_f32_16x16x32_bf16 v[46:49], v[14:17], v[50:53], v[46:49]
	v_min_u32_e32 v74, 32, v74
	v_mfma_f32_16x16x32_bf16 v[38:41], v[10:13], v[50:53], v[38:41]
	v_mfma_f32_16x16x32_bf16 v[50:53], v[14:17], v[106:109], v[54:57]
	v_mfma_f32_16x16x32_bf16 v[54:57], v[10:13], v[106:109], v[58:61]
	v_mfma_f32_16x16x32_bf16 v[58:61], v[14:17], v[94:97], v[62:65]
	v_mfma_f32_16x16x32_bf16 v[62:65], v[10:13], v[94:97], v[78:81]
	s_nop 2
	v_add_u32_e32 v79, s54, v124
	v_mul_u32_u24_e32 v78, 0x210, v74
	v_min_u32_e32 v79, 32, v79
	v_add3_u32 v78, v0, v78, s55
	v_mul_u32_u24_e32 v79, 0x210, v79
	v_mfma_f32_16x16x32_bf16 v[42:45], v[14:17], v[110:113], v[42:45]
	v_mfma_f32_16x16x32_bf16 v[30:33], v[14:17], v[98:101], v[30:33]
	s_waitcnt lgkmcnt(1)
	v_mfma_f32_16x16x32_bf16 v[74:77], v[14:17], v[130:133], v[82:85]
	s_waitcnt lgkmcnt(0)
	v_mfma_f32_16x16x32_bf16 v[14:17], v[14:17], v[134:137], v[2:5]
	s_nop 2
	v_add3_u32 v2, v0, v79, s55
	ds_read_b128 v[78:81], v78
	ds_read_b128 v[82:85], v2
	v_mfma_f32_16x16x32_bf16 v[34:37], v[10:13], v[110:113], v[34:37]
	v_mfma_f32_16x16x32_bf16 v[26:29], v[10:13], v[98:101], v[26:29]
	v_mfma_f32_16x16x32_bf16 v[70:73], v[10:13], v[130:133], v[70:73]
	v_mfma_f32_16x16x32_bf16 v[6:9], v[10:13], v[134:137], v[6:9]

	v_add_u32_e32 v2, 0x80, v129
	v_min_i32_e32 v2, 0x1ff8, v2
	v_ashrrev_i32_e32 v3, 31, v2
	v_lshl_add_u64 v[10:11], v[2:3], 1, s[22:23]
	global_load_dwordx4 v[2:5], v[10:11], off
	global_load_dword v125, v[10:11], off offset:-4
	s_waitcnt vmcnt(8)
	v_perm_b32 v10, v138, v118, s67
	v_perm_b32 v11, v118, v119, s67
	v_perm_b32 v12, v119, v120, s67
	v_perm_b32 v13, v120, v121, s67

	s_add_i32 s54, s11, 20
	s_ashr_i32 s54, s54, 3
	v_mfma_f32_16x16x32_bf16 v[102:105], v[10:13], v[130:133], v[62:65]
	s_add_i32 s55, s43, 0x300
	s_and_b32 s55, s55, 0x1c0
	s_nop 0
	v_add_u32_e32 v62, s54, v122
	v_add_u32_e32 v63, s54, v124
	v_min_u32_e32 v62, 32, v62
	v_min_u32_e32 v63, 32, v63
	v_mul_u32_u24_e32 v62, 0x210, v62
	v_mul_u32_u24_e32 v63, 0x210, v63
	v_add3_u32 v62, v0, v62, s55
	v_add3_u32 v63, v0, v63, s55
	ds_read_b128 v[90:93], v62
	ds_read_b128 v[62:65], v63
	v_mfma_f32_16x16x32_bf16 v[86:89], v[118:121], v[106:109], v[86:89]
	v_mfma_f32_16x16x32_bf16 v[66:69], v[10:13], v[106:109], v[66:69]
	v_mfma_f32_16x16x32_bf16 v[46:49], v[118:121], v[110:113], v[46:49]
	v_mfma_f32_16x16x32_bf16 v[38:41], v[10:13], v[110:113], v[38:41]
	v_mfma_f32_16x16x32_bf16 v[50:53], v[118:121], v[94:97], v[50:53]
	v_mfma_f32_16x16x32_bf16 v[54:57], v[10:13], v[94:97], v[54:57]
	v_mfma_f32_16x16x32_bf16 v[42:45], v[118:121], v[98:101], v[42:45]
	v_mfma_f32_16x16x32_bf16 v[34:37], v[10:13], v[98:101], v[34:37]
	v_mfma_f32_16x16x32_bf16 v[58:61], v[118:121], v[130:133], v[58:61]
	v_mfma_f32_16x16x32_bf16 v[30:33], v[118:121], v[134:137], v[30:33]
	v_mfma_f32_16x16x32_bf16 v[26:29], v[10:13], v[134:137], v[26:29]
	s_waitcnt lgkmcnt(3)
	v_mfma_f32_16x16x32_bf16 v[74:77], v[118:121], v[78:81], v[74:77]
	v_mfma_f32_16x16x32_bf16 v[70:73], v[10:13], v[78:81], v[70:73]
	s_waitcnt lgkmcnt(2)
	v_mfma_f32_16x16x32_bf16 v[14:17], v[118:121], v[82:85], v[14:17]
	v_mfma_f32_16x16x32_bf16 v[10:13], v[10:13], v[82:85], v[6:9]
	s_nop 0
	s_nop 1
	v_add_u32_e32 v6, 0xa0, v129
	v_min_i32_e32 v6, 0x1ff8, v6
	v_ashrrev_i32_e32 v7, 31, v6
	v_lshl_add_u64 v[106:107], v[6:7], 1, s[22:23]
	global_load_dwordx4 v[6:9], v[106:107], off
	global_load_dword v126, v[106:107], off offset:-4
	s_waitcnt vmcnt(8)
	v_perm_b32 v106, v139, v18, s67
	v_perm_b32 v107, v18, v19, s67
	v_perm_b32 v108, v19, v20, s67
	v_perm_b32 v109, v20, v21, s67

	s_add_i32 s54, s11, 21
	s_ashr_i32 s54, s54, 3
	v_mfma_f32_16x16x32_bf16 v[110:113], v[18:21], v[94:97], v[86:89]
	s_add_i32 s55, s43, 0x340
	s_and_b32 s55, s55, 0x1c0
	v_mfma_f32_16x16x32_bf16 v[66:69], v[106:109], v[94:97], v[66:69]
	v_mfma_f32_16x16x32_bf16 v[94:97], v[18:21], v[78:81], v[58:61]
	s_nop 2
	v_add_u32_e32 v58, s54, v122
	v_min_u32_e32 v58, 32, v58
	v_add_u32_e32 v59, s54, v124
	v_mul_u32_u24_e32 v58, 0x210, v58
	v_min_u32_e32 v59, 32, v59
	v_add3_u32 v58, v0, v58, s55
	v_mul_u32_u24_e32 v59, 0x210, v59
	v_mfma_f32_16x16x32_bf16 v[46:49], v[18:21], v[98:101], v[46:49]
	v_mfma_f32_16x16x32_bf16 v[50:53], v[18:21], v[130:133], v[50:53]
	v_mfma_f32_16x16x32_bf16 v[42:45], v[18:21], v[134:137], v[42:45]
	v_mfma_f32_16x16x32_bf16 v[30:33], v[18:21], v[82:85], v[30:33]
	s_waitcnt lgkmcnt(1)
	v_mfma_f32_16x16x32_bf16 v[74:77], v[18:21], v[90:93], v[74:77]
	s_waitcnt lgkmcnt(0)
	v_mfma_f32_16x16x32_bf16 v[14:17], v[18:21], v[62:65], v[14:17]
	v_add3_u32 v18, v0, v59, s55
	ds_read_b128 v[86:89], v58
	ds_read_b128 v[58:61], v18
	v_mfma_f32_16x16x32_bf16 v[38:41], v[106:109], v[98:101], v[38:41]
	v_mfma_f32_16x16x32_bf16 v[54:57], v[106:109], v[130:133], v[54:57]
	v_mfma_f32_16x16x32_bf16 v[34:37], v[106:109], v[134:137], v[34:37]
	v_mfma_f32_16x16x32_bf16 v[98:101], v[106:109], v[78:81], v[102:105]
	v_mfma_f32_16x16x32_bf16 v[26:29], v[106:109], v[82:85], v[26:29]
	v_mfma_f32_16x16x32_bf16 v[70:73], v[106:109], v[90:93], v[70:73]
	v_mfma_f32_16x16x32_bf16 v[18:21], v[106:109], v[62:65], v[10:13]
	s_nop 0
	s_nop 1
	v_add_u32_e32 v10, 0xc0, v129
	v_min_i32_e32 v10, 0x1ff8, v10
	v_ashrrev_i32_e32 v11, 31, v10
	v_lshl_add_u64 v[102:103], v[10:11], 1, s[22:23]
	global_load_dwordx4 v[10:13], v[102:103], off
	global_load_dword v127, v[102:103], off offset:-4
	s_waitcnt vmcnt(8)
	v_perm_b32 v102, v140, v22, s67
	v_perm_b32 v103, v22, v23, s67
	v_perm_b32 v104, v23, v24, s67
	v_perm_b32 v105, v24, v25, s67

	s_add_i32 s54, s11, 22
	s_ashr_i32 s54, s54, 3
	v_mfma_f32_16x16x32_bf16 v[118:121], v[102:105], v[78:81], v[54:57]
	s_add_i32 s55, s43, 0x380
	s_and_b32 s55, s55, 0x1c0
	s_nop 0
	v_add_u32_e32 v54, s54, v122
	v_min_u32_e32 v54, 32, v54
	v_add_u32_e32 v55, s54, v124
	v_mul_u32_u24_e32 v54, 0x210, v54
	v_min_u32_e32 v55, 32, v55
	v_add3_u32 v54, v0, v54, s55
	v_mul_u32_u24_e32 v55, 0x210, v55
	v_mfma_f32_16x16x32_bf16 v[106:109], v[22:25], v[130:133], v[110:113]
	v_mfma_f32_16x16x32_bf16 v[66:69], v[102:105], v[130:133], v[66:69]
	v_mfma_f32_16x16x32_bf16 v[46:49], v[22:25], v[134:137], v[46:49]
	v_mfma_f32_16x16x32_bf16 v[50:53], v[22:25], v[78:81], v[50:53]
	v_mfma_f32_16x16x32_bf16 v[42:45], v[22:25], v[82:85], v[42:45]
	v_mfma_f32_16x16x32_bf16 v[130:133], v[22:25], v[90:93], v[94:97]
	v_mfma_f32_16x16x32_bf16 v[30:33], v[22:25], v[62:65], v[30:33]
	s_waitcnt lgkmcnt(1)
	v_mfma_f32_16x16x32_bf16 v[138:141], v[22:25], v[86:89], v[74:77]
	s_waitcnt lgkmcnt(0)
	v_mfma_f32_16x16x32_bf16 v[22:25], v[22:25], v[58:61], v[14:17]
	s_nop 2
	v_add3_u32 v14, v0, v55, s55
	ds_read_b128 v[74:77], v54
	ds_read_b128 v[54:57], v14
	v_mfma_f32_16x16x32_bf16 v[38:41], v[102:105], v[134:137], v[38:41]
	v_mfma_f32_16x16x32_bf16 v[34:37], v[102:105], v[82:85], v[34:37]
	v_mfma_f32_16x16x32_bf16 v[26:29], v[102:105], v[62:65], v[26:29]
	v_mfma_f32_16x16x32_bf16 v[70:73], v[102:105], v[86:89], v[70:73]
	v_mfma_f32_16x16x32_bf16 v[18:21], v[102:105], v[58:61], v[18:21]
	v_mfma_f32_16x16x32_bf16 v[134:137], v[102:105], v[90:93], v[98:101]

	v_add_u32_e32 v14, 0xe0, v129
	v_min_i32_e32 v14, 0x1ff8, v14
	v_ashrrev_i32_e32 v15, 31, v14
	v_lshl_add_u64 v[94:95], v[14:15], 1, s[22:23]
	global_load_dwordx4 v[14:17], v[94:95], off
	global_load_dword v128, v[94:95], off offset:-4
	s_waitcnt vmcnt(8)
	v_perm_b32 v142, v142, v114, s67
	v_perm_b32 v143, v114, v115, s67
	v_perm_b32 v144, v115, v116, s67
	v_perm_b32 v145, v116, v117, s67

; #define CONV_BLOCK(DO0, DO1) do { CONV_STEP(0, DO0, DO1); CONV_STEP(1, DO0, DO1); CONV_STEP(2, DO0, DO1); CONV_STEP(3, DO0, DO1); CONV_STEP(4, DO0, DO1); CONV_STEP(5, DO0, DO1); CONV_STEP(6, DO0, DO1); CONV_STEP(7, DO0, DO1); } while (0)
; template <bool PROMPT, int HALF>
; __device__ __forceinline__ void conv_item(unsigned char* ws, KArgs ka, int ib, int oct, int g, LAS unsigned char* lds, int tid, int lane, int wave) {
;     ...
;     for (int e = E1; e < E2; e += 8) CONV_BLOCK(true, true);
;     for (int e = E2; e < E3; e += 8) CONV_BLOCK(true, false);
	s_add_i32 s54, s11, 23
	s_ashr_i32 s54, s54, 3
	v_mfma_f32_16x16x32_bf16 v[110:113], v[114:117], v[90:93], v[50:53]
	s_add_i32 s55, s43, 0x3c0
	s_and_b32 s55, s55, 0x1c0
	s_nop 0
	v_add_u32_e32 v50, s54, v122
	v_add_u32_e32 v51, s54, v124
	v_min_u32_e32 v50, 32, v50
	v_min_u32_e32 v51, 32, v51
	v_mul_u32_u24_e32 v50, 0x210, v50
	v_mul_u32_u24_e32 v51, 0x210, v51
	v_add3_u32 v50, v0, v50, s55
	v_add3_u32 v51, v0, v51, s55
	v_mfma_f32_16x16x32_bf16 v[102:105], v[114:117], v[78:81], v[106:109]
	v_mfma_f32_16x16x32_bf16 v[106:109], v[142:145], v[78:81], v[66:69]
	s_nop 2
	ds_read_b128 v[66:69], v50
	ds_read_b128 v[50:53], v51
	v_mfma_f32_16x16x32_bf16 v[46:49], v[114:117], v[82:85], v[46:49]
	v_mfma_f32_16x16x32_bf16 v[38:41], v[142:145], v[82:85], v[38:41]
	v_mfma_f32_16x16x32_bf16 v[94:97], v[142:145], v[90:93], v[118:121]
	v_mfma_f32_16x16x32_bf16 v[42:45], v[114:117], v[62:65], v[42:45]
	v_mfma_f32_16x16x32_bf16 v[34:37], v[142:145], v[62:65], v[34:37]
	v_mfma_f32_16x16x32_bf16 v[98:101], v[114:117], v[86:89], v[130:133]
	v_mfma_f32_16x16x32_bf16 v[78:81], v[142:145], v[86:89], v[134:137]
	v_mfma_f32_16x16x32_bf16 v[30:33], v[114:117], v[58:61], v[30:33]
	v_mfma_f32_16x16x32_bf16 v[26:29], v[142:145], v[58:61], v[26:29]
	s_waitcnt lgkmcnt(3)
	v_mfma_f32_16x16x32_bf16 v[82:85], v[114:117], v[74:77], v[138:141]
	v_mfma_f32_16x16x32_bf16 v[70:73], v[142:145], v[74:77], v[70:73]
	s_waitcnt lgkmcnt(2)
	v_mfma_f32_16x16x32_bf16 v[22:25], v[114:117], v[54:57], v[22:25]
	v_mfma_f32_16x16x32_bf16 v[18:21], v[142:145], v[54:57], v[18:21]
	s_nop 0
	s_add_i32 s11, s11, 8
	s_addk_i32 s43, 0x200
	s_cmpk_lt_i32 s11, 0x79
	v_add_u32_e32 v129, 0x100, v129
	s_cbranch_scc1 .LBB0_753
	s_waitcnt lgkmcnt(0)
	v_add_u32_e32 v50, 18, v122
	v_add_u32_e32 v51, 0x1180, v123
	s_movk_i32 s11, 0x79
.LBB0_755:
	v_add_u32_e32 v52, 0xffffff20, v51
	v_min_i32_e32 v52, 0x1ff8, v52
	v_ashrrev_i32_e32 v53, 31, v52
	v_lshl_add_u64 v[56:57], v[52:53], 1, s[22:23]
	global_load_dwordx4 v[52:55], v[56:57], off
	global_load_dword v122, v[56:57], off offset:-4
	s_waitcnt vmcnt(8)
	v_perm_b32 v56, v125, v2, s67
	v_perm_b32 v57, v2, v3, s67
	v_perm_b32 v58, v3, v4, s67
	v_perm_b32 v59, v4, v5, s67

	v_add_u32_e32 v64, -1, v50
	v_min_u32_e32 v64, 32, v64
	v_mad_u32_u24 v123, v64, s58, v0
	v_mfma_f32_16x16x32_bf16 v[60:63], v[56:59], v[90:93], v[106:109]
	v_mfma_f32_16x16x32_bf16 v[106:109], v[2:5], v[86:89], v[110:113]
	s_nop 2
	ds_read_b128 v[110:113], v123 offset:64
	v_mfma_f32_16x16x32_bf16 v[94:97], v[56:59], v[86:89], v[94:97]
	v_mfma_f32_16x16x32_bf16 v[98:101], v[2:5], v[74:77], v[98:101]
	v_mfma_f32_16x16x32_bf16 v[78:81], v[56:59], v[74:77], v[78:81]
	s_waitcnt lgkmcnt(1)
	v_mfma_f32_16x16x32_bf16 v[82:85], v[2:5], v[66:69], v[82:85]
	v_mfma_f32_16x16x32_bf16 v[56:59], v[56:59], v[66:69], v[70:73]

	v_add_u32_e32 v64, 0xffffff40, v51
	v_min_i32_e32 v64, 0x1ff8, v64
	v_ashrrev_i32_e32 v65, 31, v64
	v_lshl_add_u64 v[64:65], v[64:65], 1, s[22:23]
	global_load_dwordx4 v[70:73], v[64:65], off
	global_load_dword v124, v[64:65], off offset:-4
	s_waitcnt vmcnt(8)
	v_perm_b32 v114, v126, v6, s67
	v_perm_b32 v115, v6, v7, s67
	v_perm_b32 v116, v7, v8, s67
	v_perm_b32 v117, v8, v9, s67
	s_nop 1

	v_mfma_f32_16x16x32_bf16 v[60:63], v[114:117], v[86:89], v[60:63]
	v_mfma_f32_16x16x32_bf16 v[106:109], v[6:9], v[74:77], v[106:109]
	v_mfma_f32_16x16x32_bf16 v[94:97], v[114:117], v[74:77], v[94:97]
	v_mfma_f32_16x16x32_bf16 v[98:101], v[6:9], v[66:69], v[98:101]
	v_mfma_f32_16x16x32_bf16 v[78:81], v[114:117], v[66:69], v[78:81]
	s_waitcnt lgkmcnt(0)
	v_mfma_f32_16x16x32_bf16 v[82:85], v[6:9], v[110:113], v[82:85]
	v_mfma_f32_16x16x32_bf16 v[56:59], v[114:117], v[110:113], v[56:59]
	ds_read_b128 v[114:117], v123 offset:128
	v_mfma_f32_16x16x32_bf16 v[2:5], v[2:5], v[90:93], v[102:105]

	v_add_u32_e32 v64, 0xffffff60, v51
	v_min_i32_e32 v64, 0x1ff8, v64
	v_ashrrev_i32_e32 v65, 31, v64
	v_lshl_add_u64 v[64:65], v[64:65], 1, s[22:23]
	global_load_dwordx4 v[102:105], v[64:65], off
	global_load_dword v129, v[64:65], off offset:-4
	s_waitcnt vmcnt(8)
	v_perm_b32 v90, v127, v10, s67
	v_perm_b32 v91, v10, v11, s67
	v_perm_b32 v92, v11, v12, s67
	v_perm_b32 v93, v12, v13, s67

	v_mfma_f32_16x16x32_bf16 v[106:109], v[10:13], v[66:69], v[106:109]
	ds_read_b128 v[118:121], v123 offset:192
	v_mfma_f32_16x16x32_bf16 v[94:97], v[90:93], v[66:69], v[94:97]
	v_mfma_f32_16x16x32_bf16 v[98:101], v[10:13], v[110:113], v[98:101]
	v_mfma_f32_16x16x32_bf16 v[78:81], v[90:93], v[110:113], v[78:81]
	s_waitcnt lgkmcnt(1)
	v_mfma_f32_16x16x32_bf16 v[82:85], v[10:13], v[114:117], v[82:85]
	v_mfma_f32_16x16x32_bf16 v[2:5], v[6:9], v[86:89], v[2:5]
	v_mfma_f32_16x16x32_bf16 v[60:63], v[90:93], v[74:77], v[60:63]
	v_mfma_f32_16x16x32_bf16 v[56:59], v[90:93], v[114:117], v[56:59]

	v_add_u32_e32 v6, 0xffffff80, v51
	v_min_i32_e32 v6, 0x1ff8, v6
	v_ashrrev_i32_e32 v7, 31, v6
	v_lshl_add_u64 v[6:7], v[6:7], 1, s[22:23]
	global_load_dwordx4 v[130:133], v[6:7], off
	global_load_dword v142, v[6:7], off offset:-4
	s_waitcnt vmcnt(8)
	v_perm_b32 v6, v128, v14, s67
	v_perm_b32 v7, v14, v15, s67
	v_perm_b32 v8, v15, v16, s67
	v_perm_b32 v9, v16, v17, s67
	s_nop 1

	v_mfma_f32_16x16x32_bf16 v[60:63], v[6:9], v[66:69], v[60:63]
	v_mfma_f32_16x16x32_bf16 v[86:89], v[14:17], v[110:113], v[106:109]
	v_mfma_f32_16x16x32_bf16 v[90:93], v[6:9], v[110:113], v[94:97]
	v_mfma_f32_16x16x32_bf16 v[94:97], v[14:17], v[114:117], v[98:101]
	v_mfma_f32_16x16x32_bf16 v[78:81], v[6:9], v[114:117], v[78:81]
	s_waitcnt lgkmcnt(0)
	v_mfma_f32_16x16x32_bf16 v[82:85], v[14:17], v[118:121], v[82:85]
	v_mfma_f32_16x16x32_bf16 v[6:9], v[6:9], v[118:121], v[56:59]
	s_nop 2
	ds_read_b128 v[56:59], v123 offset:256
	v_mfma_f32_16x16x32_bf16 v[10:13], v[10:13], v[74:77], v[2:5]
	s_nop 0
	s_nop 1
	v_add_u32_e32 v2, 0xffffffa0, v51
	v_min_i32_e32 v2, 0x1ff8, v2
	v_ashrrev_i32_e32 v3, 31, v2
	v_lshl_add_u64 v[64:65], v[2:3], 1, s[22:23]
	global_load_dwordx4 v[2:5], v[64:65], off
	global_load_dword v125, v[64:65], off offset:-4
	s_waitcnt vmcnt(8)
	v_perm_b32 v74, v122, v52, s67
	v_perm_b32 v75, v52, v53, s67
	v_perm_b32 v76, v53, v54, s67
	v_perm_b32 v77, v54, v55, s67
	s_nop 1

	v_mfma_f32_16x16x32_bf16 v[98:101], v[74:77], v[114:117], v[90:93]
	s_nop 2
	ds_read_b128 v[90:93], v123 offset:320
	v_mfma_f32_16x16x32_bf16 v[60:63], v[74:77], v[110:113], v[60:63]
	v_mfma_f32_16x16x32_bf16 v[86:89], v[52:55], v[114:117], v[86:89]
	v_mfma_f32_16x16x32_bf16 v[94:97], v[52:55], v[118:121], v[94:97]
	v_mfma_f32_16x16x32_bf16 v[78:81], v[74:77], v[118:121], v[78:81]
	s_waitcnt lgkmcnt(1)
	v_mfma_f32_16x16x32_bf16 v[82:85], v[52:55], v[56:59], v[82:85]
	v_mfma_f32_16x16x32_bf16 v[74:77], v[74:77], v[56:59], v[6:9]
	v_mfma_f32_16x16x32_bf16 v[10:13], v[14:17], v[66:69], v[10:13]
	s_nop 0
	s_nop 0
	v_subrev_u32_e32 v6, 64, v51
	v_min_i32_e32 v6, 0x1ff8, v6
	v_ashrrev_i32_e32 v7, 31, v6
	v_lshl_add_u64 v[14:15], v[6:7], 1, s[22:23]
	global_load_dwordx4 v[6:9], v[14:15], off
	global_load_dword v126, v[14:15], off offset:-4
	s_waitcnt vmcnt(8)
	v_perm_b32 v14, v124, v70, s67
	v_perm_b32 v15, v70, v71, s67
	v_perm_b32 v16, v71, v72, s67
	v_perm_b32 v17, v72, v73, s67

	v_mfma_f32_16x16x32_bf16 v[64:67], v[70:73], v[118:121], v[86:89]
	s_nop 2
	ds_read_b128 v[86:89], v123 offset:384
	v_mfma_f32_16x16x32_bf16 v[60:63], v[14:17], v[114:117], v[60:63]
	v_mfma_f32_16x16x32_bf16 v[98:101], v[14:17], v[118:121], v[98:101]
	v_mfma_f32_16x16x32_bf16 v[94:97], v[70:73], v[56:59], v[94:97]
	v_mfma_f32_16x16x32_bf16 v[78:81], v[14:17], v[56:59], v[78:81]
	s_waitcnt lgkmcnt(1)
	v_mfma_f32_16x16x32_bf16 v[82:85], v[70:73], v[90:93], v[82:85]
	v_mfma_f32_16x16x32_bf16 v[14:17], v[14:17], v[90:93], v[74:77]
	v_mfma_f32_16x16x32_bf16 v[52:55], v[52:55], v[110:113], v[10:13]
	s_nop 0
	s_nop 1
	v_subrev_u32_e32 v10, 32, v51
	v_min_i32_e32 v10, 0x1ff8, v10
	v_ashrrev_i32_e32 v11, 31, v10
	v_lshl_add_u64 v[68:69], v[10:11], 1, s[22:23]
	global_load_dwordx4 v[10:13], v[68:69], off
	global_load_dword v127, v[68:69], off offset:-4
	s_waitcnt vmcnt(8)
	v_perm_b32 v74, v129, v102, s67
	v_perm_b32 v75, v102, v103, s67
	v_perm_b32 v76, v103, v104, s67
	v_perm_b32 v77, v104, v105, s67
	s_nop 1

	v_mfma_f32_16x16x32_bf16 v[60:63], v[74:77], v[118:121], v[60:63]
	v_mfma_f32_16x16x32_bf16 v[98:101], v[74:77], v[56:59], v[98:101]
	v_mfma_f32_16x16x32_bf16 v[78:81], v[74:77], v[90:93], v[78:81]
	s_waitcnt lgkmcnt(0)
	v_mfma_f32_16x16x32_bf16 v[138:141], v[74:77], v[86:89], v[14:17]
	ds_read_b128 v[74:77], v123 offset:448
	v_mfma_f32_16x16x32_bf16 v[64:67], v[102:105], v[56:59], v[64:67]
	v_mfma_f32_16x16x32_bf16 v[82:85], v[102:105], v[86:89], v[82:85]
	v_mfma_f32_16x16x32_bf16 v[134:137], v[102:105], v[90:93], v[94:97]
	v_mfma_f32_16x16x32_bf16 v[52:55], v[70:73], v[114:117], v[52:55]

; template <bool PROMPT, int HALF>
; __device__ __forceinline__ void conv_item(unsigned char* ws, KArgs ka, int ib, int oct, int g, LAS unsigned char* lds, int tid, int lane, int wave) {
;     ...
;     __syncthreads();
;     int lane2; { unsigned ones_ = ~0u; asm volatile("" : "+s"(ones_)); lane2 = (int)__builtin_amdgcn_mbcnt_hi(ones_, __builtin_amdgcn_mbcnt_lo(ones_, 0u)); }
;     const int nn2 = lane2 & 15, kq2 = lane2 >> 4;
;     float nsum = 0.f;
;     { const float* kq_ = (const float*)(ws + WS_KPART) + ((size_t)ib * 320 + (PROMPT ? 0 : 256)) * 2048; constexpr int ntile = PROMPT ? 256 : 64;
;       for (int q = lane2; q < ntile; q += 64) nsum += kq_[(size_t)q * 2048 + c] + kq_[(size_t)q * 2048 + 1024 + c];
	v_min_i32_e32 v14, 0x1ff8, v51
	v_ashrrev_i32_e32 v15, 31, v14
	v_lshl_add_u64 v[68:69], v[14:15], 1, s[22:23]
	global_load_dwordx4 v[14:17], v[68:69], off
	global_load_dword v128, v[68:69], off offset:-4
	s_waitcnt vmcnt(8)
	v_perm_b32 v68, v142, v130, s67
	v_perm_b32 v69, v130, v131, s67
	v_perm_b32 v70, v131, v132, s67
	v_perm_b32 v71, v132, v133, s67
	s_nop 0
	v_mfma_f32_16x16x32_bf16 v[52:55], v[102:105], v[118:121], v[52:55]
	v_mfma_f32_16x16x32_bf16 v[106:109], v[68:71], v[56:59], v[60:63]
	s_nop 2
	v_min_u32_e32 v60, 32, v50
	v_mad_u32_u24 v60, v60, s58, v0
	v_mfma_f32_16x16x32_bf16 v[110:113], v[130:133], v[90:93], v[64:67]
	v_mfma_f32_16x16x32_bf16 v[94:97], v[68:71], v[90:93], v[98:101]
	v_mfma_f32_16x16x32_bf16 v[78:81], v[68:71], v[86:89], v[78:81]
	s_waitcnt lgkmcnt(0)
	v_mfma_f32_16x16x32_bf16 v[70:73], v[68:71], v[74:77], v[138:141]
	ds_read_b128 v[66:69], v60
	v_mfma_f32_16x16x32_bf16 v[98:101], v[130:133], v[86:89], v[134:137]
	v_mfma_f32_16x16x32_bf16 v[82:85], v[130:133], v[74:77], v[82:85]
	v_mfma_f32_16x16x32_bf16 v[102:105], v[130:133], v[56:59], v[52:55]
	s_nop 0
	s_add_i32 s11, s11, 8
	v_add_u32_e32 v50, 1, v50
	s_cmpk_gt_u32 s11, 0xf8
	v_add_u32_e32 v51, 0x100, v51
	s_cbranch_scc0 .LBB0_755
	s_mov_b32 s11, -1
	s_waitcnt lgkmcnt(0)
	s_barrier
	s_nop 0
	v_mbcnt_lo_u32_b32 v0, s11, 0
	s_waitcnt vmcnt(3)
	v_mbcnt_hi_u32_b32 v12, s11, v0
	s_movk_i32 s11, 0x100
	v_cmp_gt_i32_e32 vcc, s11, v12
	v_mov_b32_e32 v0, 0
	s_and_saveexec_b64 s[22:23], vcc
	s_cbranch_execz .LBB0_760
	s_lshl_b64 s[18:19], s[18:19], 2
	s_add_u32 s18, s51, s18
	v_lshlrev_b32_e32 v0, 13, v12
	s_addc_u32 s19, s52, s19
	v_subrev_u32_e32 v4, 64, v12
	v_lshl_add_u64 v[2:3], s[18:19], 0, v[0:1]
	v_mov_b32_e32 v0, 0
	s_mov_b64 s[18:19], 0

.LBB0_769:
	v_min_i32_e32 v68, 0x1ff8, v66
	v_ashrrev_i32_e32 v69, 31, v68
	v_lshl_add_u64 v[72:73], v[68:69], 1, s[18:19]
	global_load_dwordx4 v[68:71], v[72:73], off
	global_load_dword v67, v[72:73], off offset:-4
	s_add_i32 s22, s11, 12
	s_waitcnt vmcnt(8)
	v_perm_b32 v72, v125, v2, s67
	v_perm_b32 v73, v2, v3, s67
	v_perm_b32 v74, v3, v4, s67
	v_perm_b32 v75, v4, v5, s67

	s_ashr_i32 s22, s22, 3
	v_add_u32_e32 v76, s22, v124
	v_min_u32_e32 v76, 32, v76
	v_mad_u32_u24 v76, v76, s58, v0
	v_mfma_f32_16x16x32_bf16 v[42:45], v[72:75], v[62:65], v[42:45]
	ds_read_b128 v[76:79], v76 offset:320
	v_mfma_f32_16x16x32_bf16 v[38:41], v[2:5], v[58:61], v[38:41]
	v_mfma_f32_16x16x32_bf16 v[34:37], v[72:75], v[58:61], v[34:37]
	v_mfma_f32_16x16x32_bf16 v[30:33], v[2:5], v[54:57], v[30:33]
	v_mfma_f32_16x16x32_bf16 v[26:29], v[72:75], v[54:57], v[26:29]
	s_waitcnt lgkmcnt(1)
	v_mfma_f32_16x16x32_bf16 v[22:25], v[2:5], v[50:53], v[22:25]
	v_mfma_f32_16x16x32_bf16 v[18:21], v[72:75], v[50:53], v[18:21]

	v_add_u32_e32 v72, 32, v66
	v_min_i32_e32 v72, 0x1ff8, v72
	v_ashrrev_i32_e32 v73, 31, v72
	v_lshl_add_u64 v[80:81], v[72:73], 1, s[18:19]
	global_load_dwordx4 v[72:75], v[80:81], off
	global_load_dword v96, v[80:81], off offset:-4
	s_add_i32 s22, s11, 13
	s_waitcnt vmcnt(8)
	v_perm_b32 v80, v126, v6, s67
	v_perm_b32 v81, v6, v7, s67
	v_perm_b32 v82, v7, v8, s67
	v_perm_b32 v83, v8, v9, s67

	s_ashr_i32 s22, s22, 3
	v_add_u32_e32 v84, s22, v124
	v_mfma_f32_16x16x32_bf16 v[42:45], v[80:83], v[58:61], v[42:45]
	v_mfma_f32_16x16x32_bf16 v[34:37], v[80:83], v[54:57], v[34:37]
	v_mfma_f32_16x16x32_bf16 v[26:29], v[80:83], v[50:53], v[26:29]
	s_waitcnt lgkmcnt(0)
	v_mfma_f32_16x16x32_bf16 v[18:21], v[80:83], v[76:79], v[18:21]
	v_min_u32_e32 v80, 32, v84
	v_mad_u32_u24 v80, v80, s58, v0
	ds_read_b128 v[80:83], v80 offset:384
	v_mfma_f32_16x16x32_bf16 v[38:41], v[6:9], v[54:57], v[38:41]
	v_mfma_f32_16x16x32_bf16 v[30:33], v[6:9], v[50:53], v[30:33]
	v_mfma_f32_16x16x32_bf16 v[22:25], v[6:9], v[76:79], v[22:25]
	v_mfma_f32_16x16x32_bf16 v[2:5], v[2:5], v[62:65], v[46:49]
	s_nop 0
	s_nop 1
	v_add_u32_e32 v46, 64, v66
	v_min_i32_e32 v46, 0x1ff8, v46
	v_ashrrev_i32_e32 v47, 31, v46
	v_lshl_add_u64 v[62:63], v[46:47], 1, s[18:19]
	global_load_dwordx4 v[46:49], v[62:63], off
	global_load_dword v97, v[62:63], off offset:-4
	s_waitcnt vmcnt(8)
	v_perm_b32 v62, v127, v10, s67
	v_perm_b32 v63, v10, v11, s67
	v_perm_b32 v64, v11, v12, s67
	v_perm_b32 v65, v12, v13, s67
	s_add_i32 s22, s11, 14

	s_ashr_i32 s22, s22, 3
	v_add_u32_e32 v84, s22, v124
	v_mfma_f32_16x16x32_bf16 v[42:45], v[62:65], v[54:57], v[42:45]
	v_mfma_f32_16x16x32_bf16 v[34:37], v[62:65], v[50:53], v[34:37]
	v_mfma_f32_16x16x32_bf16 v[26:29], v[62:65], v[76:79], v[26:29]
	s_waitcnt lgkmcnt(0)
	v_mfma_f32_16x16x32_bf16 v[18:21], v[62:65], v[80:83], v[18:21]
	v_min_u32_e32 v62, 32, v84
	v_mad_u32_u24 v62, v62, s58, v0
	ds_read_b128 v[84:87], v62 offset:448
	v_mfma_f32_16x16x32_bf16 v[38:41], v[10:13], v[50:53], v[38:41]
	v_mfma_f32_16x16x32_bf16 v[30:33], v[10:13], v[76:79], v[30:33]
	v_mfma_f32_16x16x32_bf16 v[22:25], v[10:13], v[80:83], v[22:25]
	v_mfma_f32_16x16x32_bf16 v[2:5], v[6:9], v[58:61], v[2:5]

	v_add_u32_e32 v6, 0x60, v66
	v_min_i32_e32 v6, 0x1ff8, v6
	v_ashrrev_i32_e32 v7, 31, v6
	v_lshl_add_u64 v[6:7], v[6:7], 1, s[18:19]
	global_load_dwordx4 v[88:91], v[6:7], off
	global_load_dword v98, v[6:7], off offset:-4
	s_waitcnt vmcnt(8)
	v_perm_b32 v6, v128, v14, s67
	v_perm_b32 v7, v14, v15, s67
	v_perm_b32 v8, v15, v16, s67
	v_perm_b32 v9, v16, v17, s67
	s_add_i32 s22, s11, 15

	s_ashr_i32 s22, s22, 3
	v_add_u32_e32 v58, s22, v124
	v_mfma_f32_16x16x32_bf16 v[42:45], v[6:9], v[50:53], v[42:45]
	v_mfma_f32_16x16x32_bf16 v[34:37], v[6:9], v[76:79], v[34:37]
	v_mfma_f32_16x16x32_bf16 v[26:29], v[6:9], v[80:83], v[26:29]
	s_waitcnt lgkmcnt(0)
	v_mfma_f32_16x16x32_bf16 v[6:9], v[6:9], v[84:87], v[18:21]
	s_nop 2
	v_min_u32_e32 v18, 32, v58
	v_mad_u32_u24 v18, v18, s58, v0
	v_mfma_f32_16x16x32_bf16 v[38:41], v[14:17], v[76:79], v[38:41]
	ds_read_b128 v[92:95], v18
	v_mfma_f32_16x16x32_bf16 v[30:33], v[14:17], v[80:83], v[30:33]
	v_mfma_f32_16x16x32_bf16 v[22:25], v[14:17], v[84:87], v[22:25]
	v_mfma_f32_16x16x32_bf16 v[10:13], v[10:13], v[54:57], v[2:5]
	s_nop 0
	s_nop 1
	v_add_u32_e32 v2, 0x80, v66
	v_min_i32_e32 v2, 0x1ff8, v2
	v_ashrrev_i32_e32 v3, 31, v2
	v_lshl_add_u64 v[18:19], v[2:3], 1, s[18:19]
	global_load_dwordx4 v[2:5], v[18:19], off
	global_load_dword v125, v[18:19], off offset:-4
	s_waitcnt vmcnt(8)
	v_perm_b32 v18, v67, v68, s67
	v_perm_b32 v19, v68, v69, s67
	v_perm_b32 v20, v69, v70, s67
	v_perm_b32 v21, v70, v71, s67
	s_add_i32 s22, s11, 16

	s_ashr_i32 s22, s22, 3
	v_add_u32_e32 v54, s22, v124
	v_mfma_f32_16x16x32_bf16 v[42:45], v[18:21], v[76:79], v[42:45]
	v_mfma_f32_16x16x32_bf16 v[34:37], v[18:21], v[80:83], v[34:37]
	v_mfma_f32_16x16x32_bf16 v[26:29], v[18:21], v[84:87], v[26:29]
	s_waitcnt lgkmcnt(0)
	v_mfma_f32_16x16x32_bf16 v[18:21], v[18:21], v[92:95], v[6:9]
	s_nop 2
	v_min_u32_e32 v6, 32, v54
	v_mad_u32_u24 v6, v6, s58, v0
	ds_read_b128 v[62:65], v6 offset:64
	v_mfma_f32_16x16x32_bf16 v[38:41], v[68:71], v[80:83], v[38:41]
	v_mfma_f32_16x16x32_bf16 v[30:33], v[68:71], v[84:87], v[30:33]
	v_mfma_f32_16x16x32_bf16 v[22:25], v[68:71], v[92:95], v[22:25]
	v_mfma_f32_16x16x32_bf16 v[10:13], v[14:17], v[50:53], v[10:13]

	v_add_u32_e32 v6, 0xa0, v66
	v_min_i32_e32 v6, 0x1ff8, v6
	v_ashrrev_i32_e32 v7, 31, v6
	v_lshl_add_u64 v[14:15], v[6:7], 1, s[18:19]
	global_load_dwordx4 v[6:9], v[14:15], off
	global_load_dword v126, v[14:15], off offset:-4
	s_waitcnt vmcnt(8)
	v_perm_b32 v14, v96, v72, s67
	v_perm_b32 v15, v72, v73, s67
	v_perm_b32 v16, v73, v74, s67
	v_perm_b32 v17, v74, v75, s67
	s_add_i32 s22, s11, 17

	s_ashr_i32 s22, s22, 3
	v_add_u32_e32 v50, s22, v124
	v_mfma_f32_16x16x32_bf16 v[42:45], v[14:17], v[80:83], v[42:45]
	v_mfma_f32_16x16x32_bf16 v[34:37], v[14:17], v[84:87], v[34:37]
	v_mfma_f32_16x16x32_bf16 v[26:29], v[14:17], v[92:95], v[26:29]
	s_waitcnt lgkmcnt(0)
	v_mfma_f32_16x16x32_bf16 v[14:17], v[14:17], v[62:65], v[18:21]
	s_nop 2
	v_min_u32_e32 v18, 32, v50
	v_mad_u32_u24 v18, v18, s58, v0
	ds_read_b128 v[58:61], v18 offset:128
	v_mfma_f32_16x16x32_bf16 v[38:41], v[72:75], v[84:87], v[38:41]
	v_mfma_f32_16x16x32_bf16 v[30:33], v[72:75], v[92:95], v[30:33]
	v_mfma_f32_16x16x32_bf16 v[22:25], v[72:75], v[62:65], v[22:25]
	v_mfma_f32_16x16x32_bf16 v[18:21], v[68:71], v[76:79], v[10:13]
	s_nop 0
	s_nop 1
	v_add_u32_e32 v10, 0xc0, v66
	v_min_i32_e32 v10, 0x1ff8, v10
	v_ashrrev_i32_e32 v11, 31, v10
	v_lshl_add_u64 v[50:51], v[10:11], 1, s[18:19]
	global_load_dwordx4 v[10:13], v[50:51], off
	global_load_dword v127, v[50:51], off offset:-4
	s_waitcnt vmcnt(8)
	v_perm_b32 v50, v97, v46, s67
	v_perm_b32 v51, v46, v47, s67
	v_perm_b32 v52, v47, v48, s67
	v_perm_b32 v53, v48, v49, s67
	s_add_i32 s22, s11, 18

	s_ashr_i32 s22, s22, 3
	v_add_u32_e32 v54, s22, v124
	v_mfma_f32_16x16x32_bf16 v[42:45], v[50:53], v[84:87], v[42:45]
	v_mfma_f32_16x16x32_bf16 v[34:37], v[50:53], v[92:95], v[34:37]
	v_mfma_f32_16x16x32_bf16 v[26:29], v[50:53], v[62:65], v[26:29]
	s_waitcnt lgkmcnt(0)
	v_mfma_f32_16x16x32_bf16 v[50:53], v[50:53], v[58:61], v[14:17]
	s_nop 2
	v_min_u32_e32 v14, 32, v54
	v_mad_u32_u24 v14, v14, s58, v0
	ds_read_b128 v[54:57], v14 offset:192
	v_mfma_f32_16x16x32_bf16 v[38:41], v[46:49], v[92:95], v[38:41]
	v_mfma_f32_16x16x32_bf16 v[30:33], v[46:49], v[62:65], v[30:33]
	v_mfma_f32_16x16x32_bf16 v[22:25], v[46:49], v[58:61], v[22:25]
	v_mfma_f32_16x16x32_bf16 v[68:71], v[72:75], v[80:83], v[18:21]

	v_add_u32_e32 v14, 0xe0, v66
	v_min_i32_e32 v14, 0x1ff8, v14
	v_ashrrev_i32_e32 v15, 31, v14
	v_lshl_add_u64 v[18:19], v[14:15], 1, s[18:19]
	global_load_dwordx4 v[14:17], v[18:19], off
	global_load_dword v128, v[18:19], off offset:-4
	s_waitcnt vmcnt(8)
	v_perm_b32 v18, v98, v88, s67
	v_perm_b32 v19, v88, v89, s67
	v_perm_b32 v20, v89, v90, s67
	v_perm_b32 v21, v90, v91, s67
	s_add_i32 s22, s11, 19

; #define CONV_LOADA(e_, k_) do { const int xh_ = min(32 * (e_) + xa, L - 8); rh[k_] = *(const u32x4a4*)(Rc + xh_); asm volatile("" ::: "memory"); rl[k_] = *(const unsigned*)(Rc + xh_ - 2); } while (0)
; #define CONV_BLOCK(DO0, DO1) do { CONV_STEP(0, DO0, DO1); CONV_STEP(1, DO0, DO1); CONV_STEP(2, DO0, DO1); CONV_STEP(3, DO0, DO1); CONV_STEP(4, DO0, DO1); CONV_STEP(5, DO0, DO1); CONV_STEP(6, DO0, DO1); CONV_STEP(7, DO0, DO1); } while (0)
; template <bool PROMPT, int HALF>
; __device__ __forceinline__ void conv_item(unsigned char* ws, KArgs ka, int ib, int oct, int g, LAS unsigned char* lds, int tid, int lane, int wave) {
;     ...
; #pragma unroll
;     for (int k = 0; k < DA; ++k) CONV_LOADA(E0 + k, k);
;     { unsigned zz_ = 0u; asm volatile("" : "+v"(zz_));
; #pragma unroll
;       for (int k = 0; k < W; ++k) F1[k] = (u32x4){zz_, zz_, zz_, zz_}; }
;     for (int e = E0; e < E1; e += 8) CONV_BLOCK(false, true);
;     { unsigned zz_ = 0u; asm volatile("" : "+v"(zz_));
; #pragma unroll
;       for (int k = 0; k < W; ++k) F0[k] = (u32x4){zz_, zz_, zz_, zz_}; }
;     for (int e = E1; e < E2; e += 8) CONV_BLOCK(true, true);
;     for (int e = E2; e < E3; e += 8) CONV_BLOCK(true, false);
	s_ashr_i32 s22, s22, 3
	v_mfma_f32_16x16x32_bf16 v[42:45], v[18:21], v[92:95], v[42:45]
	v_mfma_f32_16x16x32_bf16 v[34:37], v[18:21], v[62:65], v[34:37]
	v_mfma_f32_16x16x32_bf16 v[26:29], v[18:21], v[58:61], v[26:29]
	s_waitcnt lgkmcnt(0)
	v_mfma_f32_16x16x32_bf16 v[18:21], v[18:21], v[54:57], v[50:53]
	s_nop 2
	v_add_u32_e32 v50, s22, v124
	v_mfma_f32_16x16x32_bf16 v[46:49], v[46:49], v[84:87], v[68:71]
	v_min_u32_e32 v50, 32, v50
	v_mad_u32_u24 v50, v50, s58, v0
	ds_read_b128 v[50:53], v50 offset:256
	v_mfma_f32_16x16x32_bf16 v[38:41], v[88:91], v[62:65], v[38:41]
	v_mfma_f32_16x16x32_bf16 v[30:33], v[88:91], v[58:61], v[30:33]
	v_mfma_f32_16x16x32_bf16 v[22:25], v[88:91], v[54:57], v[22:25]
	v_mfma_f32_16x16x32_bf16 v[46:49], v[88:91], v[92:95], v[46:49]
	s_nop 0
	s_add_i32 s11, s11, 8
	s_cmp_gt_u32 s11, 0xffffff70
	v_add_u32_e32 v66, 0x100, v66
	s_cbranch_scc0 .LBB0_769
	v_mov_b32_e32 v66, v1
	v_mov_b32_e32 v70, 0
	v_add_u32_e32 v129, 0xffffefa0, v123
	s_movk_i32 s11, 0xff71
	s_movk_i32 s22, 0xde40
	v_mov_b32_e32 v71, v70
	v_mov_b32_e32 v72, v70
	v_mov_b32_e32 v73, v70
	v_mov_b32_e32 v86, v70
	v_mov_b32_e32 v87, v70
	v_mov_b32_e32 v88, v70
	v_mov_b32_e32 v89, v70
	v_mov_b32_e32 v94, v70
	v_mov_b32_e32 v95, v70
	v_mov_b32_e32 v96, v70
	v_mov_b32_e32 v97, v70
	v_mov_b32_e32 v110, v70
	v_mov_b32_e32 v111, v70
	v_mov_b32_e32 v112, v70
	v_mov_b32_e32 v113, v70
	v_mov_b32_e32 v78, v70
	v_mov_b32_e32 v79, v70
	v_mov_b32_e32 v80, v70
	v_mov_b32_e32 v81, v70
	v_mov_b32_e32 v98, v70
	v_mov_b32_e32 v99, v70
	v_mov_b32_e32 v100, v70
	v_mov_b32_e32 v101, v70
	v_mov_b32_e32 v106, v70
	v_mov_b32_e32 v107, v70
	v_mov_b32_e32 v108, v70
	v_mov_b32_e32 v109, v70
	v_mov_b32_e32 v102, v70
	v_mov_b32_e32 v103, v70
	v_mov_b32_e32 v104, v70
	v_mov_b32_e32 v105, v70
	v_mov_b32_e32 v67, v66
	v_mov_b32_e32 v68, v66
	v_mov_b32_e32 v69, v66
	v_mov_b32_e32 v74, v66
	v_mov_b32_e32 v75, v66
	v_mov_b32_e32 v76, v66
	v_mov_b32_e32 v77, v66
	v_mov_b32_e32 v82, v66
	v_mov_b32_e32 v83, v66
	v_mov_b32_e32 v84, v66
	v_mov_b32_e32 v85, v66
	v_mov_b32_e32 v90, v66
	v_mov_b32_e32 v91, v66
	v_mov_b32_e32 v92, v66
	v_mov_b32_e32 v93, v66
.LBB0_771:
	v_min_i32_e32 v114, 0x1ff8, v129
	v_ashrrev_i32_e32 v115, 31, v114
	v_lshl_add_u64 v[118:119], v[114:115], 1, s[18:19]
	global_load_dwordx4 v[114:117], v[118:119], off
	global_load_dword v138, v[118:119], off offset:-4
	s_add_i32 s23, s11, 12
	s_waitcnt vmcnt(8)
	v_perm_b32 v118, v125, v2, s67
	v_perm_b32 v119, v2, v3, s67
	v_perm_b32 v120, v3, v4, s67
	v_perm_b32 v121, v4, v5, s67

	s_ashr_i32 s23, s23, 3
	v_mfma_f32_16x16x32_bf16 v[46:49], v[2:5], v[62:65], v[46:49]
	s_add_i32 s30, s22, 0x100
	s_and_b32 s30, s30, 0x1c0
	v_mfma_f32_16x16x32_bf16 v[42:45], v[118:121], v[62:65], v[42:45]
	v_mfma_f32_16x16x32_bf16 v[62:65], v[2:5], v[82:85], v[106:109]
	s_nop 2
	v_add_u32_e32 v106, s23, v122
	v_min_u32_e32 v106, 32, v106
	v_add_u32_e32 v107, s23, v124
	v_mul_u32_u24_e32 v106, 0x210, v106
	v_min_u32_e32 v107, 32, v107
	v_add3_u32 v106, v0, v106, s30
	v_mul_u32_u24_e32 v107, 0x210, v107
	v_mfma_f32_16x16x32_bf16 v[102:105], v[2:5], v[90:93], v[102:105]
	v_mfma_f32_16x16x32_bf16 v[90:93], v[118:121], v[90:93], v[110:113]
	v_mfma_f32_16x16x32_bf16 v[38:41], v[2:5], v[58:61], v[38:41]
	v_mfma_f32_16x16x32_bf16 v[98:101], v[2:5], v[74:77], v[98:101]
	v_mfma_f32_16x16x32_bf16 v[30:33], v[2:5], v[54:57], v[30:33]
	s_waitcnt lgkmcnt(1)
	v_mfma_f32_16x16x32_bf16 v[78:81], v[2:5], v[66:69], v[78:81]
	s_waitcnt lgkmcnt(0)
	v_mfma_f32_16x16x32_bf16 v[2:5], v[2:5], v[50:53], v[22:25]
	s_nop 2
	v_add3_u32 v22, v0, v107, s30
	ds_read_b128 v[106:109], v106
	ds_read_b128 v[110:113], v22
	v_mfma_f32_16x16x32_bf16 v[94:97], v[118:121], v[82:85], v[94:97]
	v_mfma_f32_16x16x32_bf16 v[34:37], v[118:121], v[58:61], v[34:37]
	v_mfma_f32_16x16x32_bf16 v[86:89], v[118:121], v[74:77], v[86:89]
	v_mfma_f32_16x16x32_bf16 v[26:29], v[118:121], v[54:57], v[26:29]
	v_mfma_f32_16x16x32_bf16 v[70:73], v[118:121], v[66:69], v[70:73]
	v_mfma_f32_16x16x32_bf16 v[22:25], v[118:121], v[50:53], v[18:21]
	s_nop 0
	s_nop 1
	v_add_u32_e32 v18, 32, v129
	v_min_i32_e32 v18, 0x1ff8, v18
	v_ashrrev_i32_e32 v19, 31, v18
	v_lshl_add_u64 v[118:119], v[18:19], 1, s[18:19]
	global_load_dwordx4 v[18:21], v[118:119], off
	global_load_dword v139, v[118:119], off offset:-4
	s_add_i32 s23, s11, 13
	s_waitcnt vmcnt(8)
	v_perm_b32 v118, v126, v6, s67
	v_perm_b32 v119, v6, v7, s67
	v_perm_b32 v120, v7, v8, s67
	v_perm_b32 v121, v8, v9, s67

	s_ashr_i32 s23, s23, 3
	v_mfma_f32_16x16x32_bf16 v[46:49], v[6:9], v[58:61], v[46:49]
	s_add_i32 s30, s22, 0x140
	s_and_b32 s30, s30, 0x1c0
	v_mfma_f32_16x16x32_bf16 v[42:45], v[118:121], v[58:61], v[42:45]
	v_mfma_f32_16x16x32_bf16 v[58:61], v[6:9], v[74:77], v[62:65]
	v_mfma_f32_16x16x32_bf16 v[62:65], v[118:121], v[74:77], v[94:97]
	s_nop 2
	v_add_u32_e32 v94, s23, v122
	v_min_u32_e32 v94, 32, v94
	v_add_u32_e32 v95, s23, v124
	v_mul_u32_u24_e32 v94, 0x210, v94
	v_min_u32_e32 v95, 32, v95
	v_add3_u32 v94, v0, v94, s30
	v_mul_u32_u24_e32 v95, 0x210, v95
	v_mfma_f32_16x16x32_bf16 v[102:105], v[6:9], v[82:85], v[102:105]
	v_mfma_f32_16x16x32_bf16 v[82:85], v[118:121], v[82:85], v[90:93]
	v_mfma_f32_16x16x32_bf16 v[38:41], v[6:9], v[54:57], v[38:41]
	v_mfma_f32_16x16x32_bf16 v[90:93], v[6:9], v[66:69], v[98:101]
	v_mfma_f32_16x16x32_bf16 v[30:33], v[6:9], v[50:53], v[30:33]
	s_waitcnt lgkmcnt(1)
	v_mfma_f32_16x16x32_bf16 v[78:81], v[6:9], v[106:109], v[78:81]
	s_waitcnt lgkmcnt(0)
	v_mfma_f32_16x16x32_bf16 v[2:5], v[6:9], v[110:113], v[2:5]
	v_add3_u32 v6, v0, v95, s30
	ds_read_b128 v[94:97], v94
	ds_read_b128 v[98:101], v6
	v_mfma_f32_16x16x32_bf16 v[34:37], v[118:121], v[54:57], v[34:37]
	v_mfma_f32_16x16x32_bf16 v[86:89], v[118:121], v[66:69], v[86:89]
	v_mfma_f32_16x16x32_bf16 v[26:29], v[118:121], v[50:53], v[26:29]
	v_mfma_f32_16x16x32_bf16 v[70:73], v[118:121], v[106:109], v[70:73]
	v_mfma_f32_16x16x32_bf16 v[6:9], v[118:121], v[110:113], v[22:25]
	s_nop 0
	s_nop 1
	v_add_u32_e32 v22, 64, v129
	v_min_i32_e32 v22, 0x1ff8, v22
	v_ashrrev_i32_e32 v23, 31, v22
	v_lshl_add_u64 v[118:119], v[22:23], 1, s[18:19]
	global_load_dwordx4 v[22:25], v[118:119], off
	global_load_dword v140, v[118:119], off offset:-4
	s_add_i32 s23, s11, 14
	s_waitcnt vmcnt(8)
	v_perm_b32 v118, v127, v10, s67
	v_perm_b32 v119, v10, v11, s67
	v_perm_b32 v120, v11, v12, s67
	v_perm_b32 v121, v12, v13, s67

	s_ashr_i32 s23, s23, 3
	v_mfma_f32_16x16x32_bf16 v[102:105], v[10:13], v[74:77], v[102:105]
	s_add_i32 s30, s22, 0x180
	s_and_b32 s30, s30, 0x1c0
	v_mfma_f32_16x16x32_bf16 v[74:77], v[118:121], v[74:77], v[82:85]
	v_mfma_f32_16x16x32_bf16 v[82:85], v[118:121], v[106:109], v[86:89]
	s_nop 2
	v_add_u32_e32 v86, s23, v122
	v_min_u32_e32 v86, 32, v86
	v_add_u32_e32 v87, s23, v124
	v_mul_u32_u24_e32 v86, 0x210, v86
	v_min_u32_e32 v87, 32, v87
	v_add3_u32 v86, v0, v86, s30
	v_mul_u32_u24_e32 v87, 0x210, v87
	v_mfma_f32_16x16x32_bf16 v[46:49], v[10:13], v[54:57], v[46:49]
	v_mfma_f32_16x16x32_bf16 v[42:45], v[118:121], v[54:57], v[42:45]
	v_mfma_f32_16x16x32_bf16 v[54:57], v[10:13], v[66:69], v[58:61]
	v_mfma_f32_16x16x32_bf16 v[58:61], v[118:121], v[66:69], v[62:65]
	v_mfma_f32_16x16x32_bf16 v[38:41], v[10:13], v[50:53], v[38:41]
	v_mfma_f32_16x16x32_bf16 v[62:65], v[10:13], v[106:109], v[90:93]
	v_mfma_f32_16x16x32_bf16 v[30:33], v[10:13], v[110:113], v[30:33]
	s_waitcnt lgkmcnt(1)
	v_mfma_f32_16x16x32_bf16 v[78:81], v[10:13], v[94:97], v[78:81]
	s_waitcnt lgkmcnt(0)
	v_mfma_f32_16x16x32_bf16 v[2:5], v[10:13], v[98:101], v[2:5]
	v_add3_u32 v10, v0, v87, s30
	ds_read_b128 v[86:89], v86
	ds_read_b128 v[130:133], v10
	v_mfma_f32_16x16x32_bf16 v[34:37], v[118:121], v[50:53], v[34:37]
	v_mfma_f32_16x16x32_bf16 v[26:29], v[118:121], v[110:113], v[26:29]
	v_mfma_f32_16x16x32_bf16 v[70:73], v[118:121], v[94:97], v[70:73]
	v_mfma_f32_16x16x32_bf16 v[6:9], v[118:121], v[98:101], v[6:9]

	v_add_u32_e32 v10, 0x60, v129
	v_min_i32_e32 v10, 0x1ff8, v10
	v_ashrrev_i32_e32 v11, 31, v10
	v_lshl_add_u64 v[10:11], v[10:11], 1, s[18:19]
	global_load_dwordx4 v[118:121], v[10:11], off
	global_load_dword v142, v[10:11], off offset:-4
	s_waitcnt vmcnt(8)
	v_perm_b32 v10, v128, v14, s67
	v_perm_b32 v11, v14, v15, s67
	v_perm_b32 v12, v15, v16, s67
	v_perm_b32 v13, v16, v17, s67
	s_add_i32 s23, s11, 15

	s_ashr_i32 s23, s23, 3
	v_mfma_f32_16x16x32_bf16 v[90:93], v[14:17], v[66:69], v[102:105]
	s_add_i32 s30, s22, 0x1c0
	s_and_b32 s30, s30, 0x1c0
	v_mfma_f32_16x16x32_bf16 v[66:69], v[10:13], v[66:69], v[74:77]
	s_nop 2
	v_add_u32_e32 v74, s23, v122
	v_min_u32_e32 v74, 32, v74
	v_mfma_f32_16x16x32_bf16 v[46:49], v[14:17], v[50:53], v[46:49]
	v_mfma_f32_16x16x32_bf16 v[42:45], v[10:13], v[50:53], v[42:45]
	v_mfma_f32_16x16x32_bf16 v[50:53], v[14:17], v[106:109], v[54:57]
	v_mfma_f32_16x16x32_bf16 v[54:57], v[10:13], v[106:109], v[58:61]
	v_mfma_f32_16x16x32_bf16 v[58:61], v[14:17], v[94:97], v[62:65]
	v_mfma_f32_16x16x32_bf16 v[62:65], v[10:13], v[94:97], v[82:85]
	s_nop 2
	v_mul_u32_u24_e32 v82, 0x210, v74
	s_waitcnt lgkmcnt(1)
	v_mfma_f32_16x16x32_bf16 v[74:77], v[14:17], v[86:89], v[78:81]
	s_nop 2
	v_add_u32_e32 v79, s23, v124
	v_min_u32_e32 v79, 32, v79
	v_add3_u32 v78, v0, v82, s30
	v_mul_u32_u24_e32 v79, 0x210, v79
	v_mfma_f32_16x16x32_bf16 v[38:41], v[14:17], v[110:113], v[38:41]
	v_mfma_f32_16x16x32_bf16 v[30:33], v[14:17], v[98:101], v[30:33]
	s_waitcnt lgkmcnt(0)
	v_mfma_f32_16x16x32_bf16 v[14:17], v[14:17], v[130:133], v[2:5]
	s_nop 2
	v_add3_u32 v2, v0, v79, s30
	ds_read_b128 v[78:81], v78
	ds_read_b128 v[134:137], v2
	v_mfma_f32_16x16x32_bf16 v[34:37], v[10:13], v[110:113], v[34:37]
	v_mfma_f32_16x16x32_bf16 v[26:29], v[10:13], v[98:101], v[26:29]
	v_mfma_f32_16x16x32_bf16 v[70:73], v[10:13], v[86:89], v[70:73]
	v_mfma_f32_16x16x32_bf16 v[6:9], v[10:13], v[130:133], v[6:9]

	v_add_u32_e32 v2, 0x80, v129
	v_min_i32_e32 v2, 0x1ff8, v2
	v_ashrrev_i32_e32 v3, 31, v2
	v_lshl_add_u64 v[10:11], v[2:3], 1, s[18:19]
	global_load_dwordx4 v[2:5], v[10:11], off
	global_load_dword v125, v[10:11], off offset:-4
	s_waitcnt vmcnt(8)
	v_perm_b32 v10, v138, v114, s67
	v_perm_b32 v11, v114, v115, s67
	v_perm_b32 v12, v115, v116, s67
	v_perm_b32 v13, v116, v117, s67
	s_add_i32 s23, s11, 16

	s_ashr_i32 s23, s23, 3
	v_mfma_f32_16x16x32_bf16 v[102:105], v[10:13], v[86:89], v[62:65]
	s_and_b32 s30, s22, 0x1c0
	s_nop 1
	v_add_u32_e32 v62, s23, v122
	v_add_u32_e32 v63, s23, v124
	v_min_u32_e32 v62, 32, v62
	v_min_u32_e32 v63, 32, v63
	v_mul_u32_u24_e32 v62, 0x210, v62
	v_mul_u32_u24_e32 v63, 0x210, v63
	v_add3_u32 v62, v0, v62, s30
	v_add3_u32 v63, v0, v63, s30
	v_mfma_f32_16x16x32_bf16 v[82:85], v[114:117], v[106:109], v[90:93]
	s_nop 2
	ds_read_b128 v[90:93], v62
	ds_read_b128 v[62:65], v63
	v_mfma_f32_16x16x32_bf16 v[66:69], v[10:13], v[106:109], v[66:69]
	v_mfma_f32_16x16x32_bf16 v[46:49], v[114:117], v[110:113], v[46:49]
	v_mfma_f32_16x16x32_bf16 v[42:45], v[10:13], v[110:113], v[42:45]
	v_mfma_f32_16x16x32_bf16 v[50:53], v[114:117], v[94:97], v[50:53]
	v_mfma_f32_16x16x32_bf16 v[54:57], v[10:13], v[94:97], v[54:57]
	v_mfma_f32_16x16x32_bf16 v[38:41], v[114:117], v[98:101], v[38:41]
	v_mfma_f32_16x16x32_bf16 v[34:37], v[10:13], v[98:101], v[34:37]
	v_mfma_f32_16x16x32_bf16 v[58:61], v[114:117], v[86:89], v[58:61]
	v_mfma_f32_16x16x32_bf16 v[30:33], v[114:117], v[130:133], v[30:33]
	v_mfma_f32_16x16x32_bf16 v[26:29], v[10:13], v[130:133], v[26:29]
	s_waitcnt lgkmcnt(3)
	v_mfma_f32_16x16x32_bf16 v[74:77], v[114:117], v[78:81], v[74:77]
	v_mfma_f32_16x16x32_bf16 v[70:73], v[10:13], v[78:81], v[70:73]
	s_waitcnt lgkmcnt(2)
	v_mfma_f32_16x16x32_bf16 v[14:17], v[114:117], v[134:137], v[14:17]
	v_mfma_f32_16x16x32_bf16 v[10:13], v[10:13], v[134:137], v[6:9]
	s_nop 0
	s_nop 1
	v_add_u32_e32 v6, 0xa0, v129
	v_min_i32_e32 v6, 0x1ff8, v6
	v_ashrrev_i32_e32 v7, 31, v6
	v_lshl_add_u64 v[106:107], v[6:7], 1, s[18:19]
	global_load_dwordx4 v[6:9], v[106:107], off
	global_load_dword v126, v[106:107], off offset:-4
	s_waitcnt vmcnt(8)
	v_perm_b32 v106, v139, v18, s67
	v_perm_b32 v107, v18, v19, s67
	v_perm_b32 v108, v19, v20, s67
	v_perm_b32 v109, v20, v21, s67
	s_add_i32 s23, s11, 17

	s_ashr_i32 s23, s23, 3
	v_mfma_f32_16x16x32_bf16 v[110:113], v[18:21], v[94:97], v[82:85]
	s_add_i32 s30, s22, 0x240
	s_and_b32 s30, s30, 0x1c0
	v_mfma_f32_16x16x32_bf16 v[66:69], v[106:109], v[94:97], v[66:69]
	v_mfma_f32_16x16x32_bf16 v[94:97], v[18:21], v[78:81], v[58:61]
	s_nop 2
	v_add_u32_e32 v58, s23, v122
	v_min_u32_e32 v58, 32, v58
	v_add_u32_e32 v59, s23, v124
	v_mul_u32_u24_e32 v58, 0x210, v58
	v_min_u32_e32 v59, 32, v59
	v_add3_u32 v58, v0, v58, s30
	v_mul_u32_u24_e32 v59, 0x210, v59
	v_mfma_f32_16x16x32_bf16 v[46:49], v[18:21], v[98:101], v[46:49]
	v_mfma_f32_16x16x32_bf16 v[50:53], v[18:21], v[86:89], v[50:53]
	v_mfma_f32_16x16x32_bf16 v[38:41], v[18:21], v[130:133], v[38:41]
	v_mfma_f32_16x16x32_bf16 v[30:33], v[18:21], v[134:137], v[30:33]
	s_waitcnt lgkmcnt(1)
	v_mfma_f32_16x16x32_bf16 v[74:77], v[18:21], v[90:93], v[74:77]
	s_waitcnt lgkmcnt(0)
	v_mfma_f32_16x16x32_bf16 v[14:17], v[18:21], v[62:65], v[14:17]
	v_add3_u32 v18, v0, v59, s30
	ds_read_b128 v[82:85], v58
	ds_read_b128 v[58:61], v18
	v_mfma_f32_16x16x32_bf16 v[42:45], v[106:109], v[98:101], v[42:45]
	v_mfma_f32_16x16x32_bf16 v[54:57], v[106:109], v[86:89], v[54:57]
	v_mfma_f32_16x16x32_bf16 v[34:37], v[106:109], v[130:133], v[34:37]
	v_mfma_f32_16x16x32_bf16 v[98:101], v[106:109], v[78:81], v[102:105]
	v_mfma_f32_16x16x32_bf16 v[26:29], v[106:109], v[134:137], v[26:29]
	v_mfma_f32_16x16x32_bf16 v[70:73], v[106:109], v[90:93], v[70:73]
	v_mfma_f32_16x16x32_bf16 v[18:21], v[106:109], v[62:65], v[10:13]
	s_nop 0
	s_nop 1
	v_add_u32_e32 v10, 0xc0, v129
	v_min_i32_e32 v10, 0x1ff8, v10
	v_ashrrev_i32_e32 v11, 31, v10
	v_lshl_add_u64 v[102:103], v[10:11], 1, s[18:19]
	global_load_dwordx4 v[10:13], v[102:103], off
	global_load_dword v127, v[102:103], off offset:-4
	s_waitcnt vmcnt(8)
	v_perm_b32 v102, v140, v22, s67
	v_perm_b32 v103, v22, v23, s67
	v_perm_b32 v104, v23, v24, s67
	v_perm_b32 v105, v24, v25, s67
	s_add_i32 s23, s11, 18

	s_ashr_i32 s23, s23, 3
	v_mfma_f32_16x16x32_bf16 v[106:109], v[22:25], v[86:89], v[110:113]
	s_add_i32 s30, s22, 0x280
	s_and_b32 s30, s30, 0x1c0
	v_mfma_f32_16x16x32_bf16 v[66:69], v[102:105], v[86:89], v[66:69]
	v_mfma_f32_16x16x32_bf16 v[86:89], v[102:105], v[78:81], v[54:57]
	s_nop 2
	v_add_u32_e32 v54, s23, v122
	v_min_u32_e32 v54, 32, v54
	v_add_u32_e32 v55, s23, v124
	v_mul_u32_u24_e32 v54, 0x210, v54
	v_min_u32_e32 v55, 32, v55
	v_add3_u32 v54, v0, v54, s30
	v_mul_u32_u24_e32 v55, 0x210, v55
	v_mfma_f32_16x16x32_bf16 v[46:49], v[22:25], v[130:133], v[46:49]
	v_mfma_f32_16x16x32_bf16 v[50:53], v[22:25], v[78:81], v[50:53]
	v_mfma_f32_16x16x32_bf16 v[38:41], v[22:25], v[134:137], v[38:41]
	v_mfma_f32_16x16x32_bf16 v[114:117], v[22:25], v[90:93], v[94:97]
	v_mfma_f32_16x16x32_bf16 v[30:33], v[22:25], v[62:65], v[30:33]
	s_waitcnt lgkmcnt(1)
	v_mfma_f32_16x16x32_bf16 v[138:141], v[22:25], v[82:85], v[74:77]
	s_waitcnt lgkmcnt(0)
	v_mfma_f32_16x16x32_bf16 v[22:25], v[22:25], v[58:61], v[14:17]
	s_nop 2
	v_add3_u32 v14, v0, v55, s30
	ds_read_b128 v[74:77], v54
	ds_read_b128 v[54:57], v14
	v_mfma_f32_16x16x32_bf16 v[42:45], v[102:105], v[130:133], v[42:45]
	v_mfma_f32_16x16x32_bf16 v[34:37], v[102:105], v[134:137], v[34:37]
	v_mfma_f32_16x16x32_bf16 v[26:29], v[102:105], v[62:65], v[26:29]
	v_mfma_f32_16x16x32_bf16 v[70:73], v[102:105], v[82:85], v[70:73]
	v_mfma_f32_16x16x32_bf16 v[18:21], v[102:105], v[58:61], v[18:21]
	v_mfma_f32_16x16x32_bf16 v[130:133], v[102:105], v[90:93], v[98:101]

	v_add_u32_e32 v14, 0xe0, v129
	v_min_i32_e32 v14, 0x1ff8, v14
	v_ashrrev_i32_e32 v15, 31, v14
	v_lshl_add_u64 v[94:95], v[14:15], 1, s[18:19]
	global_load_dwordx4 v[14:17], v[94:95], off
	global_load_dword v128, v[94:95], off offset:-4
	s_add_i32 s23, s11, 19
	s_waitcnt vmcnt(8)
	v_perm_b32 v142, v142, v118, s67
	v_perm_b32 v143, v118, v119, s67
	v_perm_b32 v144, v119, v120, s67
	v_perm_b32 v145, v120, v121, s67

; #define CONV_LOADA(e_, k_) do { const int xh_ = min(32 * (e_) + xa, L - 8); rh[k_] = *(const u32x4a4*)(Rc + xh_); asm volatile("" ::: "memory"); rl[k_] = *(const unsigned*)(Rc + xh_ - 2); } while (0)
; #define CONV_BLOCK(DO0, DO1) do { CONV_STEP(0, DO0, DO1); CONV_STEP(1, DO0, DO1); CONV_STEP(2, DO0, DO1); CONV_STEP(3, DO0, DO1); CONV_STEP(4, DO0, DO1); CONV_STEP(5, DO0, DO1); CONV_STEP(6, DO0, DO1); CONV_STEP(7, DO0, DO1); } while (0)
; template <bool PROMPT, int HALF>
; __device__ __forceinline__ void conv_item(unsigned char* ws, KArgs ka, int ib, int oct, int g, LAS unsigned char* lds, int tid, int lane, int wave) {
;     ...
; #pragma unroll
;     for (int k = 0; k < DA; ++k) CONV_LOADA(E0 + k, k);
;     { unsigned zz_ = 0u; asm volatile("" : "+v"(zz_));
; #pragma unroll
;       for (int k = 0; k < W; ++k) F1[k] = (u32x4){zz_, zz_, zz_, zz_}; }
;     for (int e = E0; e < E1; e += 8) CONV_BLOCK(false, true);
;     { unsigned zz_ = 0u; asm volatile("" : "+v"(zz_));
; #pragma unroll
;       for (int k = 0; k < W; ++k) F0[k] = (u32x4){zz_, zz_, zz_, zz_}; }
;     for (int e = E1; e < E2; e += 8) CONV_BLOCK(true, true);
;     for (int e = E2; e < E3; e += 8) CONV_BLOCK(true, false);
	s_ashr_i32 s23, s23, 3
	v_mfma_f32_16x16x32_bf16 v[102:105], v[118:121], v[78:81], v[106:109]
	s_add_i32 s30, s22, 0x2c0
	s_and_b32 s30, s30, 0x1c0
	v_mfma_f32_16x16x32_bf16 v[106:109], v[118:121], v[90:93], v[50:53]
	s_nop 2
	v_add_u32_e32 v50, s23, v122
	v_add_u32_e32 v51, s23, v124
	v_min_u32_e32 v50, 32, v50
	v_min_u32_e32 v51, 32, v51
	v_mul_u32_u24_e32 v50, 0x210, v50
	v_mul_u32_u24_e32 v51, 0x210, v51
	v_add3_u32 v50, v0, v50, s30
	v_add3_u32 v51, v0, v51, s30
	v_mfma_f32_16x16x32_bf16 v[110:113], v[142:145], v[78:81], v[66:69]
	s_nop 2
	ds_read_b128 v[66:69], v50
	ds_read_b128 v[50:53], v51
	v_mfma_f32_16x16x32_bf16 v[46:49], v[118:121], v[134:137], v[46:49]
	v_mfma_f32_16x16x32_bf16 v[42:45], v[142:145], v[134:137], v[42:45]
	v_mfma_f32_16x16x32_bf16 v[94:97], v[142:145], v[90:93], v[86:89]
	v_mfma_f32_16x16x32_bf16 v[38:41], v[118:121], v[62:65], v[38:41]
	v_mfma_f32_16x16x32_bf16 v[34:37], v[142:145], v[62:65], v[34:37]
	v_mfma_f32_16x16x32_bf16 v[98:101], v[118:121], v[82:85], v[114:117]
	v_mfma_f32_16x16x32_bf16 v[86:89], v[142:145], v[82:85], v[130:133]
	v_mfma_f32_16x16x32_bf16 v[30:33], v[118:121], v[58:61], v[30:33]
	v_mfma_f32_16x16x32_bf16 v[26:29], v[142:145], v[58:61], v[26:29]
	s_waitcnt lgkmcnt(3)
	v_mfma_f32_16x16x32_bf16 v[78:81], v[118:121], v[74:77], v[138:141]
	v_mfma_f32_16x16x32_bf16 v[70:73], v[142:145], v[74:77], v[70:73]
	s_waitcnt lgkmcnt(2)
	v_mfma_f32_16x16x32_bf16 v[22:25], v[118:121], v[54:57], v[22:25]
	v_mfma_f32_16x16x32_bf16 v[18:21], v[142:145], v[54:57], v[18:21]
	s_nop 0
	s_add_i32 s11, s11, 8
	s_addk_i32 s22, 0x200
	s_cmpk_gt_i32 s11, 0x78
	v_add_u32_e32 v129, 0x100, v129
	s_cbranch_scc0 .LBB0_771
	s_waitcnt lgkmcnt(0)
	v_add_u32_e32 v50, 0x1180, v123
	v_add_u32_e32 v51, 17, v122
	s_movk_i32 s11, 0x79
.LBB0_773:
	v_add_u32_e32 v52, 0xffffff20, v50
	v_min_i32_e32 v52, 0x1ff8, v52
	v_ashrrev_i32_e32 v53, 31, v52
	v_lshl_add_u64 v[56:57], v[52:53], 1, s[18:19]
	global_load_dwordx4 v[52:55], v[56:57], off
	global_load_dword v122, v[56:57], off offset:-4
	s_waitcnt vmcnt(8)
	v_perm_b32 v56, v125, v2, s67
	v_perm_b32 v57, v2, v3, s67
	v_perm_b32 v58, v3, v4, s67
	v_perm_b32 v59, v4, v5, s67

	v_add_u32_e32 v64, -1, v51
	v_min_u32_e32 v64, 32, v64
	v_mad_u32_u24 v118, v64, s58, v0
	v_mfma_f32_16x16x32_bf16 v[60:63], v[56:59], v[90:93], v[110:113]
	s_nop 2
	ds_read_b128 v[110:113], v118 offset:320
	v_mfma_f32_16x16x32_bf16 v[106:109], v[2:5], v[82:85], v[106:109]
	v_mfma_f32_16x16x32_bf16 v[94:97], v[56:59], v[82:85], v[94:97]
	v_mfma_f32_16x16x32_bf16 v[98:101], v[2:5], v[74:77], v[98:101]
	v_mfma_f32_16x16x32_bf16 v[86:89], v[56:59], v[74:77], v[86:89]
	s_waitcnt lgkmcnt(1)
	v_mfma_f32_16x16x32_bf16 v[78:81], v[2:5], v[66:69], v[78:81]
	v_mfma_f32_16x16x32_bf16 v[56:59], v[56:59], v[66:69], v[70:73]

	v_add_u32_e32 v64, 0xffffff40, v50
	v_min_i32_e32 v64, 0x1ff8, v64
	v_ashrrev_i32_e32 v65, 31, v64
	v_lshl_add_u64 v[64:65], v[64:65], 1, s[18:19]
	global_load_dwordx4 v[70:73], v[64:65], off
	global_load_dword v123, v[64:65], off offset:-4
	s_waitcnt vmcnt(8)
	v_perm_b32 v114, v126, v6, s67
	v_perm_b32 v115, v6, v7, s67
	v_perm_b32 v116, v7, v8, s67
	v_perm_b32 v117, v8, v9, s67
	s_nop 1

	v_mfma_f32_16x16x32_bf16 v[60:63], v[114:117], v[82:85], v[60:63]
	v_mfma_f32_16x16x32_bf16 v[106:109], v[6:9], v[74:77], v[106:109]
	v_mfma_f32_16x16x32_bf16 v[94:97], v[114:117], v[74:77], v[94:97]
	v_mfma_f32_16x16x32_bf16 v[98:101], v[6:9], v[66:69], v[98:101]
	v_mfma_f32_16x16x32_bf16 v[86:89], v[114:117], v[66:69], v[86:89]
	s_waitcnt lgkmcnt(0)
	v_mfma_f32_16x16x32_bf16 v[78:81], v[6:9], v[110:113], v[78:81]
	v_mfma_f32_16x16x32_bf16 v[56:59], v[114:117], v[110:113], v[56:59]
	ds_read_b128 v[114:117], v118 offset:384
	v_mfma_f32_16x16x32_bf16 v[2:5], v[2:5], v[90:93], v[102:105]

	v_add_u32_e32 v64, 0xffffff60, v50
	v_min_i32_e32 v64, 0x1ff8, v64
	v_ashrrev_i32_e32 v65, 31, v64
	v_lshl_add_u64 v[64:65], v[64:65], 1, s[18:19]
	global_load_dwordx4 v[102:105], v[64:65], off
	global_load_dword v124, v[64:65], off offset:-4
	s_waitcnt vmcnt(8)
	v_perm_b32 v90, v127, v10, s67
	v_perm_b32 v91, v10, v11, s67
	v_perm_b32 v92, v11, v12, s67
	v_perm_b32 v93, v12, v13, s67

	v_mfma_f32_16x16x32_bf16 v[106:109], v[10:13], v[66:69], v[106:109]
	ds_read_b128 v[118:121], v118 offset:448
	v_mfma_f32_16x16x32_bf16 v[94:97], v[90:93], v[66:69], v[94:97]
	v_mfma_f32_16x16x32_bf16 v[98:101], v[10:13], v[110:113], v[98:101]
	v_mfma_f32_16x16x32_bf16 v[86:89], v[90:93], v[110:113], v[86:89]
	s_waitcnt lgkmcnt(1)
	v_mfma_f32_16x16x32_bf16 v[78:81], v[10:13], v[114:117], v[78:81]
	v_mfma_f32_16x16x32_bf16 v[2:5], v[6:9], v[82:85], v[2:5]
	v_mfma_f32_16x16x32_bf16 v[60:63], v[90:93], v[74:77], v[60:63]
	v_mfma_f32_16x16x32_bf16 v[56:59], v[90:93], v[114:117], v[56:59]

	v_add_u32_e32 v6, 0xffffff80, v50
	v_min_i32_e32 v6, 0x1ff8, v6
	v_ashrrev_i32_e32 v7, 31, v6
	v_lshl_add_u64 v[6:7], v[6:7], 1, s[18:19]
	global_load_dwordx4 v[130:133], v[6:7], off
	global_load_dword v129, v[6:7], off offset:-4
	s_waitcnt vmcnt(8)
	v_perm_b32 v6, v128, v14, s67
	v_perm_b32 v7, v14, v15, s67
	v_perm_b32 v8, v15, v16, s67
	v_perm_b32 v9, v16, v17, s67
	s_nop 1

	v_mfma_f32_16x16x32_bf16 v[60:63], v[6:9], v[66:69], v[60:63]
	v_mfma_f32_16x16x32_bf16 v[90:93], v[6:9], v[110:113], v[94:97]
	v_mfma_f32_16x16x32_bf16 v[86:89], v[6:9], v[114:117], v[86:89]
	s_waitcnt lgkmcnt(0)
	v_mfma_f32_16x16x32_bf16 v[6:9], v[6:9], v[118:121], v[56:59]
	s_nop 2
	v_min_u32_e32 v56, 32, v51
	v_mad_u32_u24 v142, v56, s58, v0
	v_mfma_f32_16x16x32_bf16 v[82:85], v[14:17], v[110:113], v[106:109]
	ds_read_b128 v[56:59], v142
	v_mfma_f32_16x16x32_bf16 v[94:97], v[14:17], v[114:117], v[98:101]
	v_mfma_f32_16x16x32_bf16 v[78:81], v[14:17], v[118:121], v[78:81]
	v_mfma_f32_16x16x32_bf16 v[10:13], v[10:13], v[74:77], v[2:5]
	s_nop 0
	s_nop 1
	v_add_u32_e32 v2, 0xffffffa0, v50
	v_min_i32_e32 v2, 0x1ff8, v2
	v_ashrrev_i32_e32 v3, 31, v2
	v_lshl_add_u64 v[64:65], v[2:3], 1, s[18:19]
	global_load_dwordx4 v[2:5], v[64:65], off
	global_load_dword v125, v[64:65], off offset:-4
	s_waitcnt vmcnt(8)
	v_perm_b32 v74, v122, v52, s67
	v_perm_b32 v75, v52, v53, s67
	v_perm_b32 v76, v53, v54, s67
	v_perm_b32 v77, v54, v55, s67
	s_nop 1

	v_mfma_f32_16x16x32_bf16 v[98:101], v[74:77], v[114:117], v[90:93]
	s_nop 2
	ds_read_b128 v[90:93], v142 offset:64
	v_mfma_f32_16x16x32_bf16 v[60:63], v[74:77], v[110:113], v[60:63]
	v_mfma_f32_16x16x32_bf16 v[82:85], v[52:55], v[114:117], v[82:85]
	v_mfma_f32_16x16x32_bf16 v[94:97], v[52:55], v[118:121], v[94:97]
	v_mfma_f32_16x16x32_bf16 v[86:89], v[74:77], v[118:121], v[86:89]
	s_waitcnt lgkmcnt(1)
	v_mfma_f32_16x16x32_bf16 v[78:81], v[52:55], v[56:59], v[78:81]
	v_mfma_f32_16x16x32_bf16 v[74:77], v[74:77], v[56:59], v[6:9]
	v_mfma_f32_16x16x32_bf16 v[10:13], v[14:17], v[66:69], v[10:13]
	s_nop 0
	s_nop 0
	v_subrev_u32_e32 v6, 64, v50
	v_min_i32_e32 v6, 0x1ff8, v6
	v_ashrrev_i32_e32 v7, 31, v6
	v_lshl_add_u64 v[14:15], v[6:7], 1, s[18:19]
	global_load_dwordx4 v[6:9], v[14:15], off
	global_load_dword v126, v[14:15], off offset:-4
	s_waitcnt vmcnt(8)
	v_perm_b32 v14, v123, v70, s67
	v_perm_b32 v15, v70, v71, s67
	v_perm_b32 v16, v71, v72, s67
	v_perm_b32 v17, v72, v73, s67

	v_mfma_f32_16x16x32_bf16 v[64:67], v[70:73], v[118:121], v[82:85]
	s_nop 2
	ds_read_b128 v[82:85], v142 offset:128
	v_mfma_f32_16x16x32_bf16 v[60:63], v[14:17], v[114:117], v[60:63]
	v_mfma_f32_16x16x32_bf16 v[98:101], v[14:17], v[118:121], v[98:101]
	v_mfma_f32_16x16x32_bf16 v[94:97], v[70:73], v[56:59], v[94:97]
	v_mfma_f32_16x16x32_bf16 v[86:89], v[14:17], v[56:59], v[86:89]
	s_waitcnt lgkmcnt(1)
	v_mfma_f32_16x16x32_bf16 v[78:81], v[70:73], v[90:93], v[78:81]
	v_mfma_f32_16x16x32_bf16 v[14:17], v[14:17], v[90:93], v[74:77]
	v_mfma_f32_16x16x32_bf16 v[52:55], v[52:55], v[110:113], v[10:13]
	s_nop 0
	s_nop 1
	v_subrev_u32_e32 v10, 32, v50
	v_min_i32_e32 v10, 0x1ff8, v10
	v_ashrrev_i32_e32 v11, 31, v10
	v_lshl_add_u64 v[68:69], v[10:11], 1, s[18:19]
	global_load_dwordx4 v[10:13], v[68:69], off
	global_load_dword v127, v[68:69], off offset:-4
	s_waitcnt vmcnt(8)
	v_perm_b32 v74, v124, v102, s67
	v_perm_b32 v75, v102, v103, s67
	v_perm_b32 v76, v103, v104, s67
	v_perm_b32 v77, v104, v105, s67
	s_nop 1

	v_mfma_f32_16x16x32_bf16 v[60:63], v[74:77], v[118:121], v[60:63]
	v_mfma_f32_16x16x32_bf16 v[98:101], v[74:77], v[56:59], v[98:101]
	v_mfma_f32_16x16x32_bf16 v[86:89], v[74:77], v[90:93], v[86:89]
	s_waitcnt lgkmcnt(0)
	v_mfma_f32_16x16x32_bf16 v[138:141], v[74:77], v[82:85], v[14:17]
	ds_read_b128 v[74:77], v142 offset:192
	v_mfma_f32_16x16x32_bf16 v[64:67], v[102:105], v[56:59], v[64:67]
	v_mfma_f32_16x16x32_bf16 v[78:81], v[102:105], v[82:85], v[78:81]
	v_mfma_f32_16x16x32_bf16 v[134:137], v[102:105], v[90:93], v[94:97]
	v_mfma_f32_16x16x32_bf16 v[52:55], v[70:73], v[114:117], v[52:55]

; template <bool PROMPT, int HALF>
; __device__ __forceinline__ void conv_item(unsigned char* ws, KArgs ka, int ib, int oct, int g, LAS unsigned char* lds, int tid, int lane, int wave) {
;     ...
;     __syncthreads();
;     int lane2; { unsigned ones_ = ~0u; asm volatile("" : "+s"(ones_)); lane2 = (int)__builtin_amdgcn_mbcnt_hi(ones_, __builtin_amdgcn_mbcnt_lo(ones_, 0u)); }
;     const int nn2 = lane2 & 15, kq2 = lane2 >> 4;
;     float nsum = 0.f;
;     { const float* kq_ = (const float*)(ws + WS_KPART) + ((size_t)ib * 320 + (PROMPT ? 0 : 256)) * 2048; constexpr int ntile = PROMPT ? 256 : 64;
;       for (int q = lane2; q < ntile; q += 64) nsum += kq_[(size_t)q * 2048 + c] + kq_[(size_t)q * 2048 + 1024 + c];
	v_min_i32_e32 v14, 0x1ff8, v50
	v_ashrrev_i32_e32 v15, 31, v14
	v_lshl_add_u64 v[68:69], v[14:15], 1, s[18:19]
	global_load_dwordx4 v[14:17], v[68:69], off
	global_load_dword v128, v[68:69], off offset:-4
	s_waitcnt vmcnt(8)
	v_perm_b32 v68, v129, v130, s67
	v_perm_b32 v69, v130, v131, s67
	v_perm_b32 v70, v131, v132, s67
	v_perm_b32 v71, v132, v133, s67
	s_nop 0
	v_mfma_f32_16x16x32_bf16 v[52:55], v[102:105], v[118:121], v[52:55]
	v_mfma_f32_16x16x32_bf16 v[110:113], v[68:71], v[56:59], v[60:63]
	v_mfma_f32_16x16x32_bf16 v[106:109], v[130:133], v[90:93], v[64:67]
	v_mfma_f32_16x16x32_bf16 v[94:97], v[68:71], v[90:93], v[98:101]
	v_mfma_f32_16x16x32_bf16 v[86:89], v[68:71], v[82:85], v[86:89]
	s_waitcnt lgkmcnt(0)
	v_mfma_f32_16x16x32_bf16 v[70:73], v[68:71], v[74:77], v[138:141]
	ds_read_b128 v[66:69], v142 offset:256
	v_mfma_f32_16x16x32_bf16 v[98:101], v[130:133], v[82:85], v[134:137]
	v_mfma_f32_16x16x32_bf16 v[78:81], v[130:133], v[74:77], v[78:81]
	v_mfma_f32_16x16x32_bf16 v[102:105], v[130:133], v[56:59], v[52:55]
	s_nop 0
	s_add_i32 s11, s11, 8
	v_add_u32_e32 v50, 0x100, v50
	s_cmpk_gt_u32 s11, 0xf8
	v_add_u32_e32 v51, 1, v51
	s_cbranch_scc0 .LBB0_773
	s_mov_b32 s11, -1
	s_waitcnt lgkmcnt(0)
	s_barrier
	s_nop 0
	v_mbcnt_lo_u32_b32 v0, s11, 0
	s_waitcnt vmcnt(3)
	v_mbcnt_hi_u32_b32 v12, s11, v0
	s_movk_i32 s11, 0x100
	v_cmp_gt_i32_e32 vcc, s11, v12
	v_mov_b32_e32 v0, 0
	s_and_saveexec_b64 s[18:19], vcc
	s_cbranch_execz .LBB0_778
	s_ashr_i32 s43, s42, 31
	s_lshl_b64 s[22:23], s[42:43], 2
	s_add_u32 s22, s51, s22
	v_lshlrev_b32_e32 v0, 13, v12
	s_addc_u32 s23, s52, s23
	v_subrev_u32_e32 v4, 64, v12
	v_lshl_add_u64 v[2:3], s[22:23], 0, v[0:1]
	v_mov_b32_e32 v0, 0
	s_mov_b64 s[22:23], 0
